# v9 + EpiResid epilogue: the 16 in-place residual loads of a tile preloaded in one burst (one vmcnt wait instead of 16)
# speedup vs baseline: 1.0119x; 1.0102x over previous
; __device__ __forceinline__ float bflo(unsigned u) { return __uint_as_float(u << 16); }
; __device__ __forceinline__ float bfhi(unsigned u) { return __uint_as_float(u & 0xffff0000u); }
; __device__ __forceinline__ float wave_sum(float v) {
; #pragma unroll
;     for (int o = 1; o < 64; o <<= 1) v += __shfl_xor(v, o);
;     return v;
; __global__ void __launch_bounds__(512, 2) mk_fwd(Args a) {
;     ...
;             for (int row = gw; row < T; row += NGW) {
;                 f32x4* xr = (f32x4*)(X + (size_t)row * DM) + lane; const u32x2* xb = (const u32x2*)(HB + (size_t)row * DM) + lane; f32x4 v[4]; float s = 0.f;
; #pragma unroll
;                 for (int j = 0; j < 4; ++j) { const u32x2 w = xb[64 * j]; v[j] = (f32x4){bflo(w.x), bfhi(w.x), bflo(w.y), bfhi(w.y)}; s += (v[j].x * v[j].x + v[j].y * v[j].y) + (v[j].z * v[j].z + v[j].w * v[j].w); }
;                 const float rs = rsqrtf(wave_sum(s) * (1.0f / DM) + EPS);
; #pragma unroll
;                 for (int j = 0; j < 4; ++j) { const f32x4 g4 = ((const f32x4*)gf)[lane + 64 * j]; xr[64 * j] = v[j] * rs * g4; }
;             }
.LBB0_25:
	s_and_b64 vcc, exec, s[6:7]
	s_cbranch_vccz .LBB0_30
	v_readlane_b32 s6, v254, 1
	v_readlane_b32 s8, v254, 3
	s_cmpk_gt_i32 s2, 0x7fff
	v_readlane_b32 s7, v254, 2
	v_readlane_b32 s9, v254, 4
	s_cbranch_scc1 .LBB0_29
	v_and_b32_e32 v0, 64, v217
	v_add_u32_e32 v0, 64, v0
	s_waitcnt lgkmcnt(0)
	v_xor_b32_e32 v2, 1, v217
	v_cmp_lt_i32_e32 vcc, v2, v0
	v_readlane_b32 s4, v254, 40
	v_readlane_b32 s5, v254, 41
	v_cndmask_b32_e32 v2, v217, v2, vcc
	v_lshlrev_b32_e32 v8, 2, v2
	v_xor_b32_e32 v2, 2, v217
	v_cmp_lt_i32_e32 vcc, v2, v0
	s_load_dwordx2 s[4:5], s[4:5], 0xa0
	v_and_b32_e32 v4, 63, v230
	v_cndmask_b32_e32 v2, v217, v2, vcc
	v_lshlrev_b32_e32 v9, 2, v2
	v_xor_b32_e32 v2, 4, v217
	v_cmp_lt_i32_e32 vcc, v2, v0
	s_ashr_i32 s3, s2, 31
	v_readlane_b32 s10, v254, 44
	v_cndmask_b32_e32 v2, v217, v2, vcc
	v_lshlrev_b32_e32 v10, 2, v2
	v_xor_b32_e32 v2, 8, v217
	v_cmp_lt_i32_e32 vcc, v2, v0
	v_readlane_b32 s11, v254, 45
	v_mov_b32_e32 v5, v1
	v_cndmask_b32_e32 v2, v217, v2, vcc
	v_lshlrev_b32_e32 v11, 2, v2
	v_xor_b32_e32 v2, 16, v217
	v_cmp_lt_i32_e32 vcc, v2, v0
	s_nop 1
	v_cndmask_b32_e32 v2, v217, v2, vcc
	v_lshlrev_b32_e32 v12, 2, v2
	v_xor_b32_e32 v2, 32, v217
	v_cmp_lt_i32_e32 vcc, v2, v0
	s_nop 1
	v_cndmask_b32_e32 v0, v217, v2, vcc
	v_lshlrev_b32_e32 v13, 2, v0
	v_lshlrev_b32_e32 v0, 4, v4
	s_waitcnt lgkmcnt(0)
	v_lshl_add_u64 v[2:3], s[4:5], 0, v[0:1]
	s_lshl_b64 s[4:5], s[2:3], 11
	s_add_u32 s4, s10, s4
	v_lshlrev_b32_e32 v4, 3, v4
	s_addc_u32 s5, s11, s5
	v_lshl_add_u64 v[4:5], s[4:5], 0, v[4:5]
	s_lshl_b64 s[4:5], s[2:3], 12
	s_add_u32 s4, s36, s4
	s_addc_u32 s5, s37, s5
	v_lshl_add_u64 v[6:7], s[4:5], 0, v[0:1]
	global_load_dwordx4 v[52:55], v[2:3], off
	global_load_dwordx4 v[56:59], v[2:3], off offset:1024
	global_load_dwordx4 v[60:63], v[2:3], off offset:2048
	global_load_dwordx4 v[64:67], v[2:3], off offset:3072
.LBB0_28:
	flat_load_dwordx2 v[18:19], v[4:5]
	flat_load_dwordx2 v[20:21], v[4:5] offset:512
	flat_load_dwordx2 v[22:23], v[4:5] offset:1024
	flat_load_dwordx2 v[24:25], v[4:5] offset:1536
	s_add_i32 s2, s2, s96
	v_lshl_add_u64 v[4:5], v[4:5], 0, s[8:9]
	s_cmpk_gt_i32 s2, 0x7fff
	s_waitcnt vmcnt(0) lgkmcnt(0)
	v_lshlrev_b32_e32 v26, 16, v18
	v_and_b32_e32 v27, 0xffff0000, v18
	v_lshlrev_b32_e32 v18, 16, v19
	v_and_b32_e32 v19, 0xffff0000, v19
	v_lshlrev_b32_e32 v29, 16, v21
	v_lshlrev_b32_e32 v28, 16, v20
	v_and_b32_e32 v21, 0xffff0000, v21
	v_and_b32_e32 v20, 0xffff0000, v20
	v_lshlrev_b32_e32 v30, 16, v22
	v_and_b32_e32 v31, 0xffff0000, v22
	v_lshlrev_b32_e32 v22, 16, v23
	v_and_b32_e32 v23, 0xffff0000, v23
	v_lshlrev_b32_e32 v33, 16, v24
	v_mul_f32_e32 v0, v19, v19
	v_mul_f32_e32 v32, v27, v27
	v_pk_mul_f32 v[36:37], v[20:21], v[20:21]
	v_mov_b32_e32 v39, v33
	v_mul_f32_e32 v38, v23, v23
	v_pk_fma_f32 v[40:41], v[18:19], v[18:19], v[0:1] op_sel_hi:[1,1,0]
	v_pk_fma_f32 v[42:43], v[26:27], v[26:27], v[32:33] op_sel_hi:[1,1,0]
	v_and_b32_e32 v35, 0xffff0000, v24
	v_lshlrev_b32_e32 v24, 16, v25
	v_and_b32_e32 v25, 0xffff0000, v25
	v_mul_f32_e32 v34, v31, v31
	v_pk_fma_f32 v[36:37], v[28:29], v[28:29], v[36:37]
	v_pk_fma_f32 v[46:47], v[22:23], v[22:23], v[38:39] op_sel_hi:[1,1,0]
	v_mov_b32_e32 v32, v42
	v_mov_b32_e32 v38, v40
	v_mul_f32_e32 v48, v35, v35
	v_mul_f32_e32 v49, v24, v24
	v_mul_f32_e32 v50, v25, v25
	v_pk_fma_f32 v[44:45], v[30:31], v[30:31], v[34:35] op_sel_hi:[1,1,0]
	v_pk_add_f32 v[40:41], v[42:43], v[40:41]
	v_pk_add_f32 v[36:37], v[36:37], v[36:37] op_sel:[0,1] op_sel_hi:[1,0]
	v_pk_mul_f32 v[38:39], v[32:33], v[38:39]
	v_mov_b32_e32 v45, v49
	v_mov_b32_e32 v47, v50
	v_mov_b32_e32 v37, v48
	v_mov_b32_e32 v41, v39
	v_pk_add_f32 v[42:43], v[44:45], v[46:47]
	v_pk_add_f32 v[36:37], v[40:41], v[36:37]
	v_mov_b32_e32 v34, v33
	v_pk_add_f32 v[36:37], v[36:37], v[42:43]
	s_nop 0
	v_add_f32_e32 v0, v36, v37
	ds_bpermute_b32 v32, v8, v0
	s_waitcnt lgkmcnt(0)
	v_add_f32_e32 v0, v0, v32
	ds_bpermute_b32 v32, v9, v0
	s_waitcnt lgkmcnt(0)
	v_add_f32_e32 v0, v0, v32
	ds_bpermute_b32 v32, v10, v0
	s_waitcnt lgkmcnt(0)
	v_add_f32_e32 v0, v0, v32
	ds_bpermute_b32 v32, v11, v0
	s_waitcnt lgkmcnt(0)
	v_add_f32_e32 v0, v0, v32
	ds_bpermute_b32 v32, v12, v0
	s_waitcnt lgkmcnt(0)
	v_add_f32_e32 v0, v0, v32
	ds_bpermute_b32 v32, v13, v0
	s_waitcnt lgkmcnt(0)
	v_add_f32_e32 v0, v0, v32
	v_fmamk_f32 v0, v0, 0x3a800000, v205
	v_mul_f32_e32 v32, 0x4b800000, v0
	v_cmp_gt_f32_e32 vcc, s77, v0
	s_nop 1
	v_cndmask_b32_e32 v0, v0, v32, vcc
	v_rsq_f32_e32 v0, v0
	s_nop 0
	v_mul_f32_e32 v32, 0x45800000, v0
	v_cndmask_b32_e32 v0, v0, v32, vcc
	v_pk_mul_f32 v[26:27], v[0:1], v[26:27] op_sel_hi:[0,1]
	v_pk_mul_f32 v[18:19], v[0:1], v[18:19] op_sel_hi:[0,1]
	v_pk_mul_f32 v[16:17], v[18:19], v[54:55]
	v_pk_mul_f32 v[14:15], v[26:27], v[52:53]
	flat_store_dwordx4 v[6:7], v[14:17]
	v_mov_b32_e32 v18, v29
	v_mov_b32_e32 v19, v21
	v_mov_b32_e32 v29, v20
	v_pk_mul_f32 v[18:19], v[0:1], v[18:19] op_sel_hi:[0,1]
	v_pk_mul_f32 v[20:21], v[0:1], v[28:29] op_sel_hi:[0,1]
	v_pk_mul_f32 v[14:15], v[20:21], v[56:57]
	v_pk_mul_f32 v[16:17], v[18:19], v[58:59]
	flat_store_dwordx4 v[6:7], v[14:17] offset:1024
	v_pk_mul_f32 v[18:19], v[0:1], v[22:23] op_sel_hi:[0,1]
	v_pk_mul_f32 v[20:21], v[0:1], v[30:31] op_sel_hi:[0,1]
	v_pk_mul_f32 v[14:15], v[20:21], v[60:61]
	v_pk_mul_f32 v[16:17], v[18:19], v[62:63]
	flat_store_dwordx4 v[6:7], v[14:17] offset:2048
	v_pk_mul_f32 v[18:19], v[0:1], v[24:25] op_sel_hi:[0,1]
	v_pk_mul_f32 v[20:21], v[0:1], v[34:35] op_sel_hi:[0,1]
	v_pk_mul_f32 v[14:15], v[20:21], v[64:65]
	v_pk_mul_f32 v[16:17], v[18:19], v[66:67]
	flat_store_dwordx4 v[6:7], v[14:17] offset:3072
	v_lshl_add_u64 v[6:7], v[6:7], 0, s[6:7]
	s_cbranch_scc0 .LBB0_28

; __device__ __forceinline__ void xcd_barrier(const XcdBarrier& b) {
;     asm volatile("s_waitcnt vmcnt(0)" ::: "memory");
;     __syncthreads();
;     if (threadIdx.x == 0) {
;         unsigned* bar = b.bar;
;         __builtin_amdgcn_s_waitcnt(0);
;         unsigned nloc = b.st[0], nx = b.st[1];
;         if (nloc == 0u) { xcd_barrier_complete(bar, b.x, nloc, nx); b.st[0] = nloc; b.st[1] = nx; }
; __global__ void __launch_bounds__(512, 2) mk_fwd(Args a) {
;     ...
;         dup_done = false;
;         if (sync_after && ph + 1 < a.ph_hi) { if (ph == a.ph_lo) grid.sync(); else xcd_barrier(xbar); }
.LBB0_30:
	s_andn2_b64 vcc, exec, s[4:5]
	s_cbranch_vccnz .LBB0_12
	s_add_i32 s2, s26, 1
	s_cmp_lt_i32 s2, s79
	s_cselect_b64 s[2:3], -1, 0
	s_and_b64 s[2:3], s[64:65], s[2:3]
	s_andn2_b64 vcc, exec, s[2:3]
	s_cbranch_vccnz .LBB0_12
	s_cmp_lg_u32 s26, s78
	s_mov_b64 s[2:3], -1
	s_waitcnt vmcnt(0)
	s_mov_b32 s31, s26
	s_waitcnt vmcnt(0) lgkmcnt(0)
	s_barrier
	s_mov_b64 s[2:3], exec
	v_readlane_b32 s4, v253, 59
	v_readlane_b32 s5, v253, 60
	v_readlane_b32 s12, v252, 16
	v_readlane_b32 s14, v252, 18
	v_readlane_b32 s16, v252, 20
	v_readlane_b32 s18, v252, 22
	v_readlane_b32 s20, v252, 24
	v_readlane_b32 s22, v252, 26
	v_readlane_b32 s24, v252, 28
	v_readlane_b32 s26, v252, 30
	v_readlane_b32 s28, v253, 2
	s_and_b64 s[4:5], s[2:3], s[4:5]
	v_readlane_b32 s13, v252, 17
	v_readlane_b32 s15, v252, 19
	v_readlane_b32 s17, v252, 21
	v_readlane_b32 s19, v252, 23
	v_readlane_b32 s21, v252, 25
	v_readlane_b32 s23, v252, 27
	v_readlane_b32 s25, v252, 29
	v_readlane_b32 s27, v252, 31
	v_readlane_b32 s29, v253, 3
	s_mov_b64 exec, s[4:5]
	s_cbranch_execz .LBB0_497
	v_readlane_b32 s4, v253, 57
	s_waitcnt vmcnt(0) expcnt(0) lgkmcnt(0)
	s_nop 0
	v_mov_b32_e32 v0, s4
	ds_read_b32 v3, v0
	v_readlane_b32 s4, v253, 58
	s_waitcnt lgkmcnt(0)
	v_cmp_ne_u32_e32 vcc, 0, v3
	v_mov_b32_e32 v0, s4
	ds_read_b32 v2, v0
	s_cbranch_vccnz .LBB0_64
	s_mov_b32 s10, 1
	s_branch .LBB0_37

; __device__ __forceinline__ unsigned pk2(float lo, float hi) { f32x2_t v = {lo, hi}; bf16x2_t b = __builtin_convertvector(v, bf16x2_t); return __builtin_bit_cast(unsigned, b); }
; __device__ __forceinline__ bf16_t* wdst(int kind, int n, unsigned char* Wb) {
;     ...
;     case 0: case 2: { const int up = n >= FF, j = up ? n - FF : n; const int row = 256 * (j >> 7) + (j & 127) + (up ? 128 : 0); return (bf16_t*)(Wb + (kind == 0 ? O_GU1 : O_GU2)) + (size_t)row * 1024; }
; __device__ __forceinline__ void conv_item(const float* W, int K, int N, int kind, int item, const float* gain, unsigned char* Wb, float* scr, int lane) {
;     ...
;     for (int j = 0; j < 4; ++j) { const int n = (lane >> 3) + 8 * j; const float* s = scr + (8 * c) * 33 + n;
;         u32x4 o; o.x = pk2(s[0] * gg[0], s[33] * gg[1]); o.y = pk2(s[2 * 33] * gg[2], s[3 * 33] * gg[3]); o.z = pk2(s[4 * 33] * gg[4], s[5 * 33] * gg[5]); o.w = pk2(s[6 * 33] * gg[6], s[7 * 33] * gg[7]);
;         *(u32x4*)(wdst(kind, n0 + n, Wb) + k0 + 8 * c) = o; }
;     __builtin_amdgcn_s_waitcnt(0); asm volatile("" ::: "memory");
.LBB0_247:
	ds_read_b32 v16, v30
	ds_read_b32 v17, v30 offset:132
	ds_read_b32 v18, v30 offset:264
	ds_read_b32 v19, v30 offset:396
	ds_read_b32 v20, v30 offset:528
	ds_read_b32 v21, v30 offset:660
	ds_read_b32 v22, v30 offset:792
	ds_read_b32 v23, v30 offset:924
	v_add_u32_e32 v24, s16, v7
	s_movk_i32 s12, 0xaff
	s_waitcnt vmcnt(0) lgkmcnt(6)
	v_pk_mul_f32 v[16:17], v[8:9], v[16:17]
	s_waitcnt lgkmcnt(4)
	v_pk_mul_f32 v[18:19], v[10:11], v[18:19]
	v_add_u32_e32 v0, 0xfffff500, v24
	v_cmp_lt_i32_e32 vcc, s12, v24
	v_cvt_pk_bf16_f32 v16, v16, v17
	v_cvt_pk_bf16_f32 v17, v18, v19
	s_waitcnt lgkmcnt(2)
	v_pk_mul_f32 v[18:19], v[12:13], v[20:21]
	s_waitcnt lgkmcnt(0)
	v_pk_mul_f32 v[20:21], v[14:15], v[22:23]
	v_cndmask_b32_e32 v0, v24, v0, vcc
	v_cvt_pk_bf16_f32 v18, v18, v19
	v_cvt_pk_bf16_f32 v19, v20, v21
	v_lshlrev_b32_e32 v20, 1, v0
	v_and_b32_e32 v20, 0xffffff00, v20
	v_and_b32_e32 v0, 0x67, v0
	v_cndmask_b32_e32 v21, 0, v225, vcc
	v_or3_b32 v20, v0, v21, v20
	v_ashrrev_i32_e32 v21, 31, v20
	v_readlane_b32 s14, v254, 52
	s_ashr_i32 s7, s6, 31
	v_lshlrev_b64 v[20:21], 11, v[20:21]
	v_readlane_b32 s15, v254, 53
	s_lshl_b64 s[4:5], s[6:7], 1
	v_lshlrev_b32_e32 v0, 1, v6
	v_lshl_add_u64 v[20:21], s[14:15], 0, v[20:21]
	v_lshl_add_u64 v[20:21], v[20:21], 0, s[4:5]
	v_lshl_add_u64 v[20:21], v[20:21], 0, v[0:1]
	flat_store_dwordx4 v[20:21], v[16:19]
	ds_read_b32 v16, v30 offset:32
	ds_read_b32 v17, v30 offset:164
	ds_read_b32 v18, v30 offset:296
	ds_read_b32 v19, v30 offset:428
	ds_read_b32 v20, v30 offset:560
	ds_read_b32 v21, v30 offset:692
	ds_read_b32 v22, v30 offset:824
	ds_read_b32 v23, v30 offset:956
	s_waitcnt lgkmcnt(0)
	v_pk_mul_f32 v[16:17], v[8:9], v[16:17]
	v_pk_mul_f32 v[18:19], v[10:11], v[18:19]
	v_cvt_pk_bf16_f32 v16, v16, v17
	v_cvt_pk_bf16_f32 v17, v18, v19
	v_pk_mul_f32 v[18:19], v[12:13], v[20:21]
	v_pk_mul_f32 v[20:21], v[14:15], v[22:23]
	v_cvt_pk_bf16_f32 v18, v18, v19
	v_cvt_pk_bf16_f32 v19, v20, v21
	v_add_u32_e32 v20, 8, v24
	v_add_u32_e32 v21, 0xfffff508, v24
	v_cmp_lt_i32_e32 vcc, s12, v20
	v_add_u32_e32 v25, 24, v24
	s_nop 0
	v_cndmask_b32_e32 v20, v20, v21, vcc
	v_lshlrev_b32_e32 v21, 1, v20
	v_and_b32_e32 v21, 0xffffff00, v21
	v_and_b32_e32 v20, 0x6f, v20
	v_cndmask_b32_e32 v22, 0, v225, vcc
	v_or3_b32 v20, v20, v22, v21
	v_ashrrev_i32_e32 v21, 31, v20
	v_lshlrev_b64 v[20:21], 11, v[20:21]
	v_lshl_add_u64 v[20:21], s[14:15], 0, v[20:21]
	v_lshl_add_u64 v[20:21], v[20:21], 0, s[4:5]
	v_lshl_add_u64 v[20:21], v[20:21], 0, v[0:1]
	flat_store_dwordx4 v[20:21], v[16:19]
	ds_read_b32 v16, v30 offset:64
	ds_read_b32 v17, v30 offset:196
	ds_read_b32 v18, v30 offset:328
	ds_read_b32 v19, v30 offset:460
	ds_read_b32 v20, v30 offset:592
	ds_read_b32 v21, v30 offset:724
	ds_read_b32 v22, v30 offset:856
	ds_read_b32 v23, v30 offset:988
	s_waitcnt lgkmcnt(0)
	v_pk_mul_f32 v[16:17], v[8:9], v[16:17]
	v_pk_mul_f32 v[18:19], v[10:11], v[18:19]
	v_cvt_pk_bf16_f32 v16, v16, v17
	v_cvt_pk_bf16_f32 v17, v18, v19
	v_pk_mul_f32 v[18:19], v[12:13], v[20:21]
	v_pk_mul_f32 v[20:21], v[14:15], v[22:23]
	v_cvt_pk_bf16_f32 v18, v18, v19
	v_cvt_pk_bf16_f32 v19, v20, v21
	v_add_u32_e32 v20, 16, v24
	v_add_u32_e32 v21, 0xfffff510, v24
	v_cmp_lt_i32_e32 vcc, s12, v20
	v_add_u32_e32 v24, 0xfffff518, v24
	s_nop 0
	v_cndmask_b32_e32 v20, v20, v21, vcc
	v_lshlrev_b32_e32 v21, 1, v20
	v_and_b32_e32 v21, 0xffffff00, v21
	v_and_b32_e32 v20, 0x77, v20
	v_cndmask_b32_e32 v22, 0, v225, vcc
	v_or3_b32 v20, v20, v22, v21
	v_ashrrev_i32_e32 v21, 31, v20
	v_lshlrev_b64 v[20:21], 11, v[20:21]
	v_lshl_add_u64 v[20:21], s[14:15], 0, v[20:21]
	v_lshl_add_u64 v[20:21], v[20:21], 0, s[4:5]
	v_lshl_add_u64 v[20:21], v[20:21], 0, v[0:1]
	v_cmp_lt_i32_e32 vcc, s12, v25
	flat_store_dwordx4 v[20:21], v[16:19]
	ds_read_b32 v16, v30 offset:96
	ds_read_b32 v17, v30 offset:228
	ds_read_b32 v18, v30 offset:360
	ds_read_b32 v19, v30 offset:492
	ds_read_b32 v20, v30 offset:624
	ds_read_b32 v21, v30 offset:756
	ds_read_b32 v22, v30 offset:888
	ds_read_b32 v23, v30 offset:1020
	v_cndmask_b32_e32 v24, v25, v24, vcc
	v_lshlrev_b32_e32 v25, 1, v24
	v_and_b32_e32 v25, 0xffffff00, v25
	v_and_b32_e32 v24, 0x7f, v24
	v_cndmask_b32_e32 v26, 0, v225, vcc
	v_or3_b32 v24, v24, v26, v25
	v_ashrrev_i32_e32 v25, 31, v24
	v_lshlrev_b64 v[24:25], 11, v[24:25]
	s_waitcnt lgkmcnt(0)
	v_pk_mul_f32 v[8:9], v[8:9], v[16:17]
	v_pk_mul_f32 v[10:11], v[10:11], v[18:19]
	v_lshl_add_u64 v[24:25], s[14:15], 0, v[24:25]
	v_cvt_pk_bf16_f32 v8, v8, v9
	v_cvt_pk_bf16_f32 v9, v10, v11
	v_pk_mul_f32 v[10:11], v[12:13], v[20:21]
	v_pk_mul_f32 v[12:13], v[14:15], v[22:23]
	v_cvt_pk_bf16_f32 v10, v10, v11
	v_cvt_pk_bf16_f32 v11, v12, v13
	v_lshl_add_u64 v[12:13], v[24:25], 0, s[4:5]
	v_lshl_add_u64 v[12:13], v[12:13], 0, v[0:1]
	flat_store_dwordx4 v[12:13], v[8:11]
	s_waitcnt lgkmcnt(0)

; __device__ __forceinline__ unsigned pk2(float lo, float hi) { f32x2_t v = {lo, hi}; bf16x2_t b = __builtin_convertvector(v, bf16x2_t); return __builtin_bit_cast(unsigned, b); }
; __device__ __forceinline__ bf16_t* wdst(int kind, int n, unsigned char* Wb) {
;     ...
;     case 6: { const int hd = n >> 7, d = n & 127; return d < 64 ? (bf16_t*)(Wb + O_WUK) + (size_t)(hd * 64 + d) * 128 : (bf16_t*)(Wb + O_WUV) + (size_t)(hd * 64 + d - 64) * 128; }
; __device__ __forceinline__ void conv_item(const float* W, int K, int N, int kind, int item, const float* gain, unsigned char* Wb, float* scr, int lane) {
;     ...
;     for (int j = 0; j < 4; ++j) { const int n = (lane >> 3) + 8 * j; const float* s = scr + (8 * c) * 33 + n;
;         u32x4 o; o.x = pk2(s[0] * gg[0], s[33] * gg[1]); o.y = pk2(s[2 * 33] * gg[2], s[3 * 33] * gg[3]); o.z = pk2(s[4 * 33] * gg[4], s[5 * 33] * gg[5]); o.w = pk2(s[6 * 33] * gg[6], s[7 * 33] * gg[7]);
;         *(u32x4*)(wdst(kind, n0 + n, Wb) + k0 + 8 * c) = o; }
;     __builtin_amdgcn_s_waitcnt(0); asm volatile("" ::: "memory");
.LBB0_275:
	ds_read_b32 v16, v30
	ds_read_b32 v17, v30 offset:132
	ds_read_b32 v18, v30 offset:264
	ds_read_b32 v19, v30 offset:396
	ds_read_b32 v20, v30 offset:528
	ds_read_b32 v21, v30 offset:660
	ds_read_b32 v22, v30 offset:792
	ds_read_b32 v23, v30 offset:924
	s_lshl_b32 s4, s13, 4
	s_and_b32 s7, s4, 0xffffffc0
	s_sub_i32 s13, s7, 64
	s_and_b32 s6, s6, 0x60
	s_waitcnt vmcnt(0) lgkmcnt(6)
	v_pk_mul_f32 v[16:17], v[8:9], v[16:17]
	s_waitcnt lgkmcnt(4)
	v_pk_mul_f32 v[18:19], v[10:11], v[18:19]
	s_cmp_lt_u32 s6, 64
	v_cvt_pk_bf16_f32 v16, v16, v17
	v_cvt_pk_bf16_f32 v17, v18, v19
	s_waitcnt lgkmcnt(2)
	v_pk_mul_f32 v[18:19], v[12:13], v[20:21]
	s_waitcnt lgkmcnt(0)
	v_pk_mul_f32 v[20:21], v[14:15], v[22:23]
	v_or_b32_e32 v0, s6, v7
	s_cselect_b64 vcc, -1, 0
	v_cvt_pk_bf16_f32 v18, v18, v19
	v_cvt_pk_bf16_f32 v19, v20, v21
	v_add_u32_e32 v20, s13, v0
	v_or_b32_e32 v0, s7, v0
	s_and_b64 s[4:5], vcc, exec
	v_cndmask_b32_e32 v20, v20, v0, vcc
	v_readlane_b32 s4, v254, 62
	s_cselect_b32 s5, s27, s4
	v_readlane_b32 s4, v254, 60
	v_readlane_b32 s14, v254, 42
	v_ashrrev_i32_e32 v21, 31, v20
	s_cselect_b32 s4, s14, s4
	v_lshlrev_b64 v[20:21], 8, v[20:21]
	v_lshl_add_u64 v[20:21], s[4:5], 0, v[20:21]
	s_lshl_b32 s92, s12, 1
	v_lshl_add_u64 v[20:21], v[20:21], 0, s[92:93]
	v_lshlrev_b32_e32 v0, 1, v6
	v_lshl_add_u64 v[20:21], v[20:21], 0, v[0:1]
	flat_store_dwordx4 v[20:21], v[16:19]
	ds_read_b32 v16, v30 offset:32
	ds_read_b32 v17, v30 offset:164
	ds_read_b32 v18, v30 offset:296
	ds_read_b32 v19, v30 offset:428
	ds_read_b32 v20, v30 offset:560
	ds_read_b32 v21, v30 offset:692
	ds_read_b32 v22, v30 offset:824
	ds_read_b32 v23, v30 offset:956
	s_waitcnt lgkmcnt(0)
	v_pk_mul_f32 v[16:17], v[8:9], v[16:17]
	v_pk_mul_f32 v[18:19], v[10:11], v[18:19]
	v_cvt_pk_bf16_f32 v16, v16, v17
	v_cvt_pk_bf16_f32 v17, v18, v19
	v_pk_mul_f32 v[18:19], v[12:13], v[20:21]
	v_pk_mul_f32 v[20:21], v[14:15], v[22:23]
	v_cvt_pk_bf16_f32 v18, v18, v19
	v_cvt_pk_bf16_f32 v19, v20, v21
	v_or_b32_e32 v20, s6, v31
	v_or_b32_e32 v21, s7, v20
	v_add_u32_e32 v20, s13, v20
	v_cndmask_b32_e32 v20, v20, v21, vcc
	v_ashrrev_i32_e32 v21, 31, v20
	v_lshlrev_b64 v[20:21], 8, v[20:21]
	v_lshl_add_u64 v[20:21], s[4:5], 0, v[20:21]
	v_lshl_add_u64 v[20:21], v[20:21], 0, s[92:93]
	v_lshl_add_u64 v[20:21], v[20:21], 0, v[0:1]
	flat_store_dwordx4 v[20:21], v[16:19]
	ds_read_b32 v16, v30 offset:64
	ds_read_b32 v17, v30 offset:196
	ds_read_b32 v18, v30 offset:328
	ds_read_b32 v19, v30 offset:460
	ds_read_b32 v20, v30 offset:592
	ds_read_b32 v21, v30 offset:724
	ds_read_b32 v22, v30 offset:856
	ds_read_b32 v23, v30 offset:988
	s_waitcnt lgkmcnt(0)
	v_pk_mul_f32 v[16:17], v[8:9], v[16:17]
	v_pk_mul_f32 v[18:19], v[10:11], v[18:19]
	v_cvt_pk_bf16_f32 v16, v16, v17
	v_cvt_pk_bf16_f32 v17, v18, v19
	v_pk_mul_f32 v[18:19], v[12:13], v[20:21]
	v_pk_mul_f32 v[20:21], v[14:15], v[22:23]
	v_cvt_pk_bf16_f32 v18, v18, v19
	v_cvt_pk_bf16_f32 v19, v20, v21
	v_or_b32_e32 v20, s6, v32
	v_or_b32_e32 v21, s7, v20
	v_add_u32_e32 v20, s13, v20
	v_cndmask_b32_e32 v20, v20, v21, vcc
	v_ashrrev_i32_e32 v21, 31, v20
	v_lshlrev_b64 v[20:21], 8, v[20:21]
	v_lshl_add_u64 v[20:21], s[4:5], 0, v[20:21]
	v_lshl_add_u64 v[20:21], v[20:21], 0, s[92:93]
	v_lshl_add_u64 v[20:21], v[20:21], 0, v[0:1]
	flat_store_dwordx4 v[20:21], v[16:19]
	ds_read_b32 v16, v30 offset:96
	ds_read_b32 v17, v30 offset:228
	ds_read_b32 v18, v30 offset:360
	ds_read_b32 v19, v30 offset:492
	ds_read_b32 v20, v30 offset:624
	ds_read_b32 v21, v30 offset:756
	ds_read_b32 v22, v30 offset:888
	ds_read_b32 v23, v30 offset:1020
	v_or_b32_e32 v24, s6, v33
	v_add_u32_e32 v25, s13, v24
	v_or_b32_e32 v24, s7, v24
	v_cndmask_b32_e32 v24, v25, v24, vcc
	v_ashrrev_i32_e32 v25, 31, v24
	v_lshlrev_b64 v[24:25], 8, v[24:25]
	s_waitcnt lgkmcnt(0)
	v_pk_mul_f32 v[8:9], v[8:9], v[16:17]
	v_pk_mul_f32 v[10:11], v[10:11], v[18:19]
	v_lshl_add_u64 v[24:25], s[4:5], 0, v[24:25]
	v_cvt_pk_bf16_f32 v8, v8, v9
	v_cvt_pk_bf16_f32 v9, v10, v11
	v_pk_mul_f32 v[10:11], v[12:13], v[20:21]
	v_pk_mul_f32 v[12:13], v[14:15], v[22:23]
	v_cvt_pk_bf16_f32 v10, v10, v11
	v_cvt_pk_bf16_f32 v11, v12, v13
	v_lshl_add_u64 v[12:13], v[24:25], 0, s[92:93]
	v_lshl_add_u64 v[12:13], v[12:13], 0, v[0:1]
	flat_store_dwordx4 v[12:13], v[8:11]
	s_waitcnt lgkmcnt(0)
	s_mov_b64 s[4:5], 0

; __device__ __forceinline__ unsigned pk2(float lo, float hi) { f32x2_t v = {lo, hi}; bf16x2_t b = __builtin_convertvector(v, bf16x2_t); return __builtin_bit_cast(unsigned, b); }
; __device__ __forceinline__ bf16_t* wdst(int kind, int n, unsigned char* Wb) {
;     ...
;     case 5: { const int hd = n / 96, d = n - hd * 96; int row = n; if (d >= 64) { const int c = d - 64; row = hd * 96 + 64 + 2 * (c & 15) + (c >> 4); } return (bf16_t*)(Wb + O_WUQ) + (size_t)row * 256; }
; __device__ __forceinline__ void conv_item(const float* W, int K, int N, int kind, int item, const float* gain, unsigned char* Wb, float* scr, int lane) {
;     ...
;     for (int j = 0; j < 4; ++j) { const int n = (lane >> 3) + 8 * j; const float* s = scr + (8 * c) * 33 + n;
;         u32x4 o; o.x = pk2(s[0] * gg[0], s[33] * gg[1]); o.y = pk2(s[2 * 33] * gg[2], s[3 * 33] * gg[3]); o.z = pk2(s[4 * 33] * gg[4], s[5 * 33] * gg[5]); o.w = pk2(s[6 * 33] * gg[6], s[7 * 33] * gg[7]);
;         *(u32x4*)(wdst(kind, n0 + n, Wb) + k0 + 8 * c) = o; }
;     __builtin_amdgcn_s_waitcnt(0); asm volatile("" ::: "memory");
.LBB0_293:
	ds_read2_b32 v[24:25], v30 offset1:33
	ds_read2_b32 v[22:23], v30 offset0:66 offset1:99
	ds_read2_b32 v[20:21], v30 offset0:132 offset1:165
	ds_read2_b32 v[16:17], v30 offset0:198 offset1:231
	v_add_u32_e32 v18, s12, v48
	s_mulk_i32 s14, 0xffe8
	v_mul_hi_i32 v0, v18, s29
	s_add_i32 s4, s82, s14
	v_lshrrev_b32_e32 v19, 31, v0
	v_lshrrev_b32_e32 v0, 4, v0
	s_lshl_b32 s6, s4, 5
	v_add_u32_e32 v0, v0, v19
	s_movk_i32 s4, 0x60
	v_mul_lo_u32 v0, v0, s4
	v_sub_u32_e32 v0, v18, v0
	s_add_i32 s6, s6, 0xfff9d600
	v_cmp_lt_i32_e32 vcc, 63, v0
	s_and_saveexec_b64 s[4:5], vcc
	v_or_b32_e32 v18, s6, v7
	v_lshlrev_b32_e32 v26, 1, v0
	v_subrev_u32_e32 v19, 64, v0
	v_and_b32_e32 v26, 14, v26
	v_sub_u32_e32 v0, v18, v0
	v_lshrrev_b32_e32 v19, 4, v19
	v_add_u32_e32 v0, v0, v26
	v_add3_u32 v18, v0, v19, 64
	s_or_b64 exec, exec, s[4:5]
	s_waitcnt vmcnt(0) lgkmcnt(0)
	v_pk_mul_f32 v[16:17], v[14:15], v[16:17]
	v_ashrrev_i32_e32 v19, 31, v18
	v_cvt_pk_bf16_f32 v27, v16, v17
	v_lshlrev_b64 v[16:17], 9, v[18:19]
	v_lshl_add_u64 v[16:17], s[64:65], 0, v[16:17]
	s_lshl_b32 s92, s13, 1
	v_pk_mul_f32 v[24:25], v[8:9], v[24:25]
	v_pk_mul_f32 v[22:23], v[10:11], v[22:23]
	v_pk_mul_f32 v[20:21], v[12:13], v[20:21]
	v_lshl_add_u64 v[16:17], v[16:17], 0, s[92:93]
	v_lshlrev_b32_e32 v0, 1, v6
	v_cvt_pk_bf16_f32 v24, v24, v25
	v_cvt_pk_bf16_f32 v25, v22, v23
	v_cvt_pk_bf16_f32 v26, v20, v21
	v_lshl_add_u64 v[16:17], v[16:17], 0, v[0:1]
	flat_store_dwordx4 v[16:17], v[24:27]
	ds_read2_b32 v[24:25], v30 offset0:8 offset1:41
	ds_read2_b32 v[20:21], v30 offset0:74 offset1:107
	ds_read2_b32 v[18:19], v30 offset0:140 offset1:173
	ds_read2_b32 v[16:17], v30 offset0:206 offset1:239
	v_add_u32_e32 v22, s12, v47
	v_mul_hi_i32 v23, v22, s29
	v_lshrrev_b32_e32 v26, 31, v23
	v_lshrrev_b32_e32 v23, 4, v23
	v_add_u32_e32 v23, v23, v26
	s_movk_i32 s4, 0x60
	v_mul_lo_u32 v23, v23, s4
	v_sub_u32_e32 v23, v22, v23
	v_cmp_lt_i32_e32 vcc, 63, v23
	s_and_saveexec_b64 s[4:5], vcc
	v_or_b32_e32 v22, s6, v31
	v_lshlrev_b32_e32 v27, 1, v23
	v_subrev_u32_e32 v26, 64, v23
	v_and_b32_e32 v27, 30, v27
	v_sub_u32_e32 v22, v22, v23
	v_lshrrev_b32_e32 v26, 4, v26
	v_add_u32_e32 v22, v22, v27
	v_add3_u32 v22, v22, v26, 64
	s_or_b64 exec, exec, s[4:5]
	s_waitcnt lgkmcnt(0)
	v_pk_mul_f32 v[16:17], v[14:15], v[16:17]
	v_ashrrev_i32_e32 v23, 31, v22
	v_cvt_pk_bf16_f32 v27, v16, v17
	v_lshlrev_b64 v[16:17], 9, v[22:23]
	v_lshl_add_u64 v[16:17], s[64:65], 0, v[16:17]
	v_pk_mul_f32 v[24:25], v[8:9], v[24:25]
	v_pk_mul_f32 v[20:21], v[10:11], v[20:21]
	v_pk_mul_f32 v[18:19], v[12:13], v[18:19]
	v_lshl_add_u64 v[16:17], v[16:17], 0, s[92:93]
	v_cvt_pk_bf16_f32 v24, v24, v25
	v_cvt_pk_bf16_f32 v25, v20, v21
	v_cvt_pk_bf16_f32 v26, v18, v19
	v_lshl_add_u64 v[16:17], v[16:17], 0, v[0:1]
	flat_store_dwordx4 v[16:17], v[24:27]
	ds_read2_b32 v[24:25], v30 offset0:16 offset1:49
	ds_read2_b32 v[20:21], v30 offset0:82 offset1:115
	ds_read2_b32 v[18:19], v30 offset0:148 offset1:181
	ds_read2_b32 v[16:17], v30 offset0:214 offset1:247
	v_add_u32_e32 v22, s12, v46
	v_mul_hi_i32 v23, v22, s29
	v_lshrrev_b32_e32 v26, 31, v23
	v_lshrrev_b32_e32 v23, 4, v23
	v_add_u32_e32 v23, v23, v26
	s_movk_i32 s4, 0x60
	v_mul_lo_u32 v23, v23, s4
	v_sub_u32_e32 v23, v22, v23
	v_cmp_lt_i32_e32 vcc, 63, v23
	s_and_saveexec_b64 s[4:5], vcc
	v_or_b32_e32 v22, s6, v32
	v_lshlrev_b32_e32 v27, 1, v23
	v_subrev_u32_e32 v26, 64, v23
	v_and_b32_e32 v27, 14, v27
	v_sub_u32_e32 v22, v22, v23
	v_lshrrev_b32_e32 v26, 4, v26
	v_add_u32_e32 v22, v22, v27
	v_add3_u32 v22, v22, v26, 64
	s_or_b64 exec, exec, s[4:5]
	s_waitcnt lgkmcnt(0)
	v_pk_mul_f32 v[16:17], v[14:15], v[16:17]
	v_ashrrev_i32_e32 v23, 31, v22
	v_cvt_pk_bf16_f32 v27, v16, v17
	v_lshlrev_b64 v[16:17], 9, v[22:23]
	v_lshl_add_u64 v[16:17], s[64:65], 0, v[16:17]
	v_pk_mul_f32 v[24:25], v[8:9], v[24:25]
	v_pk_mul_f32 v[20:21], v[10:11], v[20:21]
	v_pk_mul_f32 v[18:19], v[12:13], v[18:19]
	v_lshl_add_u64 v[16:17], v[16:17], 0, s[92:93]
	v_cvt_pk_bf16_f32 v24, v24, v25
	v_cvt_pk_bf16_f32 v25, v20, v21
	v_cvt_pk_bf16_f32 v26, v18, v19
	v_lshl_add_u64 v[16:17], v[16:17], 0, v[0:1]
	flat_store_dwordx4 v[16:17], v[24:27]
	ds_read2_b32 v[22:23], v30 offset0:24 offset1:57
	ds_read2_b32 v[20:21], v30 offset0:90 offset1:123
	ds_read2_b32 v[18:19], v30 offset0:156 offset1:189
	ds_read2_b32 v[16:17], v30 offset0:222 offset1:255
	v_add_u32_e32 v24, s12, v45
	v_mul_hi_i32 v25, v24, s29
	v_lshrrev_b32_e32 v26, 31, v25
	v_lshrrev_b32_e32 v25, 4, v25
	v_add_u32_e32 v25, v25, v26
	s_movk_i32 s4, 0x60
	v_mul_lo_u32 v25, v25, s4
	v_sub_u32_e32 v25, v24, v25
	v_cmp_lt_i32_e32 vcc, 63, v25
	s_and_saveexec_b64 s[4:5], vcc
	v_or_b32_e32 v24, s6, v33
	v_lshlrev_b32_e32 v27, 1, v25
	v_subrev_u32_e32 v26, 64, v25
	v_and_b32_e32 v27, 30, v27
	v_sub_u32_e32 v24, v24, v25
	v_lshrrev_b32_e32 v26, 4, v26
	v_add_u32_e32 v24, v24, v27
	v_add3_u32 v24, v24, v26, 64
	s_or_b64 exec, exec, s[4:5]
	v_ashrrev_i32_e32 v25, 31, v24
	v_lshlrev_b64 v[24:25], 9, v[24:25]
	s_waitcnt lgkmcnt(0)
	v_pk_mul_f32 v[8:9], v[8:9], v[22:23]
	v_pk_mul_f32 v[10:11], v[10:11], v[20:21]
	v_lshl_add_u64 v[24:25], s[64:65], 0, v[24:25]
	v_cvt_pk_bf16_f32 v8, v8, v9
	v_cvt_pk_bf16_f32 v9, v10, v11
	v_pk_mul_f32 v[10:11], v[12:13], v[18:19]
	v_pk_mul_f32 v[12:13], v[14:15], v[16:17]
	v_cvt_pk_bf16_f32 v10, v10, v11
	v_cvt_pk_bf16_f32 v11, v12, v13
	v_lshl_add_u64 v[12:13], v[24:25], 0, s[92:93]
	v_lshl_add_u64 v[12:13], v[12:13], 0, v[0:1]
	flat_store_dwordx4 v[12:13], v[8:11]
	s_waitcnt lgkmcnt(0)

; __device__ __forceinline__ void conv_item(const float* W, int K, int N, int kind, int item, const float* gain, unsigned char* Wb, float* scr, int lane) {
;     const int nblk = N / 32, kb = item / nblk, nb = item - kb * nblk, k0 = 64 * kb, n0 = 32 * nb;
;     float wv_[32];
; #pragma unroll
;     for (int i = 0; i < 32; ++i) wv_[i] = W[(size_t)(k0 + 2 * i + (lane >> 5)) * N + n0 + (lane & 31)];
.LBB0_303:
	s_andn2_b64 vcc, exec, s[4:5]
	s_cbranch_vccnz .LBB0_305
	s_lshl_b32 s4, s76, 5
	s_and_b32 s6, s4, 0xfffffc00
	v_readlane_b32 s4, v254, 40
	v_readlane_b32 s5, v254, 41
	s_load_dwordx2 s[4:5], s[4:5], 0x78
	s_lshl_b32 s7, s73, 1
	v_lshlrev_b32_e32 v0, 2, v4
	s_waitcnt lgkmcnt(0)
	s_add_u32 s12, s4, s44
	s_addc_u32 s13, s5, s45
	s_add_i32 s4, s7, 0x2c0
	s_and_b32 s92, s4, 0xffffffc0
	s_sub_i32 s4, s75, s6
	s_add_i32 s4, s4, 0xfff9f600
	s_ashr_i32 s5, s4, 31
	s_lshl_b64 s[6:7], s[4:5], 2
	s_add_u32 s6, s12, s6
	v_or_b32_e32 v10, s92, v3
	s_addc_u32 s7, s13, s7
	v_lshl_add_u64 v[8:9], s[6:7], 0, v[0:1]
	v_lshlrev_b32_e32 v0, 10, v10
	v_lshl_add_u64 v[8:9], v[0:1], 2, v[8:9]
	s_movk_i32 s5, 0x2000
	v_add_co_u32_e32 v10, vcc, s5, v8
	s_movk_i32 s5, 0x4000
	s_nop 0
	v_addc_co_u32_e32 v11, vcc, 0, v9, vcc
	global_load_dword v0, v[8:9], off
	global_load_dword v12, v[10:11], off
	v_add_co_u32_e32 v10, vcc, s5, v8
	s_movk_i32 s5, 0x6000
	s_nop 0
	v_addc_co_u32_e32 v11, vcc, 0, v9, vcc
	global_load_dword v13, v[10:11], off
	v_add_co_u32_e32 v10, vcc, s5, v8
	s_mov_b32 s5, 0x8000
	s_nop 0
	v_addc_co_u32_e32 v11, vcc, 0, v9, vcc
	global_load_dword v14, v[10:11], off
	v_add_co_u32_e32 v10, vcc, s5, v8
	s_mov_b32 s5, 0xa000
	s_nop 0
	v_addc_co_u32_e32 v11, vcc, 0, v9, vcc
	global_load_dword v15, v[10:11], off
	v_add_co_u32_e32 v10, vcc, s5, v8
	s_mov_b32 s5, 0xc000
	s_nop 0
	v_addc_co_u32_e32 v11, vcc, 0, v9, vcc
	global_load_dword v16, v[10:11], off
	v_add_co_u32_e32 v10, vcc, s5, v8
	s_mov_b32 s5, 0xe000
	s_nop 0
	v_addc_co_u32_e32 v11, vcc, 0, v9, vcc
	global_load_dword v17, v[10:11], off
	v_add_co_u32_e32 v10, vcc, s5, v8
	s_mov_b32 s5, 0x10000
	s_nop 0
	v_addc_co_u32_e32 v11, vcc, 0, v9, vcc
	global_load_dword v18, v[10:11], off
	v_add_co_u32_e32 v10, vcc, s5, v8
	s_mov_b32 s5, 0x12000
	s_nop 0
	v_addc_co_u32_e32 v11, vcc, 0, v9, vcc
	global_load_dword v19, v[10:11], off
	v_add_co_u32_e32 v10, vcc, s5, v8
	s_mov_b32 s5, 0x14000
	s_nop 0
	v_addc_co_u32_e32 v11, vcc, 0, v9, vcc
	global_load_dword v20, v[10:11], off
	v_add_co_u32_e32 v10, vcc, s5, v8
	s_mov_b32 s5, 0x16000
	s_nop 0
	v_addc_co_u32_e32 v11, vcc, 0, v9, vcc
	global_load_dword v21, v[10:11], off
	v_add_co_u32_e32 v10, vcc, s5, v8
	s_mov_b32 s5, 0x18000
	s_nop 0
	v_addc_co_u32_e32 v11, vcc, 0, v9, vcc
	global_load_dword v22, v[10:11], off
	v_add_co_u32_e32 v10, vcc, s5, v8
	s_mov_b32 s5, 0x1a000
	s_nop 0
	v_addc_co_u32_e32 v11, vcc, 0, v9, vcc
	global_load_dword v23, v[10:11], off
	v_add_co_u32_e32 v10, vcc, s5, v8
	s_mov_b32 s5, 0x1c000
	s_nop 0
	v_addc_co_u32_e32 v11, vcc, 0, v9, vcc
	global_load_dword v24, v[10:11], off
	v_add_co_u32_e32 v10, vcc, s5, v8
	s_mov_b32 s5, 0x1e000
	s_nop 0
	v_addc_co_u32_e32 v11, vcc, 0, v9, vcc
	global_load_dword v25, v[10:11], off
	v_add_co_u32_e32 v10, vcc, s5, v8
	s_mov_b32 s5, 0x20000
	s_nop 0
	v_addc_co_u32_e32 v11, vcc, 0, v9, vcc
	global_load_dword v26, v[10:11], off
	v_add_co_u32_e32 v10, vcc, s5, v8
	s_mov_b32 s5, 0x22000
	s_nop 0
	v_addc_co_u32_e32 v11, vcc, 0, v9, vcc
	global_load_dword v27, v[10:11], off
	v_add_co_u32_e32 v10, vcc, s5, v8
	s_mov_b32 s5, 0x24000
	s_nop 0
	v_addc_co_u32_e32 v11, vcc, 0, v9, vcc
	global_load_dword v28, v[10:11], off
	v_add_co_u32_e32 v10, vcc, s5, v8
	s_mov_b32 s5, 0x26000
	s_nop 0
	v_addc_co_u32_e32 v11, vcc, 0, v9, vcc
	global_load_dword v29, v[10:11], off
	v_add_co_u32_e32 v10, vcc, s5, v8
	s_mov_b32 s5, 0x28000
	s_nop 0
	v_addc_co_u32_e32 v11, vcc, 0, v9, vcc
	global_load_dword v104, v[10:11], off
	v_add_co_u32_e32 v10, vcc, s5, v8
	s_mov_b32 s5, 0x2a000
	s_nop 0
	v_addc_co_u32_e32 v11, vcc, 0, v9, vcc
	global_load_dword v105, v[10:11], off
	v_add_co_u32_e32 v10, vcc, s5, v8
	s_mov_b32 s5, 0x2c000
	s_nop 0
	v_addc_co_u32_e32 v11, vcc, 0, v9, vcc
	global_load_dword v106, v[10:11], off
	v_add_co_u32_e32 v10, vcc, s5, v8
	s_mov_b32 s5, 0x2e000
	s_nop 0
	v_addc_co_u32_e32 v11, vcc, 0, v9, vcc
	global_load_dword v107, v[10:11], off
	v_add_co_u32_e32 v10, vcc, s5, v8
	s_mov_b32 s5, 0x30000
	s_nop 0
	v_addc_co_u32_e32 v11, vcc, 0, v9, vcc
	global_load_dword v108, v[10:11], off
	v_add_co_u32_e32 v10, vcc, s5, v8
	s_mov_b32 s5, 0x32000
	s_nop 0
	v_addc_co_u32_e32 v11, vcc, 0, v9, vcc
	global_load_dword v109, v[10:11], off
	v_add_co_u32_e32 v10, vcc, s5, v8
	s_mov_b32 s5, 0x34000
	s_nop 0
	v_addc_co_u32_e32 v11, vcc, 0, v9, vcc
	global_load_dword v110, v[10:11], off
	v_add_co_u32_e32 v10, vcc, s5, v8
	s_mov_b32 s5, 0x36000
	s_nop 0
	v_addc_co_u32_e32 v11, vcc, 0, v9, vcc
	global_load_dword v111, v[10:11], off
	v_add_co_u32_e32 v10, vcc, s5, v8
	s_mov_b32 s5, 0x38000
	s_nop 0
	v_addc_co_u32_e32 v11, vcc, 0, v9, vcc
	global_load_dword v112, v[10:11], off
	v_add_co_u32_e32 v10, vcc, s5, v8
	s_mov_b32 s5, 0x3a000
	s_nop 0
	v_addc_co_u32_e32 v11, vcc, 0, v9, vcc
	global_load_dword v113, v[10:11], off
	v_add_co_u32_e32 v10, vcc, s5, v8
	s_mov_b32 s5, 0x3c000
	s_nop 0
	v_addc_co_u32_e32 v11, vcc, 0, v9, vcc
	global_load_dword v114, v[10:11], off
	v_add_co_u32_e32 v10, vcc, s5, v8
	s_mov_b32 s5, 0x3e000
	s_nop 0
	v_addc_co_u32_e32 v11, vcc, 0, v9, vcc
	v_add_co_u32_e32 v8, vcc, s5, v8
	global_load_dword v10, v[10:11], off
	s_nop 0
	v_addc_co_u32_e32 v9, vcc, 0, v9, vcc
	global_load_dword v8, v[8:9], off
	s_waitcnt vmcnt(0)
; __device__ __forceinline__ unsigned pk2(float lo, float hi) { f32x2_t v = {lo, hi}; bf16x2_t b = __builtin_convertvector(v, bf16x2_t); return __builtin_bit_cast(unsigned, b); }
; __device__ __forceinline__ bf16_t* wdst(int kind, int n, unsigned char* Wb) {
;     ...
;     case 9: return (bf16_t*)(Wb + O_WCO) + (size_t)n * 512;
; __device__ __forceinline__ void conv_item(const float* W, int K, int N, int kind, int item, const float* gain, unsigned char* Wb, float* scr, int lane) {
;     ...
;     for (int i = 0; i < 32; ++i) scr[(2 * i + (lane >> 5)) * 33 + (lane & 31)] = wv_[i];
;     __builtin_amdgcn_s_waitcnt(0); asm volatile("" ::: "memory");
;     const int c = lane & 7; float gg[8];
; #pragma unroll
;     for (int e = 0; e < 8; ++e) gg[e] = gain ? gain[k0 + 8 * c + e] : 1.0f;
; #pragma unroll
;     for (int j = 0; j < 4; ++j) { const int n = (lane >> 3) + 8 * j; const float* s = scr + (8 * c) * 33 + n;
;         u32x4 o; o.x = pk2(s[0] * gg[0], s[33] * gg[1]); o.y = pk2(s[2 * 33] * gg[2], s[3 * 33] * gg[3]); o.z = pk2(s[4 * 33] * gg[4], s[5 * 33] * gg[5]); o.w = pk2(s[6 * 33] * gg[6], s[7 * 33] * gg[7]);
;         *(u32x4*)(wdst(kind, n0 + n, Wb) + k0 + 8 * c) = o; }
;     __builtin_amdgcn_s_waitcnt(0); asm volatile("" ::: "memory");
	ds_write2_b32 v5, v0, v12 offset1:66
	ds_write2_b32 v5, v13, v14 offset0:132 offset1:198
	v_add_u32_e32 v0, 0x400, v5
	ds_write2_b32 v0, v15, v16 offset0:8 offset1:74
	ds_write2_b32 v0, v17, v18 offset0:140 offset1:206
	v_add_u32_e32 v0, 0x800, v5
	ds_write2_b32 v0, v19, v20 offset0:16 offset1:82
	ds_write2_b32 v0, v21, v22 offset0:148 offset1:214
	v_add_u32_e32 v0, 0xc00, v5
	ds_write2_b32 v0, v23, v24 offset0:24 offset1:90
	ds_write2_b32 v0, v25, v26 offset0:156 offset1:222
	v_add_u32_e32 v0, 0x1000, v5
	ds_write2_b32 v0, v27, v28 offset0:32 offset1:98
	ds_write2_b32 v0, v29, v104 offset0:164 offset1:230
	v_add_u32_e32 v0, 0x1400, v5
	ds_write2_b32 v0, v105, v106 offset0:40 offset1:106
	ds_write2_b32 v0, v107, v108 offset0:172 offset1:238
	v_add_u32_e32 v0, 0x1800, v5
	ds_write2_b32 v0, v109, v110 offset0:48 offset1:114
	ds_write2_b32 v0, v111, v112 offset0:180 offset1:246
	v_add_u32_e32 v0, 0x1c00, v5
	ds_write2_b32 v0, v113, v114 offset0:56 offset1:122
	ds_write2_b32 v0, v10, v8 offset0:188 offset1:254
	s_waitcnt vmcnt(0) expcnt(0) lgkmcnt(0)
	ds_read_b32 v0, v30
	ds_read_b32 v8, v30 offset:132
	s_lshl_b64 s[6:7], s[92:93], 1
	s_waitcnt lgkmcnt(0)
	v_cvt_pk_bf16_f32 v8, v0, v8
	ds_read_b32 v0, v30 offset:264
	ds_read_b32 v9, v30 offset:396
	s_waitcnt lgkmcnt(0)
	v_cvt_pk_bf16_f32 v9, v0, v9
	ds_read_b32 v0, v30 offset:528
	ds_read_b32 v10, v30 offset:660
	s_waitcnt lgkmcnt(0)
	v_cvt_pk_bf16_f32 v10, v0, v10
	ds_read_b32 v0, v30 offset:792
	ds_read_b32 v11, v30 offset:924
	s_waitcnt lgkmcnt(0)
	v_cvt_pk_bf16_f32 v11, v0, v11
	v_add_u32_e32 v0, s4, v49
	v_add_u32_e32 v12, 0x60a00, v0
	v_ashrrev_i32_e32 v13, 31, v12
	v_lshlrev_b64 v[12:13], 10, v[12:13]
	v_lshl_add_u64 v[12:13], s[46:47], 0, v[12:13]
	v_lshl_add_u64 v[12:13], v[12:13], 0, s[6:7]
	v_lshlrev_b32_e32 v0, 1, v6
	v_lshl_add_u64 v[12:13], v[12:13], 0, v[0:1]
	flat_store_dwordx4 v[12:13], v[8:11]
	ds_read_b32 v8, v30 offset:32
	ds_read_b32 v9, v30 offset:164
	s_waitcnt lgkmcnt(0)
	v_cvt_pk_bf16_f32 v8, v8, v9
	ds_read_b32 v9, v30 offset:296
	ds_read_b32 v10, v30 offset:428
	s_waitcnt lgkmcnt(0)
	v_cvt_pk_bf16_f32 v9, v9, v10
	ds_read_b32 v10, v30 offset:560
	ds_read_b32 v11, v30 offset:692
	s_waitcnt lgkmcnt(0)
	v_cvt_pk_bf16_f32 v10, v10, v11
	ds_read_b32 v11, v30 offset:824
	ds_read_b32 v12, v30 offset:956
	s_waitcnt lgkmcnt(0)
	v_cvt_pk_bf16_f32 v11, v11, v12
	v_add_u32_e32 v12, s4, v50
	v_add_u32_e32 v12, 0x60a00, v12
	v_ashrrev_i32_e32 v13, 31, v12
	v_lshlrev_b64 v[12:13], 10, v[12:13]
	v_lshl_add_u64 v[12:13], s[46:47], 0, v[12:13]
	v_lshl_add_u64 v[12:13], v[12:13], 0, s[6:7]
	v_lshl_add_u64 v[12:13], v[12:13], 0, v[0:1]
	flat_store_dwordx4 v[12:13], v[8:11]
	ds_read_b32 v8, v30 offset:64
	ds_read_b32 v9, v30 offset:196
	s_waitcnt lgkmcnt(0)
	v_cvt_pk_bf16_f32 v8, v8, v9
	ds_read_b32 v9, v30 offset:328
	ds_read_b32 v10, v30 offset:460
	s_waitcnt lgkmcnt(0)
	v_cvt_pk_bf16_f32 v9, v9, v10
	ds_read_b32 v10, v30 offset:592
	ds_read_b32 v11, v30 offset:724
	s_waitcnt lgkmcnt(0)
	v_cvt_pk_bf16_f32 v10, v10, v11
	ds_read_b32 v11, v30 offset:856
	ds_read_b32 v12, v30 offset:988
	s_waitcnt lgkmcnt(0)
	v_cvt_pk_bf16_f32 v11, v11, v12
	v_add_u32_e32 v12, s4, v51
	v_add_u32_e32 v12, 0x60a00, v12
	v_ashrrev_i32_e32 v13, 31, v12
	v_lshlrev_b64 v[12:13], 10, v[12:13]
	v_lshl_add_u64 v[12:13], s[46:47], 0, v[12:13]
	v_lshl_add_u64 v[12:13], v[12:13], 0, s[6:7]
	v_lshl_add_u64 v[12:13], v[12:13], 0, v[0:1]
	flat_store_dwordx4 v[12:13], v[8:11]
	ds_read_b32 v10, v30 offset:96
	ds_read_b32 v11, v30 offset:228
	ds_read_b32 v14, v30 offset:360
	ds_read_b32 v15, v30 offset:492
	ds_read_b32 v16, v30 offset:624
	ds_read_b32 v17, v30 offset:756
	ds_read_b32 v18, v30 offset:888
	ds_read_b32 v19, v30 offset:1020
	v_add_u32_e32 v8, s4, v52
	v_add_u32_e32 v8, 0x60a00, v8
	v_ashrrev_i32_e32 v9, 31, v8
	v_lshlrev_b64 v[8:9], 10, v[8:9]
	v_lshl_add_u64 v[12:13], s[46:47], 0, v[8:9]
	v_lshl_add_u64 v[12:13], v[12:13], 0, s[6:7]
	s_waitcnt lgkmcnt(0)
	v_cvt_pk_bf16_f32 v8, v10, v11
	v_cvt_pk_bf16_f32 v9, v14, v15
	v_cvt_pk_bf16_f32 v10, v16, v17
	v_cvt_pk_bf16_f32 v11, v18, v19
	v_lshl_add_u64 v[12:13], v[12:13], 0, v[0:1]
	flat_store_dwordx4 v[12:13], v[8:11]
	s_waitcnt lgkmcnt(0)

; __device__ __forceinline__ void conv_item(const float* W, int K, int N, int kind, int item, const float* gain, unsigned char* Wb, float* scr, int lane) {
;     const int nblk = N / 32, kb = item / nblk, nb = item - kb * nblk, k0 = 64 * kb, n0 = 32 * nb;
;     float wv_[32];
; #pragma unroll
;     for (int i = 0; i < 32; ++i) wv_[i] = W[(size_t)(k0 + 2 * i + (lane >> 5)) * N + n0 + (lane & 31)];
.LBB0_306:
	s_andn2_b64 vcc, exec, s[4:5]
	s_cbranch_vccnz .LBB0_308
	s_lshl_b32 s4, s77, 5
	s_and_b32 s6, s4, 0xfffffc00
	v_readlane_b32 s4, v254, 40
	v_readlane_b32 s5, v254, 41
	s_load_dwordx2 s[4:5], s[4:5], 0x68
	s_lshl_b32 s7, s73, 1
	v_lshlrev_b32_e32 v0, 2, v4
	s_waitcnt lgkmcnt(0)
	s_add_u32 s12, s4, s44
	s_addc_u32 s13, s5, s45
	s_add_i32 s4, s7, 0x4c0
	s_and_b32 s92, s4, 0xffffffc0
	s_sub_i32 s4, s75, s6
	s_add_i32 s4, s4, 0xfffa1600
	s_ashr_i32 s5, s4, 31
	s_lshl_b64 s[6:7], s[4:5], 2
	s_add_u32 s6, s12, s6
	v_or_b32_e32 v10, s92, v3
	s_addc_u32 s7, s13, s7
	v_lshl_add_u64 v[8:9], s[6:7], 0, v[0:1]
	v_lshlrev_b32_e32 v0, 10, v10
	v_lshl_add_u64 v[8:9], v[0:1], 2, v[8:9]
	s_movk_i32 s5, 0x2000
	v_add_co_u32_e32 v10, vcc, s5, v8
	s_movk_i32 s5, 0x4000
	s_nop 0
	v_addc_co_u32_e32 v11, vcc, 0, v9, vcc
	global_load_dword v0, v[8:9], off
	global_load_dword v12, v[10:11], off
	v_add_co_u32_e32 v10, vcc, s5, v8
	s_movk_i32 s5, 0x6000
	s_nop 0
	v_addc_co_u32_e32 v11, vcc, 0, v9, vcc
	global_load_dword v13, v[10:11], off
	v_add_co_u32_e32 v10, vcc, s5, v8
	s_mov_b32 s5, 0x8000
	s_nop 0
	v_addc_co_u32_e32 v11, vcc, 0, v9, vcc
	global_load_dword v14, v[10:11], off
	v_add_co_u32_e32 v10, vcc, s5, v8
	s_mov_b32 s5, 0xa000
	s_nop 0
	v_addc_co_u32_e32 v11, vcc, 0, v9, vcc
	global_load_dword v15, v[10:11], off
	v_add_co_u32_e32 v10, vcc, s5, v8
	s_mov_b32 s5, 0xc000
	s_nop 0
	v_addc_co_u32_e32 v11, vcc, 0, v9, vcc
	global_load_dword v16, v[10:11], off
	v_add_co_u32_e32 v10, vcc, s5, v8
	s_mov_b32 s5, 0xe000
	s_nop 0
	v_addc_co_u32_e32 v11, vcc, 0, v9, vcc
	global_load_dword v17, v[10:11], off
	v_add_co_u32_e32 v10, vcc, s5, v8
	s_mov_b32 s5, 0x10000
	s_nop 0
	v_addc_co_u32_e32 v11, vcc, 0, v9, vcc
	global_load_dword v18, v[10:11], off
	v_add_co_u32_e32 v10, vcc, s5, v8
	s_mov_b32 s5, 0x12000
	s_nop 0
	v_addc_co_u32_e32 v11, vcc, 0, v9, vcc
	global_load_dword v19, v[10:11], off
	v_add_co_u32_e32 v10, vcc, s5, v8
	s_mov_b32 s5, 0x14000
	s_nop 0
	v_addc_co_u32_e32 v11, vcc, 0, v9, vcc
	global_load_dword v20, v[10:11], off
	v_add_co_u32_e32 v10, vcc, s5, v8
	s_mov_b32 s5, 0x16000
	s_nop 0
	v_addc_co_u32_e32 v11, vcc, 0, v9, vcc
	global_load_dword v21, v[10:11], off
	v_add_co_u32_e32 v10, vcc, s5, v8
	s_mov_b32 s5, 0x18000
	s_nop 0
	v_addc_co_u32_e32 v11, vcc, 0, v9, vcc
	global_load_dword v22, v[10:11], off
	v_add_co_u32_e32 v10, vcc, s5, v8
	s_mov_b32 s5, 0x1a000
	s_nop 0
	v_addc_co_u32_e32 v11, vcc, 0, v9, vcc
	global_load_dword v23, v[10:11], off
	v_add_co_u32_e32 v10, vcc, s5, v8
	s_mov_b32 s5, 0x1c000
	s_nop 0
	v_addc_co_u32_e32 v11, vcc, 0, v9, vcc
	global_load_dword v24, v[10:11], off
	v_add_co_u32_e32 v10, vcc, s5, v8
	s_mov_b32 s5, 0x1e000
	s_nop 0
	v_addc_co_u32_e32 v11, vcc, 0, v9, vcc
	global_load_dword v25, v[10:11], off
	v_add_co_u32_e32 v10, vcc, s5, v8
	s_mov_b32 s5, 0x20000
	s_nop 0
	v_addc_co_u32_e32 v11, vcc, 0, v9, vcc
	global_load_dword v26, v[10:11], off
	v_add_co_u32_e32 v10, vcc, s5, v8
	s_mov_b32 s5, 0x22000
	s_nop 0
	v_addc_co_u32_e32 v11, vcc, 0, v9, vcc
	global_load_dword v27, v[10:11], off
	v_add_co_u32_e32 v10, vcc, s5, v8
	s_mov_b32 s5, 0x24000
	s_nop 0
	v_addc_co_u32_e32 v11, vcc, 0, v9, vcc
	global_load_dword v28, v[10:11], off
	v_add_co_u32_e32 v10, vcc, s5, v8
	s_mov_b32 s5, 0x26000
	s_nop 0
	v_addc_co_u32_e32 v11, vcc, 0, v9, vcc
	global_load_dword v29, v[10:11], off
	v_add_co_u32_e32 v10, vcc, s5, v8
	s_mov_b32 s5, 0x28000
	s_nop 0
	v_addc_co_u32_e32 v11, vcc, 0, v9, vcc
	global_load_dword v104, v[10:11], off
	v_add_co_u32_e32 v10, vcc, s5, v8
	s_mov_b32 s5, 0x2a000
	s_nop 0
	v_addc_co_u32_e32 v11, vcc, 0, v9, vcc
	global_load_dword v105, v[10:11], off
	v_add_co_u32_e32 v10, vcc, s5, v8
	s_mov_b32 s5, 0x2c000
	s_nop 0
	v_addc_co_u32_e32 v11, vcc, 0, v9, vcc
	global_load_dword v106, v[10:11], off
	v_add_co_u32_e32 v10, vcc, s5, v8
	s_mov_b32 s5, 0x2e000
	s_nop 0
	v_addc_co_u32_e32 v11, vcc, 0, v9, vcc
	global_load_dword v107, v[10:11], off
	v_add_co_u32_e32 v10, vcc, s5, v8
	s_mov_b32 s5, 0x30000
	s_nop 0
	v_addc_co_u32_e32 v11, vcc, 0, v9, vcc
	global_load_dword v108, v[10:11], off
	v_add_co_u32_e32 v10, vcc, s5, v8
	s_mov_b32 s5, 0x32000
	s_nop 0
	v_addc_co_u32_e32 v11, vcc, 0, v9, vcc
	global_load_dword v109, v[10:11], off
	v_add_co_u32_e32 v10, vcc, s5, v8
	s_mov_b32 s5, 0x34000
	s_nop 0
	v_addc_co_u32_e32 v11, vcc, 0, v9, vcc
	global_load_dword v110, v[10:11], off
	v_add_co_u32_e32 v10, vcc, s5, v8
	s_mov_b32 s5, 0x36000
	s_nop 0
	v_addc_co_u32_e32 v11, vcc, 0, v9, vcc
	global_load_dword v111, v[10:11], off
	v_add_co_u32_e32 v10, vcc, s5, v8
	s_mov_b32 s5, 0x38000
	s_nop 0
	v_addc_co_u32_e32 v11, vcc, 0, v9, vcc
	global_load_dword v112, v[10:11], off
	v_add_co_u32_e32 v10, vcc, s5, v8
	s_mov_b32 s5, 0x3a000
	s_nop 0
	v_addc_co_u32_e32 v11, vcc, 0, v9, vcc
	global_load_dword v113, v[10:11], off
	v_add_co_u32_e32 v10, vcc, s5, v8
	s_mov_b32 s5, 0x3c000
	s_nop 0
	v_addc_co_u32_e32 v11, vcc, 0, v9, vcc
	global_load_dword v114, v[10:11], off
	v_add_co_u32_e32 v10, vcc, s5, v8
	s_mov_b32 s5, 0x3e000
	s_nop 0
	v_addc_co_u32_e32 v11, vcc, 0, v9, vcc
	v_add_co_u32_e32 v8, vcc, s5, v8
	global_load_dword v10, v[10:11], off
	s_nop 0
	v_addc_co_u32_e32 v9, vcc, 0, v9, vcc
	global_load_dword v8, v[8:9], off
	s_waitcnt vmcnt(0)
; __device__ __forceinline__ unsigned pk2(float lo, float hi) { f32x2_t v = {lo, hi}; bf16x2_t b = __builtin_convertvector(v, bf16x2_t); return __builtin_bit_cast(unsigned, b); }
; __device__ __forceinline__ bf16_t* wdst(int kind, int n, unsigned char* Wb) {
;     ...
;     case 8: return (bf16_t*)(Wb + O_WBO) + (size_t)n * 512;
; __device__ __forceinline__ void conv_item(const float* W, int K, int N, int kind, int item, const float* gain, unsigned char* Wb, float* scr, int lane) {
;     ...
;     for (int i = 0; i < 32; ++i) scr[(2 * i + (lane >> 5)) * 33 + (lane & 31)] = wv_[i];
;     __builtin_amdgcn_s_waitcnt(0); asm volatile("" ::: "memory");
;     const int c = lane & 7; float gg[8];
; #pragma unroll
;     for (int e = 0; e < 8; ++e) gg[e] = gain ? gain[k0 + 8 * c + e] : 1.0f;
; #pragma unroll
;     for (int j = 0; j < 4; ++j) { const int n = (lane >> 3) + 8 * j; const float* s = scr + (8 * c) * 33 + n;
;         u32x4 o; o.x = pk2(s[0] * gg[0], s[33] * gg[1]); o.y = pk2(s[2 * 33] * gg[2], s[3 * 33] * gg[3]); o.z = pk2(s[4 * 33] * gg[4], s[5 * 33] * gg[5]); o.w = pk2(s[6 * 33] * gg[6], s[7 * 33] * gg[7]);
;         *(u32x4*)(wdst(kind, n0 + n, Wb) + k0 + 8 * c) = o; }
;     __builtin_amdgcn_s_waitcnt(0); asm volatile("" ::: "memory");
	ds_write2_b32 v5, v0, v12 offset1:66
	ds_write2_b32 v5, v13, v14 offset0:132 offset1:198
	v_add_u32_e32 v0, 0x400, v5
	ds_write2_b32 v0, v15, v16 offset0:8 offset1:74
	ds_write2_b32 v0, v17, v18 offset0:140 offset1:206
	v_add_u32_e32 v0, 0x800, v5
	ds_write2_b32 v0, v19, v20 offset0:16 offset1:82
	ds_write2_b32 v0, v21, v22 offset0:148 offset1:214
	v_add_u32_e32 v0, 0xc00, v5
	ds_write2_b32 v0, v23, v24 offset0:24 offset1:90
	ds_write2_b32 v0, v25, v26 offset0:156 offset1:222
	v_add_u32_e32 v0, 0x1000, v5
	ds_write2_b32 v0, v27, v28 offset0:32 offset1:98
	ds_write2_b32 v0, v29, v104 offset0:164 offset1:230
	v_add_u32_e32 v0, 0x1400, v5
	ds_write2_b32 v0, v105, v106 offset0:40 offset1:106
	ds_write2_b32 v0, v107, v108 offset0:172 offset1:238
	v_add_u32_e32 v0, 0x1800, v5
	ds_write2_b32 v0, v109, v110 offset0:48 offset1:114
	ds_write2_b32 v0, v111, v112 offset0:180 offset1:246
	v_add_u32_e32 v0, 0x1c00, v5
	ds_write2_b32 v0, v113, v114 offset0:56 offset1:122
	ds_write2_b32 v0, v10, v8 offset0:188 offset1:254
	s_waitcnt vmcnt(0) expcnt(0) lgkmcnt(0)
	ds_read_b32 v0, v30
	ds_read_b32 v8, v30 offset:132
	s_lshl_b64 s[6:7], s[92:93], 1
	s_waitcnt lgkmcnt(0)
	v_cvt_pk_bf16_f32 v8, v0, v8
	ds_read_b32 v0, v30 offset:264
	ds_read_b32 v9, v30 offset:396
	s_waitcnt lgkmcnt(0)
	v_cvt_pk_bf16_f32 v9, v0, v9
	ds_read_b32 v0, v30 offset:528
	ds_read_b32 v10, v30 offset:660
	s_waitcnt lgkmcnt(0)
	v_cvt_pk_bf16_f32 v10, v0, v10
	ds_read_b32 v0, v30 offset:792
	ds_read_b32 v11, v30 offset:924
	s_waitcnt lgkmcnt(0)
	v_cvt_pk_bf16_f32 v11, v0, v11
	v_add_u32_e32 v0, s4, v53
	v_add_u32_e32 v12, 0x5ea00, v0
	v_ashrrev_i32_e32 v13, 31, v12
	v_lshlrev_b64 v[12:13], 10, v[12:13]
	v_lshl_add_u64 v[12:13], s[48:49], 0, v[12:13]
	v_lshl_add_u64 v[12:13], v[12:13], 0, s[6:7]
	v_lshlrev_b32_e32 v0, 1, v6
	v_lshl_add_u64 v[12:13], v[12:13], 0, v[0:1]
	flat_store_dwordx4 v[12:13], v[8:11]
	ds_read_b32 v8, v30 offset:32
	ds_read_b32 v9, v30 offset:164
	s_waitcnt lgkmcnt(0)
	v_cvt_pk_bf16_f32 v8, v8, v9
	ds_read_b32 v9, v30 offset:296
	ds_read_b32 v10, v30 offset:428
	s_waitcnt lgkmcnt(0)
	v_cvt_pk_bf16_f32 v9, v9, v10
	ds_read_b32 v10, v30 offset:560
	ds_read_b32 v11, v30 offset:692
	s_waitcnt lgkmcnt(0)
	v_cvt_pk_bf16_f32 v10, v10, v11
	ds_read_b32 v11, v30 offset:824
	ds_read_b32 v12, v30 offset:956
	s_waitcnt lgkmcnt(0)
	v_cvt_pk_bf16_f32 v11, v11, v12
	v_add_u32_e32 v12, s4, v54
	v_add_u32_e32 v12, 0x5ea00, v12
	v_ashrrev_i32_e32 v13, 31, v12
	v_lshlrev_b64 v[12:13], 10, v[12:13]
	v_lshl_add_u64 v[12:13], s[48:49], 0, v[12:13]
	v_lshl_add_u64 v[12:13], v[12:13], 0, s[6:7]
	v_lshl_add_u64 v[12:13], v[12:13], 0, v[0:1]
	flat_store_dwordx4 v[12:13], v[8:11]
	ds_read_b32 v8, v30 offset:64
	ds_read_b32 v9, v30 offset:196
	s_waitcnt lgkmcnt(0)
	v_cvt_pk_bf16_f32 v8, v8, v9
	ds_read_b32 v9, v30 offset:328
	ds_read_b32 v10, v30 offset:460
	s_waitcnt lgkmcnt(0)
	v_cvt_pk_bf16_f32 v9, v9, v10
	ds_read_b32 v10, v30 offset:592
	ds_read_b32 v11, v30 offset:724
	s_waitcnt lgkmcnt(0)
	v_cvt_pk_bf16_f32 v10, v10, v11
	ds_read_b32 v11, v30 offset:856
	ds_read_b32 v12, v30 offset:988
	s_waitcnt lgkmcnt(0)
	v_cvt_pk_bf16_f32 v11, v11, v12
	v_add_u32_e32 v12, s4, v55
	v_add_u32_e32 v12, 0x5ea00, v12
	v_ashrrev_i32_e32 v13, 31, v12
	v_lshlrev_b64 v[12:13], 10, v[12:13]
	v_lshl_add_u64 v[12:13], s[48:49], 0, v[12:13]
	v_lshl_add_u64 v[12:13], v[12:13], 0, s[6:7]
	v_lshl_add_u64 v[12:13], v[12:13], 0, v[0:1]
	flat_store_dwordx4 v[12:13], v[8:11]
	ds_read_b32 v10, v30 offset:96
	ds_read_b32 v11, v30 offset:228
	ds_read_b32 v14, v30 offset:360
	ds_read_b32 v15, v30 offset:492
	ds_read_b32 v16, v30 offset:624
	ds_read_b32 v17, v30 offset:756
	ds_read_b32 v18, v30 offset:888
	ds_read_b32 v19, v30 offset:1020
	v_add_u32_e32 v8, s4, v56
	v_add_u32_e32 v8, 0x5ea00, v8
	v_ashrrev_i32_e32 v9, 31, v8
	v_lshlrev_b64 v[8:9], 10, v[8:9]
	v_lshl_add_u64 v[12:13], s[48:49], 0, v[8:9]
	v_lshl_add_u64 v[12:13], v[12:13], 0, s[6:7]
	s_waitcnt lgkmcnt(0)
	v_cvt_pk_bf16_f32 v8, v10, v11
	v_cvt_pk_bf16_f32 v9, v14, v15
	v_cvt_pk_bf16_f32 v10, v16, v17
	v_cvt_pk_bf16_f32 v11, v18, v19
	v_lshl_add_u64 v[12:13], v[12:13], 0, v[0:1]
	flat_store_dwordx4 v[12:13], v[8:11]
	s_waitcnt lgkmcnt(0)

; __device__ __forceinline__ void conv_item(const float* W, int K, int N, int kind, int item, const float* gain, unsigned char* Wb, float* scr, int lane) {
;     const int nblk = N / 32, kb = item / nblk, nb = item - kb * nblk, k0 = 64 * kb, n0 = 32 * nb;
;     float wv_[32];
; #pragma unroll
;     for (int i = 0; i < 32; ++i) wv_[i] = W[(size_t)(k0 + 2 * i + (lane >> 5)) * N + n0 + (lane & 31)];
.LBB0_309:
	s_andn2_b64 vcc, exec, s[4:5]
	s_cbranch_vccnz .LBB0_311
	s_lshl_b32 s4, s78, 5
	s_and_b32 s6, s4, 0xfffffc00
	v_readlane_b32 s4, v254, 40
	v_readlane_b32 s5, v254, 41
	s_load_dwordx2 s[4:5], s[4:5], 0x58
	s_lshl_b32 s7, s73, 1
	v_lshlrev_b32_e32 v0, 2, v4
	s_waitcnt lgkmcnt(0)
	s_add_u32 s12, s4, s44
	s_addc_u32 s13, s5, s45
	s_add_i32 s4, s7, 0x6c0
	s_and_b32 s92, s4, 0xffffffc0
	s_sub_i32 s4, s75, s6
	s_add_i32 s4, s4, 0xfffa3600
	s_ashr_i32 s5, s4, 31
	s_lshl_b64 s[6:7], s[4:5], 2
	s_add_u32 s6, s12, s6
	v_or_b32_e32 v10, s92, v3
	s_addc_u32 s7, s13, s7
	v_lshl_add_u64 v[8:9], s[6:7], 0, v[0:1]
	v_lshlrev_b32_e32 v0, 10, v10
	v_lshl_add_u64 v[8:9], v[0:1], 2, v[8:9]
	s_movk_i32 s5, 0x2000
	v_add_co_u32_e32 v10, vcc, s5, v8
	s_movk_i32 s5, 0x4000
	s_nop 0
	v_addc_co_u32_e32 v11, vcc, 0, v9, vcc
	global_load_dword v0, v[8:9], off
	global_load_dword v12, v[10:11], off
	v_add_co_u32_e32 v10, vcc, s5, v8
	s_movk_i32 s5, 0x6000
	s_nop 0
	v_addc_co_u32_e32 v11, vcc, 0, v9, vcc
	global_load_dword v13, v[10:11], off
	v_add_co_u32_e32 v10, vcc, s5, v8
	s_mov_b32 s5, 0x8000
	s_nop 0
	v_addc_co_u32_e32 v11, vcc, 0, v9, vcc
	global_load_dword v14, v[10:11], off
	v_add_co_u32_e32 v10, vcc, s5, v8
	s_mov_b32 s5, 0xa000
	s_nop 0
	v_addc_co_u32_e32 v11, vcc, 0, v9, vcc
	global_load_dword v15, v[10:11], off
	v_add_co_u32_e32 v10, vcc, s5, v8
	s_mov_b32 s5, 0xc000
	s_nop 0
	v_addc_co_u32_e32 v11, vcc, 0, v9, vcc
	global_load_dword v16, v[10:11], off
	v_add_co_u32_e32 v10, vcc, s5, v8
	s_mov_b32 s5, 0xe000
	s_nop 0
	v_addc_co_u32_e32 v11, vcc, 0, v9, vcc
	global_load_dword v17, v[10:11], off
	v_add_co_u32_e32 v10, vcc, s5, v8
	s_mov_b32 s5, 0x10000
	s_nop 0
	v_addc_co_u32_e32 v11, vcc, 0, v9, vcc
	global_load_dword v18, v[10:11], off
	v_add_co_u32_e32 v10, vcc, s5, v8
	s_mov_b32 s5, 0x12000
	s_nop 0
	v_addc_co_u32_e32 v11, vcc, 0, v9, vcc
	global_load_dword v19, v[10:11], off
	v_add_co_u32_e32 v10, vcc, s5, v8
	s_mov_b32 s5, 0x14000
	s_nop 0
	v_addc_co_u32_e32 v11, vcc, 0, v9, vcc
	global_load_dword v20, v[10:11], off
	v_add_co_u32_e32 v10, vcc, s5, v8
	s_mov_b32 s5, 0x16000
	s_nop 0
	v_addc_co_u32_e32 v11, vcc, 0, v9, vcc
	global_load_dword v21, v[10:11], off
	v_add_co_u32_e32 v10, vcc, s5, v8
	s_mov_b32 s5, 0x18000
	s_nop 0
	v_addc_co_u32_e32 v11, vcc, 0, v9, vcc
	global_load_dword v22, v[10:11], off
	v_add_co_u32_e32 v10, vcc, s5, v8
	s_mov_b32 s5, 0x1a000
	s_nop 0
	v_addc_co_u32_e32 v11, vcc, 0, v9, vcc
	global_load_dword v23, v[10:11], off
	v_add_co_u32_e32 v10, vcc, s5, v8
	s_mov_b32 s5, 0x1c000
	s_nop 0
	v_addc_co_u32_e32 v11, vcc, 0, v9, vcc
	global_load_dword v24, v[10:11], off
	v_add_co_u32_e32 v10, vcc, s5, v8
	s_mov_b32 s5, 0x1e000
	s_nop 0
	v_addc_co_u32_e32 v11, vcc, 0, v9, vcc
	global_load_dword v25, v[10:11], off
	v_add_co_u32_e32 v10, vcc, s5, v8
	s_mov_b32 s5, 0x20000
	s_nop 0
	v_addc_co_u32_e32 v11, vcc, 0, v9, vcc
	global_load_dword v26, v[10:11], off
	v_add_co_u32_e32 v10, vcc, s5, v8
	s_mov_b32 s5, 0x22000
	s_nop 0
	v_addc_co_u32_e32 v11, vcc, 0, v9, vcc
	global_load_dword v27, v[10:11], off
	v_add_co_u32_e32 v10, vcc, s5, v8
	s_mov_b32 s5, 0x24000
	s_nop 0
	v_addc_co_u32_e32 v11, vcc, 0, v9, vcc
	global_load_dword v28, v[10:11], off
	v_add_co_u32_e32 v10, vcc, s5, v8
	s_mov_b32 s5, 0x26000
	s_nop 0
	v_addc_co_u32_e32 v11, vcc, 0, v9, vcc
	global_load_dword v29, v[10:11], off
	v_add_co_u32_e32 v10, vcc, s5, v8
	s_mov_b32 s5, 0x28000
	s_nop 0
	v_addc_co_u32_e32 v11, vcc, 0, v9, vcc
	global_load_dword v104, v[10:11], off
	v_add_co_u32_e32 v10, vcc, s5, v8
	s_mov_b32 s5, 0x2a000
	s_nop 0
	v_addc_co_u32_e32 v11, vcc, 0, v9, vcc
	global_load_dword v105, v[10:11], off
	v_add_co_u32_e32 v10, vcc, s5, v8
	s_mov_b32 s5, 0x2c000
	s_nop 0
	v_addc_co_u32_e32 v11, vcc, 0, v9, vcc
	global_load_dword v106, v[10:11], off
	v_add_co_u32_e32 v10, vcc, s5, v8
	s_mov_b32 s5, 0x2e000
	s_nop 0
	v_addc_co_u32_e32 v11, vcc, 0, v9, vcc
	global_load_dword v107, v[10:11], off
	v_add_co_u32_e32 v10, vcc, s5, v8
	s_mov_b32 s5, 0x30000
	s_nop 0
	v_addc_co_u32_e32 v11, vcc, 0, v9, vcc
	global_load_dword v108, v[10:11], off
	v_add_co_u32_e32 v10, vcc, s5, v8
	s_mov_b32 s5, 0x32000
	s_nop 0
	v_addc_co_u32_e32 v11, vcc, 0, v9, vcc
	global_load_dword v109, v[10:11], off
	v_add_co_u32_e32 v10, vcc, s5, v8
	s_mov_b32 s5, 0x34000
	s_nop 0
	v_addc_co_u32_e32 v11, vcc, 0, v9, vcc
	global_load_dword v110, v[10:11], off
	v_add_co_u32_e32 v10, vcc, s5, v8
	s_mov_b32 s5, 0x36000
	s_nop 0
	v_addc_co_u32_e32 v11, vcc, 0, v9, vcc
	global_load_dword v111, v[10:11], off
	v_add_co_u32_e32 v10, vcc, s5, v8
	s_mov_b32 s5, 0x38000
	s_nop 0
	v_addc_co_u32_e32 v11, vcc, 0, v9, vcc
	global_load_dword v112, v[10:11], off
	v_add_co_u32_e32 v10, vcc, s5, v8
	s_mov_b32 s5, 0x3a000
	s_nop 0
	v_addc_co_u32_e32 v11, vcc, 0, v9, vcc
	global_load_dword v113, v[10:11], off
	v_add_co_u32_e32 v10, vcc, s5, v8
	s_mov_b32 s5, 0x3c000
	s_nop 0
	v_addc_co_u32_e32 v11, vcc, 0, v9, vcc
	global_load_dword v114, v[10:11], off
	v_add_co_u32_e32 v10, vcc, s5, v8
	s_mov_b32 s5, 0x3e000
	s_nop 0
	v_addc_co_u32_e32 v11, vcc, 0, v9, vcc
	v_add_co_u32_e32 v8, vcc, s5, v8
	global_load_dword v10, v[10:11], off
	s_nop 0
	v_addc_co_u32_e32 v9, vcc, 0, v9, vcc
	global_load_dword v8, v[8:9], off
	s_waitcnt vmcnt(0)
; __device__ __forceinline__ unsigned pk2(float lo, float hi) { f32x2_t v = {lo, hi}; bf16x2_t b = __builtin_convertvector(v, bf16x2_t); return __builtin_bit_cast(unsigned, b); }
; __device__ __forceinline__ bf16_t* wdst(int kind, int n, unsigned char* Wb) {
;     ...
;     case 7: return (bf16_t*)(Wb + O_WAO) + (size_t)n * 512;
; __device__ __forceinline__ void conv_item(const float* W, int K, int N, int kind, int item, const float* gain, unsigned char* Wb, float* scr, int lane) {
;     ...
;     for (int i = 0; i < 32; ++i) scr[(2 * i + (lane >> 5)) * 33 + (lane & 31)] = wv_[i];
;     __builtin_amdgcn_s_waitcnt(0); asm volatile("" ::: "memory");
;     const int c = lane & 7; float gg[8];
; #pragma unroll
;     for (int e = 0; e < 8; ++e) gg[e] = gain ? gain[k0 + 8 * c + e] : 1.0f;
; #pragma unroll
;     for (int j = 0; j < 4; ++j) { const int n = (lane >> 3) + 8 * j; const float* s = scr + (8 * c) * 33 + n;
;         u32x4 o; o.x = pk2(s[0] * gg[0], s[33] * gg[1]); o.y = pk2(s[2 * 33] * gg[2], s[3 * 33] * gg[3]); o.z = pk2(s[4 * 33] * gg[4], s[5 * 33] * gg[5]); o.w = pk2(s[6 * 33] * gg[6], s[7 * 33] * gg[7]);
;         *(u32x4*)(wdst(kind, n0 + n, Wb) + k0 + 8 * c) = o; }
;     __builtin_amdgcn_s_waitcnt(0); asm volatile("" ::: "memory");
	ds_write2_b32 v5, v0, v12 offset1:66
	ds_write2_b32 v5, v13, v14 offset0:132 offset1:198
	v_add_u32_e32 v0, 0x400, v5
	ds_write2_b32 v0, v15, v16 offset0:8 offset1:74
	ds_write2_b32 v0, v17, v18 offset0:140 offset1:206
	v_add_u32_e32 v0, 0x800, v5
	ds_write2_b32 v0, v19, v20 offset0:16 offset1:82
	ds_write2_b32 v0, v21, v22 offset0:148 offset1:214
	v_add_u32_e32 v0, 0xc00, v5
	ds_write2_b32 v0, v23, v24 offset0:24 offset1:90
	ds_write2_b32 v0, v25, v26 offset0:156 offset1:222
	v_add_u32_e32 v0, 0x1000, v5
	ds_write2_b32 v0, v27, v28 offset0:32 offset1:98
	ds_write2_b32 v0, v29, v104 offset0:164 offset1:230
	v_add_u32_e32 v0, 0x1400, v5
	ds_write2_b32 v0, v105, v106 offset0:40 offset1:106
	ds_write2_b32 v0, v107, v108 offset0:172 offset1:238
	v_add_u32_e32 v0, 0x1800, v5
	ds_write2_b32 v0, v109, v110 offset0:48 offset1:114
	ds_write2_b32 v0, v111, v112 offset0:180 offset1:246
	v_add_u32_e32 v0, 0x1c00, v5
	ds_write2_b32 v0, v113, v114 offset0:56 offset1:122
	ds_write2_b32 v0, v10, v8 offset0:188 offset1:254
	s_waitcnt vmcnt(0) expcnt(0) lgkmcnt(0)
	ds_read_b32 v0, v30
	ds_read_b32 v8, v30 offset:132
	s_lshl_b64 s[6:7], s[92:93], 1
	s_waitcnt lgkmcnt(0)
	v_cvt_pk_bf16_f32 v8, v0, v8
	ds_read_b32 v0, v30 offset:264
	ds_read_b32 v9, v30 offset:396
	s_waitcnt lgkmcnt(0)
	v_cvt_pk_bf16_f32 v9, v0, v9
	ds_read_b32 v0, v30 offset:528
	ds_read_b32 v10, v30 offset:660
	s_waitcnt lgkmcnt(0)
	v_cvt_pk_bf16_f32 v10, v0, v10
	ds_read_b32 v0, v30 offset:792
	ds_read_b32 v11, v30 offset:924
	s_waitcnt lgkmcnt(0)
	v_cvt_pk_bf16_f32 v11, v0, v11
	v_add_u32_e32 v0, s4, v57
	v_add_u32_e32 v12, 0x5ca00, v0
	v_ashrrev_i32_e32 v13, 31, v12
	v_lshlrev_b64 v[12:13], 10, v[12:13]
	v_lshl_add_u64 v[12:13], s[50:51], 0, v[12:13]
	v_lshl_add_u64 v[12:13], v[12:13], 0, s[6:7]
	v_lshlrev_b32_e32 v0, 1, v6
	v_lshl_add_u64 v[12:13], v[12:13], 0, v[0:1]
	flat_store_dwordx4 v[12:13], v[8:11]
	ds_read_b32 v8, v30 offset:32
	ds_read_b32 v9, v30 offset:164
	s_waitcnt lgkmcnt(0)
	v_cvt_pk_bf16_f32 v8, v8, v9
	ds_read_b32 v9, v30 offset:296
	ds_read_b32 v10, v30 offset:428
	s_waitcnt lgkmcnt(0)
	v_cvt_pk_bf16_f32 v9, v9, v10
	ds_read_b32 v10, v30 offset:560
	ds_read_b32 v11, v30 offset:692
	s_waitcnt lgkmcnt(0)
	v_cvt_pk_bf16_f32 v10, v10, v11
	ds_read_b32 v11, v30 offset:824
	ds_read_b32 v12, v30 offset:956
	s_waitcnt lgkmcnt(0)
	v_cvt_pk_bf16_f32 v11, v11, v12
	v_add_u32_e32 v12, s4, v58
	v_add_u32_e32 v12, 0x5ca00, v12
	v_ashrrev_i32_e32 v13, 31, v12
	v_lshlrev_b64 v[12:13], 10, v[12:13]
	v_lshl_add_u64 v[12:13], s[50:51], 0, v[12:13]
	v_lshl_add_u64 v[12:13], v[12:13], 0, s[6:7]
	v_lshl_add_u64 v[12:13], v[12:13], 0, v[0:1]
	flat_store_dwordx4 v[12:13], v[8:11]
	ds_read_b32 v8, v30 offset:64
	ds_read_b32 v9, v30 offset:196
	s_waitcnt lgkmcnt(0)
	v_cvt_pk_bf16_f32 v8, v8, v9
	ds_read_b32 v9, v30 offset:328
	ds_read_b32 v10, v30 offset:460
	s_waitcnt lgkmcnt(0)
	v_cvt_pk_bf16_f32 v9, v9, v10
	ds_read_b32 v10, v30 offset:592
	ds_read_b32 v11, v30 offset:724
	s_waitcnt lgkmcnt(0)
	v_cvt_pk_bf16_f32 v10, v10, v11
	ds_read_b32 v11, v30 offset:856
	ds_read_b32 v12, v30 offset:988
	s_waitcnt lgkmcnt(0)
	v_cvt_pk_bf16_f32 v11, v11, v12
	v_add_u32_e32 v12, s4, v59
	v_add_u32_e32 v12, 0x5ca00, v12
	v_ashrrev_i32_e32 v13, 31, v12
	v_lshlrev_b64 v[12:13], 10, v[12:13]
	v_lshl_add_u64 v[12:13], s[50:51], 0, v[12:13]
	v_lshl_add_u64 v[12:13], v[12:13], 0, s[6:7]
	v_lshl_add_u64 v[12:13], v[12:13], 0, v[0:1]
	flat_store_dwordx4 v[12:13], v[8:11]
	ds_read_b32 v10, v30 offset:96
	ds_read_b32 v11, v30 offset:228
	ds_read_b32 v14, v30 offset:360
	ds_read_b32 v15, v30 offset:492
	ds_read_b32 v16, v30 offset:624
	ds_read_b32 v17, v30 offset:756
	ds_read_b32 v18, v30 offset:888
	ds_read_b32 v19, v30 offset:1020
	v_add_u32_e32 v8, s4, v60
	v_add_u32_e32 v8, 0x5ca00, v8
	v_ashrrev_i32_e32 v9, 31, v8
	v_lshlrev_b64 v[8:9], 10, v[8:9]
	v_lshl_add_u64 v[12:13], s[50:51], 0, v[8:9]
	v_lshl_add_u64 v[12:13], v[12:13], 0, s[6:7]
	s_waitcnt lgkmcnt(0)
	v_cvt_pk_bf16_f32 v8, v10, v11
	v_cvt_pk_bf16_f32 v9, v14, v15
	v_cvt_pk_bf16_f32 v10, v16, v17
	v_cvt_pk_bf16_f32 v11, v18, v19
	v_lshl_add_u64 v[12:13], v[12:13], 0, v[0:1]
	flat_store_dwordx4 v[12:13], v[8:11]
	s_waitcnt lgkmcnt(0)

; __device__ __forceinline__ void conv_item(const float* W, int K, int N, int kind, int item, const float* gain, unsigned char* Wb, float* scr, int lane) {
;     const int nblk = N / 32, kb = item / nblk, nb = item - kb * nblk, k0 = 64 * kb, n0 = 32 * nb;
;     float wv_[32];
; #pragma unroll
;     for (int i = 0; i < 32; ++i) wv_[i] = W[(size_t)(k0 + 2 * i + (lane >> 5)) * N + n0 + (lane & 31)];
.LBB0_312:
	s_andn2_b64 vcc, exec, s[4:5]
	s_cbranch_vccnz .LBB0_314
	s_lshl_b32 s4, s79, 5
	s_and_b32 s6, s4, 0xfffffc00
	v_readlane_b32 s4, v254, 40
	v_readlane_b32 s5, v254, 41
	s_load_dwordx2 s[4:5], s[4:5], 0x80
	s_lshl_b32 s7, s73, 1
	v_lshlrev_b32_e32 v0, 2, v4
	s_waitcnt lgkmcnt(0)
	s_add_u32 s12, s4, s52
	s_addc_u32 s13, s5, s53
	s_add_i32 s4, s7, 0xac0
	s_and_b32 s92, s4, 0xffffffc0
	s_sub_i32 s4, s75, s6
	s_add_i32 s4, s4, 0xfffa7600
	s_ashr_i32 s5, s4, 31
	s_lshl_b64 s[6:7], s[4:5], 2
	s_add_u32 s6, s12, s6
	v_or_b32_e32 v10, s92, v3
	s_addc_u32 s7, s13, s7
	v_lshl_add_u64 v[8:9], s[6:7], 0, v[0:1]
	v_lshlrev_b32_e32 v0, 10, v10
	v_lshl_add_u64 v[8:9], v[0:1], 2, v[8:9]
	s_movk_i32 s5, 0x2000
	v_add_co_u32_e32 v10, vcc, s5, v8
	s_movk_i32 s5, 0x4000
	s_nop 0
	v_addc_co_u32_e32 v11, vcc, 0, v9, vcc
	global_load_dword v0, v[8:9], off
	global_load_dword v12, v[10:11], off
	v_add_co_u32_e32 v10, vcc, s5, v8
	s_movk_i32 s5, 0x6000
	s_nop 0
	v_addc_co_u32_e32 v11, vcc, 0, v9, vcc
	global_load_dword v13, v[10:11], off
	v_add_co_u32_e32 v10, vcc, s5, v8
	s_mov_b32 s5, 0x8000
	s_nop 0
	v_addc_co_u32_e32 v11, vcc, 0, v9, vcc
	global_load_dword v14, v[10:11], off
	v_add_co_u32_e32 v10, vcc, s5, v8
	s_mov_b32 s5, 0xa000
	s_nop 0
	v_addc_co_u32_e32 v11, vcc, 0, v9, vcc
	global_load_dword v15, v[10:11], off
	v_add_co_u32_e32 v10, vcc, s5, v8
	s_mov_b32 s5, 0xc000
	s_nop 0
	v_addc_co_u32_e32 v11, vcc, 0, v9, vcc
	global_load_dword v16, v[10:11], off
	v_add_co_u32_e32 v10, vcc, s5, v8
	s_mov_b32 s5, 0xe000
	s_nop 0
	v_addc_co_u32_e32 v11, vcc, 0, v9, vcc
	global_load_dword v17, v[10:11], off
	v_add_co_u32_e32 v10, vcc, s5, v8
	s_mov_b32 s5, 0x10000
	s_nop 0
	v_addc_co_u32_e32 v11, vcc, 0, v9, vcc
	global_load_dword v18, v[10:11], off
	v_add_co_u32_e32 v10, vcc, s5, v8
	s_mov_b32 s5, 0x12000
	s_nop 0
	v_addc_co_u32_e32 v11, vcc, 0, v9, vcc
	global_load_dword v19, v[10:11], off
	v_add_co_u32_e32 v10, vcc, s5, v8
	s_mov_b32 s5, 0x14000
	s_nop 0
	v_addc_co_u32_e32 v11, vcc, 0, v9, vcc
	global_load_dword v20, v[10:11], off
	v_add_co_u32_e32 v10, vcc, s5, v8
	s_mov_b32 s5, 0x16000
	s_nop 0
	v_addc_co_u32_e32 v11, vcc, 0, v9, vcc
	global_load_dword v21, v[10:11], off
	v_add_co_u32_e32 v10, vcc, s5, v8
	s_mov_b32 s5, 0x18000
	s_nop 0
	v_addc_co_u32_e32 v11, vcc, 0, v9, vcc
	global_load_dword v22, v[10:11], off
	v_add_co_u32_e32 v10, vcc, s5, v8
	s_mov_b32 s5, 0x1a000
	s_nop 0
	v_addc_co_u32_e32 v11, vcc, 0, v9, vcc
	global_load_dword v23, v[10:11], off
	v_add_co_u32_e32 v10, vcc, s5, v8
	s_mov_b32 s5, 0x1c000
	s_nop 0
	v_addc_co_u32_e32 v11, vcc, 0, v9, vcc
	global_load_dword v24, v[10:11], off
	v_add_co_u32_e32 v10, vcc, s5, v8
	s_mov_b32 s5, 0x1e000
	s_nop 0
	v_addc_co_u32_e32 v11, vcc, 0, v9, vcc
	global_load_dword v25, v[10:11], off
	v_add_co_u32_e32 v10, vcc, s5, v8
	s_mov_b32 s5, 0x20000
	s_nop 0
	v_addc_co_u32_e32 v11, vcc, 0, v9, vcc
	global_load_dword v26, v[10:11], off
	v_add_co_u32_e32 v10, vcc, s5, v8
	s_mov_b32 s5, 0x22000
	s_nop 0
	v_addc_co_u32_e32 v11, vcc, 0, v9, vcc
	global_load_dword v27, v[10:11], off
	v_add_co_u32_e32 v10, vcc, s5, v8
	s_mov_b32 s5, 0x24000
	s_nop 0
	v_addc_co_u32_e32 v11, vcc, 0, v9, vcc
	global_load_dword v28, v[10:11], off
	v_add_co_u32_e32 v10, vcc, s5, v8
	s_mov_b32 s5, 0x26000
	s_nop 0
	v_addc_co_u32_e32 v11, vcc, 0, v9, vcc
	global_load_dword v29, v[10:11], off
	v_add_co_u32_e32 v10, vcc, s5, v8
	s_mov_b32 s5, 0x28000
	s_nop 0
	v_addc_co_u32_e32 v11, vcc, 0, v9, vcc
	global_load_dword v104, v[10:11], off
	v_add_co_u32_e32 v10, vcc, s5, v8
	s_mov_b32 s5, 0x2a000
	s_nop 0
	v_addc_co_u32_e32 v11, vcc, 0, v9, vcc
	global_load_dword v105, v[10:11], off
	v_add_co_u32_e32 v10, vcc, s5, v8
	s_mov_b32 s5, 0x2c000
	s_nop 0
	v_addc_co_u32_e32 v11, vcc, 0, v9, vcc
	global_load_dword v106, v[10:11], off
	v_add_co_u32_e32 v10, vcc, s5, v8
	s_mov_b32 s5, 0x2e000
	s_nop 0
	v_addc_co_u32_e32 v11, vcc, 0, v9, vcc
	global_load_dword v107, v[10:11], off
	v_add_co_u32_e32 v10, vcc, s5, v8
	s_mov_b32 s5, 0x30000
	s_nop 0
	v_addc_co_u32_e32 v11, vcc, 0, v9, vcc
	global_load_dword v108, v[10:11], off
	v_add_co_u32_e32 v10, vcc, s5, v8
	s_mov_b32 s5, 0x32000
	s_nop 0
	v_addc_co_u32_e32 v11, vcc, 0, v9, vcc
	global_load_dword v109, v[10:11], off
	v_add_co_u32_e32 v10, vcc, s5, v8
	s_mov_b32 s5, 0x34000
	s_nop 0
	v_addc_co_u32_e32 v11, vcc, 0, v9, vcc
	global_load_dword v110, v[10:11], off
	v_add_co_u32_e32 v10, vcc, s5, v8
	s_mov_b32 s5, 0x36000
	s_nop 0
	v_addc_co_u32_e32 v11, vcc, 0, v9, vcc
	global_load_dword v111, v[10:11], off
	v_add_co_u32_e32 v10, vcc, s5, v8
	s_mov_b32 s5, 0x38000
	s_nop 0
	v_addc_co_u32_e32 v11, vcc, 0, v9, vcc
	global_load_dword v112, v[10:11], off
	v_add_co_u32_e32 v10, vcc, s5, v8
	s_mov_b32 s5, 0x3a000
	s_nop 0
	v_addc_co_u32_e32 v11, vcc, 0, v9, vcc
	global_load_dword v113, v[10:11], off
	v_add_co_u32_e32 v10, vcc, s5, v8
	s_mov_b32 s5, 0x3c000
	s_nop 0
	v_addc_co_u32_e32 v11, vcc, 0, v9, vcc
	global_load_dword v114, v[10:11], off
	v_add_co_u32_e32 v10, vcc, s5, v8
	s_mov_b32 s5, 0x3e000
	s_nop 0
	v_addc_co_u32_e32 v11, vcc, 0, v9, vcc
	v_add_co_u32_e32 v8, vcc, s5, v8
	global_load_dword v10, v[10:11], off
	s_nop 0
	v_addc_co_u32_e32 v9, vcc, 0, v9, vcc
	global_load_dword v8, v[8:9], off
	s_waitcnt vmcnt(0)
; __device__ __forceinline__ unsigned pk2(float lo, float hi) { f32x2_t v = {lo, hi}; bf16x2_t b = __builtin_convertvector(v, bf16x2_t); return __builtin_bit_cast(unsigned, b); }
; __device__ __forceinline__ bf16_t* wdst(int kind, int n, unsigned char* Wb) {
;     ...
;     default: return (bf16_t*)(Wb + O_WO) + (size_t)n * 1024;
; __device__ __forceinline__ void conv_item(const float* W, int K, int N, int kind, int item, const float* gain, unsigned char* Wb, float* scr, int lane) {
;     ...
;     for (int i = 0; i < 32; ++i) scr[(2 * i + (lane >> 5)) * 33 + (lane & 31)] = wv_[i];
;     __builtin_amdgcn_s_waitcnt(0); asm volatile("" ::: "memory");
;     const int c = lane & 7; float gg[8];
; #pragma unroll
;     for (int e = 0; e < 8; ++e) gg[e] = gain ? gain[k0 + 8 * c + e] : 1.0f;
; #pragma unroll
;     for (int j = 0; j < 4; ++j) { const int n = (lane >> 3) + 8 * j; const float* s = scr + (8 * c) * 33 + n;
;         u32x4 o; o.x = pk2(s[0] * gg[0], s[33] * gg[1]); o.y = pk2(s[2 * 33] * gg[2], s[3 * 33] * gg[3]); o.z = pk2(s[4 * 33] * gg[4], s[5 * 33] * gg[5]); o.w = pk2(s[6 * 33] * gg[6], s[7 * 33] * gg[7]);
;         *(u32x4*)(wdst(kind, n0 + n, Wb) + k0 + 8 * c) = o; }
;     __builtin_amdgcn_s_waitcnt(0); asm volatile("" ::: "memory");
	ds_write2_b32 v5, v0, v12 offset1:66
	ds_write2_b32 v5, v13, v14 offset0:132 offset1:198
	v_add_u32_e32 v0, 0x400, v5
	ds_write2_b32 v0, v15, v16 offset0:8 offset1:74
	ds_write2_b32 v0, v17, v18 offset0:140 offset1:206
	v_add_u32_e32 v0, 0x800, v5
	ds_write2_b32 v0, v19, v20 offset0:16 offset1:82
	ds_write2_b32 v0, v21, v22 offset0:148 offset1:214
	v_add_u32_e32 v0, 0xc00, v5
	ds_write2_b32 v0, v23, v24 offset0:24 offset1:90
	ds_write2_b32 v0, v25, v26 offset0:156 offset1:222
	v_add_u32_e32 v0, 0x1000, v5
	ds_write2_b32 v0, v27, v28 offset0:32 offset1:98
	ds_write2_b32 v0, v29, v104 offset0:164 offset1:230
	v_add_u32_e32 v0, 0x1400, v5
	ds_write2_b32 v0, v105, v106 offset0:40 offset1:106
	ds_write2_b32 v0, v107, v108 offset0:172 offset1:238
	v_add_u32_e32 v0, 0x1800, v5
	ds_write2_b32 v0, v109, v110 offset0:48 offset1:114
	ds_write2_b32 v0, v111, v112 offset0:180 offset1:246
	v_add_u32_e32 v0, 0x1c00, v5
	ds_write2_b32 v0, v113, v114 offset0:56 offset1:122
	ds_write2_b32 v0, v10, v8 offset0:188 offset1:254
	s_waitcnt vmcnt(0) expcnt(0) lgkmcnt(0)
	ds_read_b32 v0, v30
	ds_read_b32 v8, v30 offset:132
	s_lshl_b64 s[6:7], s[92:93], 1
	s_waitcnt lgkmcnt(0)
	v_cvt_pk_bf16_f32 v8, v0, v8
	ds_read_b32 v0, v30 offset:264
	ds_read_b32 v9, v30 offset:396
	s_waitcnt lgkmcnt(0)
	v_cvt_pk_bf16_f32 v9, v0, v9
	ds_read_b32 v0, v30 offset:528
	ds_read_b32 v10, v30 offset:660
	s_waitcnt lgkmcnt(0)
	v_cvt_pk_bf16_f32 v10, v0, v10
	ds_read_b32 v0, v30 offset:792
	ds_read_b32 v11, v30 offset:924
	s_waitcnt lgkmcnt(0)
	v_cvt_pk_bf16_f32 v11, v0, v11
	v_add_u32_e32 v0, s4, v61
	v_add_u32_e32 v12, 0x58a00, v0
	v_ashrrev_i32_e32 v13, 31, v12
	v_lshlrev_b64 v[12:13], 11, v[12:13]
	v_lshl_add_u64 v[12:13], s[54:55], 0, v[12:13]
	v_lshl_add_u64 v[12:13], v[12:13], 0, s[6:7]
	v_lshlrev_b32_e32 v0, 1, v6
	v_lshl_add_u64 v[12:13], v[12:13], 0, v[0:1]
	flat_store_dwordx4 v[12:13], v[8:11]
	ds_read_b32 v8, v30 offset:32
	ds_read_b32 v9, v30 offset:164
	s_waitcnt lgkmcnt(0)
	v_cvt_pk_bf16_f32 v8, v8, v9
	ds_read_b32 v9, v30 offset:296
	ds_read_b32 v10, v30 offset:428
	s_waitcnt lgkmcnt(0)
	v_cvt_pk_bf16_f32 v9, v9, v10
	ds_read_b32 v10, v30 offset:560
	ds_read_b32 v11, v30 offset:692
	s_waitcnt lgkmcnt(0)
	v_cvt_pk_bf16_f32 v10, v10, v11
	ds_read_b32 v11, v30 offset:824
	ds_read_b32 v12, v30 offset:956
	s_waitcnt lgkmcnt(0)
	v_cvt_pk_bf16_f32 v11, v11, v12
	v_add_u32_e32 v12, s4, v62
	v_add_u32_e32 v12, 0x58a00, v12
	v_ashrrev_i32_e32 v13, 31, v12
	v_lshlrev_b64 v[12:13], 11, v[12:13]
	v_lshl_add_u64 v[12:13], s[54:55], 0, v[12:13]
	v_lshl_add_u64 v[12:13], v[12:13], 0, s[6:7]
	v_lshl_add_u64 v[12:13], v[12:13], 0, v[0:1]
	flat_store_dwordx4 v[12:13], v[8:11]
	ds_read_b32 v8, v30 offset:64
	ds_read_b32 v9, v30 offset:196
	s_waitcnt lgkmcnt(0)
	v_cvt_pk_bf16_f32 v8, v8, v9
	ds_read_b32 v9, v30 offset:328
	ds_read_b32 v10, v30 offset:460
	s_waitcnt lgkmcnt(0)
	v_cvt_pk_bf16_f32 v9, v9, v10
	ds_read_b32 v10, v30 offset:592
	ds_read_b32 v11, v30 offset:724
	s_waitcnt lgkmcnt(0)
	v_cvt_pk_bf16_f32 v10, v10, v11
	ds_read_b32 v11, v30 offset:856
	ds_read_b32 v12, v30 offset:988
	s_waitcnt lgkmcnt(0)
	v_cvt_pk_bf16_f32 v11, v11, v12
	v_add_u32_e32 v12, s4, v63
	v_add_u32_e32 v12, 0x58a00, v12
	v_ashrrev_i32_e32 v13, 31, v12
	v_lshlrev_b64 v[12:13], 11, v[12:13]
	v_lshl_add_u64 v[12:13], s[54:55], 0, v[12:13]
	v_lshl_add_u64 v[12:13], v[12:13], 0, s[6:7]
	v_lshl_add_u64 v[12:13], v[12:13], 0, v[0:1]
	flat_store_dwordx4 v[12:13], v[8:11]
	ds_read_b32 v10, v30 offset:96
	ds_read_b32 v11, v30 offset:228
	ds_read_b32 v14, v30 offset:360
	ds_read_b32 v15, v30 offset:492
	ds_read_b32 v16, v30 offset:624
	ds_read_b32 v17, v30 offset:756
	ds_read_b32 v18, v30 offset:888
	ds_read_b32 v19, v30 offset:1020
	v_add_u32_e32 v8, s4, v64
	v_add_u32_e32 v8, 0x58a00, v8
	v_ashrrev_i32_e32 v9, 31, v8
	v_lshlrev_b64 v[8:9], 11, v[8:9]
	v_lshl_add_u64 v[12:13], s[54:55], 0, v[8:9]
	v_lshl_add_u64 v[12:13], v[12:13], 0, s[6:7]
	s_waitcnt lgkmcnt(0)
	v_cvt_pk_bf16_f32 v8, v10, v11
	v_cvt_pk_bf16_f32 v9, v14, v15
	v_cvt_pk_bf16_f32 v10, v16, v17
	v_cvt_pk_bf16_f32 v11, v18, v19
	v_lshl_add_u64 v[12:13], v[12:13], 0, v[0:1]
	flat_store_dwordx4 v[12:13], v[8:11]
	s_waitcnt lgkmcnt(0)

; __device__ __forceinline__ void conv_item(const float* W, int K, int N, int kind, int item, const float* gain, unsigned char* Wb, float* scr, int lane) {
;     const int nblk = N / 32, kb = item / nblk, nb = item - kb * nblk, k0 = 64 * kb, n0 = 32 * nb;
;     float wv_[32];
; #pragma unroll
;     for (int i = 0; i < 32; ++i) wv_[i] = W[(size_t)(k0 + 2 * i + (lane >> 5)) * N + n0 + (lane & 31)];
.LBB0_315:
	s_andn2_b64 vcc, exec, s[4:5]
	s_cbranch_vccnz .LBB0_317
	s_lshl_b32 s4, s80, 5
	s_and_b32 s6, s4, 0xfffffc00
	v_readlane_b32 s4, v254, 40
	v_readlane_b32 s5, v254, 41
	s_load_dwordx2 s[4:5], s[4:5], 0x20
	s_lshl_b32 s7, s73, 1
	v_lshlrev_b32_e32 v0, 2, v4
	s_waitcnt lgkmcnt(0)
	s_add_u32 s12, s4, s3
	s_addc_u32 s13, s5, s67
	s_add_i32 s4, s7, 0x20c0
	s_and_b32 s92, s4, 0xffffffc0
	s_sub_i32 s4, s75, s6
	s_add_i32 s4, s4, 0xfffbd600
	s_ashr_i32 s5, s4, 31
	s_lshl_b64 s[6:7], s[4:5], 2
	s_add_u32 s6, s12, s6
	v_or_b32_e32 v10, s92, v3
	s_addc_u32 s7, s13, s7
	v_lshl_add_u64 v[8:9], s[6:7], 0, v[0:1]
	v_lshlrev_b32_e32 v0, 10, v10
	v_lshl_add_u64 v[8:9], v[0:1], 2, v[8:9]
	s_movk_i32 s5, 0x2000
	v_add_co_u32_e32 v10, vcc, s5, v8
	s_movk_i32 s5, 0x4000
	s_nop 0
	v_addc_co_u32_e32 v11, vcc, 0, v9, vcc
	global_load_dword v0, v[8:9], off
	global_load_dword v12, v[10:11], off
	v_add_co_u32_e32 v10, vcc, s5, v8
	s_movk_i32 s5, 0x6000
	s_nop 0
	v_addc_co_u32_e32 v11, vcc, 0, v9, vcc
	global_load_dword v13, v[10:11], off
	v_add_co_u32_e32 v10, vcc, s5, v8
	s_mov_b32 s5, 0x8000
	s_nop 0
	v_addc_co_u32_e32 v11, vcc, 0, v9, vcc
	global_load_dword v14, v[10:11], off
	v_add_co_u32_e32 v10, vcc, s5, v8
	s_mov_b32 s5, 0xa000
	s_nop 0
	v_addc_co_u32_e32 v11, vcc, 0, v9, vcc
	global_load_dword v15, v[10:11], off
	v_add_co_u32_e32 v10, vcc, s5, v8
	s_mov_b32 s5, 0xc000
	s_nop 0
	v_addc_co_u32_e32 v11, vcc, 0, v9, vcc
	global_load_dword v16, v[10:11], off
	v_add_co_u32_e32 v10, vcc, s5, v8
	s_mov_b32 s5, 0xe000
	s_nop 0
	v_addc_co_u32_e32 v11, vcc, 0, v9, vcc
	global_load_dword v17, v[10:11], off
	v_add_co_u32_e32 v10, vcc, s5, v8
	s_mov_b32 s5, 0x10000
	s_nop 0
	v_addc_co_u32_e32 v11, vcc, 0, v9, vcc
	global_load_dword v18, v[10:11], off
	v_add_co_u32_e32 v10, vcc, s5, v8
	s_mov_b32 s5, 0x12000
	s_nop 0
	v_addc_co_u32_e32 v11, vcc, 0, v9, vcc
	global_load_dword v19, v[10:11], off
	v_add_co_u32_e32 v10, vcc, s5, v8
	s_mov_b32 s5, 0x14000
	s_nop 0
	v_addc_co_u32_e32 v11, vcc, 0, v9, vcc
	global_load_dword v20, v[10:11], off
	v_add_co_u32_e32 v10, vcc, s5, v8
	s_mov_b32 s5, 0x16000
	s_nop 0
	v_addc_co_u32_e32 v11, vcc, 0, v9, vcc
	global_load_dword v21, v[10:11], off
	v_add_co_u32_e32 v10, vcc, s5, v8
	s_mov_b32 s5, 0x18000
	s_nop 0
	v_addc_co_u32_e32 v11, vcc, 0, v9, vcc
	global_load_dword v22, v[10:11], off
	v_add_co_u32_e32 v10, vcc, s5, v8
	s_mov_b32 s5, 0x1a000
	s_nop 0
	v_addc_co_u32_e32 v11, vcc, 0, v9, vcc
	global_load_dword v23, v[10:11], off
	v_add_co_u32_e32 v10, vcc, s5, v8
	s_mov_b32 s5, 0x1c000
	s_nop 0
	v_addc_co_u32_e32 v11, vcc, 0, v9, vcc
	global_load_dword v24, v[10:11], off
	v_add_co_u32_e32 v10, vcc, s5, v8
	s_mov_b32 s5, 0x1e000
	s_nop 0
	v_addc_co_u32_e32 v11, vcc, 0, v9, vcc
	global_load_dword v25, v[10:11], off
	v_add_co_u32_e32 v10, vcc, s5, v8
	s_mov_b32 s5, 0x20000
	s_nop 0
	v_addc_co_u32_e32 v11, vcc, 0, v9, vcc
	global_load_dword v26, v[10:11], off
	v_add_co_u32_e32 v10, vcc, s5, v8
	s_mov_b32 s5, 0x22000
	s_nop 0
	v_addc_co_u32_e32 v11, vcc, 0, v9, vcc
	global_load_dword v27, v[10:11], off
	v_add_co_u32_e32 v10, vcc, s5, v8
	s_mov_b32 s5, 0x24000
	s_nop 0
	v_addc_co_u32_e32 v11, vcc, 0, v9, vcc
	global_load_dword v28, v[10:11], off
	v_add_co_u32_e32 v10, vcc, s5, v8
	s_mov_b32 s5, 0x26000
	s_nop 0
	v_addc_co_u32_e32 v11, vcc, 0, v9, vcc
	global_load_dword v29, v[10:11], off
	v_add_co_u32_e32 v10, vcc, s5, v8
	s_mov_b32 s5, 0x28000
	s_nop 0
	v_addc_co_u32_e32 v11, vcc, 0, v9, vcc
	global_load_dword v104, v[10:11], off
	v_add_co_u32_e32 v10, vcc, s5, v8
	s_mov_b32 s5, 0x2a000
	s_nop 0
	v_addc_co_u32_e32 v11, vcc, 0, v9, vcc
	global_load_dword v105, v[10:11], off
	v_add_co_u32_e32 v10, vcc, s5, v8
	s_mov_b32 s5, 0x2c000
	s_nop 0
	v_addc_co_u32_e32 v11, vcc, 0, v9, vcc
	global_load_dword v106, v[10:11], off
	v_add_co_u32_e32 v10, vcc, s5, v8
	s_mov_b32 s5, 0x2e000
	s_nop 0
	v_addc_co_u32_e32 v11, vcc, 0, v9, vcc
	global_load_dword v107, v[10:11], off
	v_add_co_u32_e32 v10, vcc, s5, v8
	s_mov_b32 s5, 0x30000
	s_nop 0
	v_addc_co_u32_e32 v11, vcc, 0, v9, vcc
	global_load_dword v108, v[10:11], off
	v_add_co_u32_e32 v10, vcc, s5, v8
	s_mov_b32 s5, 0x32000
	s_nop 0
	v_addc_co_u32_e32 v11, vcc, 0, v9, vcc
	global_load_dword v109, v[10:11], off
	v_add_co_u32_e32 v10, vcc, s5, v8
	s_mov_b32 s5, 0x34000
	s_nop 0
	v_addc_co_u32_e32 v11, vcc, 0, v9, vcc
	global_load_dword v110, v[10:11], off
	v_add_co_u32_e32 v10, vcc, s5, v8
	s_mov_b32 s5, 0x36000
	s_nop 0
	v_addc_co_u32_e32 v11, vcc, 0, v9, vcc
	global_load_dword v111, v[10:11], off
	v_add_co_u32_e32 v10, vcc, s5, v8
	s_mov_b32 s5, 0x38000
	s_nop 0
	v_addc_co_u32_e32 v11, vcc, 0, v9, vcc
	global_load_dword v112, v[10:11], off
	v_add_co_u32_e32 v10, vcc, s5, v8
	s_mov_b32 s5, 0x3a000
	s_nop 0
	v_addc_co_u32_e32 v11, vcc, 0, v9, vcc
	global_load_dword v113, v[10:11], off
	v_add_co_u32_e32 v10, vcc, s5, v8
	s_mov_b32 s5, 0x3c000
	s_nop 0
	v_addc_co_u32_e32 v11, vcc, 0, v9, vcc
	global_load_dword v114, v[10:11], off
	v_add_co_u32_e32 v10, vcc, s5, v8
	s_mov_b32 s5, 0x3e000
	s_nop 0
	v_addc_co_u32_e32 v11, vcc, 0, v9, vcc
	v_add_co_u32_e32 v8, vcc, s5, v8
	global_load_dword v10, v[10:11], off
	s_nop 0
	v_addc_co_u32_e32 v9, vcc, 0, v9, vcc
	global_load_dword v8, v[8:9], off
	s_waitcnt vmcnt(0)
; __device__ __forceinline__ unsigned pk2(float lo, float hi) { f32x2_t v = {lo, hi}; bf16x2_t b = __builtin_convertvector(v, bf16x2_t); return __builtin_bit_cast(unsigned, b); }
; __device__ __forceinline__ bf16_t* wdst(int kind, int n, unsigned char* Wb) {
;     ...
;     case 1: case 3: return (bf16_t*)(Wb + (kind == 1 ? O_DN1 : O_DN2)) + (size_t)n * FF;
; __device__ __forceinline__ void conv_item(const float* W, int K, int N, int kind, int item, const float* gain, unsigned char* Wb, float* scr, int lane) {
;     ...
;     for (int i = 0; i < 32; ++i) scr[(2 * i + (lane >> 5)) * 33 + (lane & 31)] = wv_[i];
;     __builtin_amdgcn_s_waitcnt(0); asm volatile("" ::: "memory");
;     const int c = lane & 7; float gg[8];
; #pragma unroll
;     for (int e = 0; e < 8; ++e) gg[e] = gain ? gain[k0 + 8 * c + e] : 1.0f;
; #pragma unroll
;     for (int j = 0; j < 4; ++j) { const int n = (lane >> 3) + 8 * j; const float* s = scr + (8 * c) * 33 + n;
;         u32x4 o; o.x = pk2(s[0] * gg[0], s[33] * gg[1]); o.y = pk2(s[2 * 33] * gg[2], s[3 * 33] * gg[3]); o.z = pk2(s[4 * 33] * gg[4], s[5 * 33] * gg[5]); o.w = pk2(s[6 * 33] * gg[6], s[7 * 33] * gg[7]);
;         *(u32x4*)(wdst(kind, n0 + n, Wb) + k0 + 8 * c) = o; }
;     __builtin_amdgcn_s_waitcnt(0); asm volatile("" ::: "memory");
	ds_write2_b32 v5, v0, v12 offset1:66
	ds_write2_b32 v5, v13, v14 offset0:132 offset1:198
	v_add_u32_e32 v0, 0x400, v5
	ds_write2_b32 v0, v15, v16 offset0:8 offset1:74
	ds_write2_b32 v0, v17, v18 offset0:140 offset1:206
	v_add_u32_e32 v0, 0x800, v5
	ds_write2_b32 v0, v19, v20 offset0:16 offset1:82
	ds_write2_b32 v0, v21, v22 offset0:148 offset1:214
	v_add_u32_e32 v0, 0xc00, v5
	ds_write2_b32 v0, v23, v24 offset0:24 offset1:90
	ds_write2_b32 v0, v25, v26 offset0:156 offset1:222
	v_add_u32_e32 v0, 0x1000, v5
	ds_write2_b32 v0, v27, v28 offset0:32 offset1:98
	ds_write2_b32 v0, v29, v104 offset0:164 offset1:230
	v_add_u32_e32 v0, 0x1400, v5
	ds_write2_b32 v0, v105, v106 offset0:40 offset1:106
	ds_write2_b32 v0, v107, v108 offset0:172 offset1:238
	v_add_u32_e32 v0, 0x1800, v5
	ds_write2_b32 v0, v109, v110 offset0:48 offset1:114
	ds_write2_b32 v0, v111, v112 offset0:180 offset1:246
	v_add_u32_e32 v0, 0x1c00, v5
	ds_write2_b32 v0, v113, v114 offset0:56 offset1:122
	ds_write2_b32 v0, v10, v8 offset0:188 offset1:254
	s_waitcnt vmcnt(0) expcnt(0) lgkmcnt(0)
	ds_read_b32 v0, v30
	ds_read_b32 v8, v30 offset:132
	v_mov_b64_e32 v[12:13], s[56:57]
	s_movk_i32 s5, 0x1600
	v_add_u32_e32 v18, s4, v68
	v_add_u32_e32 v18, 0x42a00, v18
	s_waitcnt lgkmcnt(0)
	v_cvt_pk_bf16_f32 v8, v0, v8
	ds_read_b32 v0, v30 offset:264
	ds_read_b32 v9, v30 offset:396
	s_waitcnt lgkmcnt(0)
	v_cvt_pk_bf16_f32 v9, v0, v9
	ds_read_b32 v0, v30 offset:528
	ds_read_b32 v10, v30 offset:660
	s_waitcnt lgkmcnt(0)
	v_cvt_pk_bf16_f32 v10, v0, v10
	ds_read_b32 v0, v30 offset:792
	ds_read_b32 v11, v30 offset:924
	s_waitcnt lgkmcnt(0)
	v_cvt_pk_bf16_f32 v11, v0, v11
	v_add_u32_e32 v0, s4, v65
	v_add_u32_e32 v0, 0x42a00, v0
	v_mad_i64_i32 v[14:15], s[6:7], v0, s5, v[12:13]
	s_lshl_b64 s[6:7], s[92:93], 1
	s_nop 0
	v_lshl_add_u64 v[14:15], v[14:15], 0, s[6:7]
	v_lshlrev_b32_e32 v0, 1, v6
	v_lshl_add_u64 v[14:15], v[14:15], 0, v[0:1]
	flat_store_dwordx4 v[14:15], v[8:11]
	ds_read_b32 v8, v30 offset:32
	ds_read_b32 v9, v30 offset:164
	s_waitcnt lgkmcnt(0)
	v_cvt_pk_bf16_f32 v8, v8, v9
	ds_read_b32 v9, v30 offset:296
	ds_read_b32 v10, v30 offset:428
	s_waitcnt lgkmcnt(0)
	v_cvt_pk_bf16_f32 v9, v9, v10
	ds_read_b32 v10, v30 offset:560
	ds_read_b32 v11, v30 offset:692
	s_waitcnt lgkmcnt(0)
	v_cvt_pk_bf16_f32 v10, v10, v11
	ds_read_b32 v11, v30 offset:824
	ds_read_b32 v14, v30 offset:956
	s_waitcnt lgkmcnt(0)
	v_cvt_pk_bf16_f32 v11, v11, v14
	v_add_u32_e32 v14, s4, v66
	v_add_u32_e32 v14, 0x42a00, v14
	v_mad_i64_i32 v[14:15], s[12:13], v14, s5, v[12:13]
	v_lshl_add_u64 v[14:15], v[14:15], 0, s[6:7]
	v_lshl_add_u64 v[14:15], v[14:15], 0, v[0:1]
	flat_store_dwordx4 v[14:15], v[8:11]
	ds_read_b32 v8, v30 offset:64
	ds_read_b32 v9, v30 offset:196
	s_waitcnt lgkmcnt(0)
	v_cvt_pk_bf16_f32 v8, v8, v9
	ds_read_b32 v9, v30 offset:328
	ds_read_b32 v10, v30 offset:460
	s_waitcnt lgkmcnt(0)
	v_cvt_pk_bf16_f32 v9, v9, v10
	ds_read_b32 v10, v30 offset:592
	ds_read_b32 v11, v30 offset:724
	s_waitcnt lgkmcnt(0)
	v_cvt_pk_bf16_f32 v10, v10, v11
	ds_read_b32 v11, v30 offset:856
	ds_read_b32 v14, v30 offset:988
	s_waitcnt lgkmcnt(0)
	v_cvt_pk_bf16_f32 v11, v11, v14
	v_add_u32_e32 v14, s4, v67
	v_add_u32_e32 v14, 0x42a00, v14
	v_mad_i64_i32 v[14:15], s[12:13], v14, s5, v[12:13]
	v_lshl_add_u64 v[14:15], v[14:15], 0, s[6:7]
	v_lshl_add_u64 v[14:15], v[14:15], 0, v[0:1]
	flat_store_dwordx4 v[14:15], v[8:11]
	ds_read_b32 v8, v30 offset:96
	ds_read_b32 v9, v30 offset:228
	ds_read_b32 v10, v30 offset:360
	ds_read_b32 v11, v30 offset:492
	ds_read_b32 v14, v30 offset:624
	ds_read_b32 v15, v30 offset:756
	ds_read_b32 v16, v30 offset:888
	ds_read_b32 v17, v30 offset:1020
	v_mad_i64_i32 v[12:13], s[4:5], v18, s5, v[12:13]
	v_lshl_add_u64 v[12:13], v[12:13], 0, s[6:7]
	s_waitcnt lgkmcnt(0)
	v_cvt_pk_bf16_f32 v8, v8, v9
	v_cvt_pk_bf16_f32 v9, v10, v11
	v_cvt_pk_bf16_f32 v10, v14, v15
	v_cvt_pk_bf16_f32 v11, v16, v17
	v_lshl_add_u64 v[12:13], v[12:13], 0, v[0:1]
	flat_store_dwordx4 v[12:13], v[8:11]
	s_waitcnt lgkmcnt(0)

; __device__ __forceinline__ unsigned pk2(float lo, float hi) { f32x2_t v = {lo, hi}; bf16x2_t b = __builtin_convertvector(v, bf16x2_t); return __builtin_bit_cast(unsigned, b); }
; __device__ __forceinline__ void conv_item(const float* W, int K, int N, int kind, int item, const float* gain, unsigned char* Wb, float* scr, int lane) {
;     ...
;     for (int j = 0; j < 4; ++j) { const int n = (lane >> 3) + 8 * j; const float* s = scr + (8 * c) * 33 + n;
;         u32x4 o; o.x = pk2(s[0] * gg[0], s[33] * gg[1]); o.y = pk2(s[2 * 33] * gg[2], s[3 * 33] * gg[3]); o.z = pk2(s[4 * 33] * gg[4], s[5 * 33] * gg[5]); o.w = pk2(s[6 * 33] * gg[6], s[7 * 33] * gg[7]);
;         *(u32x4*)(wdst(kind, n0 + n, Wb) + k0 + 8 * c) = o; }
;     __builtin_amdgcn_s_waitcnt(0); asm volatile("" ::: "memory");
.LBB0_454:
	s_or_b64 exec, exec, s[4:5]
	v_mov_b64_e32 v[28:29], s[16:17]
	s_and_saveexec_b64 s[4:5], s[20:21]
	v_ashrrev_i32_e32 v27, 31, v26
	v_mov_b64_e32 v[28:29], s[60:61]
	v_mov_b64_e32 v[24:25], v[26:27]
	s_or_b64 exec, exec, s[4:5]
	v_lshlrev_b64 v[24:25], 11, v[24:25]
	s_waitcnt lgkmcnt(0)
	v_pk_mul_f32 v[8:9], v[8:9], v[22:23]
	v_pk_mul_f32 v[10:11], v[10:11], v[20:21]
	v_lshl_add_u64 v[24:25], v[28:29], 0, v[24:25]
	v_cvt_pk_bf16_f32 v8, v8, v9
	v_cvt_pk_bf16_f32 v9, v10, v11
	v_pk_mul_f32 v[10:11], v[12:13], v[18:19]
	v_pk_mul_f32 v[12:13], v[14:15], v[16:17]
	v_cvt_pk_bf16_f32 v10, v10, v11
	v_cvt_pk_bf16_f32 v11, v12, v13
	v_lshl_add_u64 v[12:13], v[24:25], 0, s[92:93]
	v_lshl_add_u64 v[12:13], v[12:13], 0, v[0:1]
	flat_store_dwordx4 v[12:13], v[8:11]
	s_waitcnt lgkmcnt(0)

; __device__ __forceinline__ u32x4 pack8(f32x4 a, f32x4 b) { u32x4 w; w.x = pk2(a[0], a[1]); w.y = pk2(a[2], a[3]); w.z = pk2(b[0], b[1]); w.w = pk2(b[2], b[3]); return w; }
; __device__ __forceinline__ void unpack8(u32x4 w, f32x4& a, f32x4& b) { a = (f32x4){bflo(w.x), bfhi(w.x), bflo(w.y), bfhi(w.y)}; b = (f32x4){bflo(w.z), bfhi(w.z), bflo(w.w), bfhi(w.w)}; }
;     __device__ __forceinline__ void operator()(const Acc& acc, const Unit& u, int wr, int wc, int fr, int fq, const RsCtx& rc) const {
;     ...
;             for (int m = 0; m < 4; ++m) { const int row = EPI_ROW(u, ai, wr, m, fr); float s = 0.f;
; #pragma unroll
;                 for (int bj = 0; bj < 2; ++bj) { const size_t off = (size_t)row * DM + u.pn * 256 + bj * 128 + wc * 32 + 8 * fq;
;                     f32x4 x0, x1; unpack8(*(const u32x4*)(XB + off), x0, x1);
;                     x0 = x0 + acc[ai][bj][m][0] * alpha; x1 = x1 + acc[ai][bj][m][1] * alpha;
;                     *(u32x4*)(XB + off) = pack8(x0, x1);
; #pragma unroll
;                     for (int e = 0; e < 4; ++e) s += x0[e] * x0[e] + x1[e] * x1[e]; }
;                 s += __shfl_xor(s, 16); s += __shfl_xor(s, 32);
;                 if (fq == 0) ssq_x[(size_t)row * 16 + u.pn * 4 + wc] = s;
.LBB0_1104:
	v_and_b32_e32 v149, 64, v217
	v_xor_b32_e32 v0, 16, v217
	v_add_u32_e32 v149, 64, v149
	v_cmp_lt_i32_e32 vcc, v0, v149
	v_lshl_add_u32 v148, s37, 8, v141
	s_lshl_b32 s50, s36, 8
	v_cndmask_b32_e32 v0, v217, v0, vcc
	v_lshlrev_b32_e32 v155, 2, v0
	v_xor_b32_e32 v0, 32, v217
	v_cmp_lt_i32_e32 vcc, v0, v149
	s_lshl_b32 s48, s36, 2
	v_ashrrev_i32_e32 v149, 31, v148
	v_readlane_b32 s36, v254, 44
	v_lshlrev_b64 v[150:151], 11, v[148:149]
	v_readlane_b32 s37, v254, 45
	s_ashr_i32 s51, s50, 31
	v_cndmask_b32_e32 v0, v217, v0, vcc
	v_lshl_add_u64 v[150:151], s[36:37], 0, v[150:151]
	v_lshl_add_u64 v[150:151], s[50:51], 1, v[150:151]
	s_lshl_b32 s92, s55, 1
	v_lshlrev_b32_e32 v154, 2, v0
	v_lshl_add_u64 v[150:151], v[150:151], 0, s[92:93]
	v_lshlrev_b32_e32 v0, 1, v140
	v_lshl_add_u64 v[150:151], v[150:151], 0, v[0:1]
	v_lshl_add_u32 v210, v148, 11, v0
	s_lshl_b64 s[28:29], s[50:51], 1
	s_add_u32 s28, s28, s36
	s_addc_u32 s29, s29, s37
	s_add_u32 s28, s28, s92
	s_addc_u32 s29, s29, s93
	global_load_dwordx4 v[156:159], v210, s[28:29]
	global_load_dwordx4 v[164:167], v210, s[28:29] offset:256
	s_add_u32 s28, s28, 0x8000
	s_addc_u32 s29, s29, 0
	global_load_dwordx4 v[168:171], v210, s[28:29]
	global_load_dwordx4 v[172:175], v210, s[28:29] offset:256
	s_add_u32 s28, s28, 0x8000
	s_addc_u32 s29, s29, 0
	global_load_dwordx4 v[176:179], v210, s[28:29]
	global_load_dwordx4 v[180:183], v210, s[28:29] offset:256
	s_add_u32 s28, s28, 0x8000
	s_addc_u32 s29, s29, 0
	global_load_dwordx4 v[184:187], v210, s[28:29]
	global_load_dwordx4 v[188:191], v210, s[28:29] offset:256
	s_add_u32 s28, s28, 0x28000
	s_addc_u32 s29, s29, 0
	global_load_dwordx4 v[192:195], v210, s[28:29]
	global_load_dwordx4 v[206:209], v210, s[28:29] offset:256
	s_add_u32 s28, s28, 0x8000
	s_addc_u32 s29, s29, 0
	global_load_dwordx4 v[218:221], v210, s[28:29]
	global_load_dwordx4 v[232:235], v210, s[28:29] offset:256
	s_add_u32 s28, s28, 0x8000
	s_addc_u32 s29, s29, 0
	global_load_dwordx4 v[236:239], v210, s[28:29]
	global_load_dwordx4 v[240:243], v210, s[28:29] offset:256
	s_add_u32 s28, s28, 0x8000
	s_addc_u32 s29, s29, 0
	global_load_dwordx4 v[244:247], v210, s[28:29]
	global_load_dwordx4 v[248:251], v210, s[28:29] offset:256
	s_ashr_i32 s49, s48, 31
	s_waitcnt vmcnt(0) lgkmcnt(0)
	v_lshlrev_b32_e32 v160, 16, v156
	v_and_b32_e32 v161, 0xffff0000, v156
	v_lshlrev_b32_e32 v156, 16, v157
	v_and_b32_e32 v157, 0xffff0000, v157
	v_lshlrev_b32_e32 v162, 16, v158
	v_and_b32_e32 v163, 0xffff0000, v158
	v_lshlrev_b32_e32 v158, 16, v159
	v_and_b32_e32 v159, 0xffff0000, v159
	v_pk_fma_f32 v[156:157], v[142:143], v[124:125], v[156:157]
	v_pk_fma_f32 v[160:161], v[130:131], v[122:123], v[160:161]
	v_pk_fma_f32 v[128:129], v[142:143], v[128:129], v[158:159]
	v_pk_fma_f32 v[126:127], v[130:131], v[126:127], v[162:163]
	v_cvt_pk_bf16_f32 v122, v160, v161
	v_cvt_pk_bf16_f32 v123, v156, v157
	v_cvt_pk_bf16_f32 v124, v126, v127
	v_cvt_pk_bf16_f32 v125, v128, v129
	flat_store_dwordx4 v[150:151], v[122:125]
	s_nop 1
	v_mul_f32_e32 v122, v126, v126
	v_mul_f32_e32 v123, v127, v127
	v_fmac_f32_e32 v122, v160, v160
	v_fmac_f32_e32 v123, v161, v161
	v_add_f32_e32 v122, v122, v123
	v_mul_f32_e32 v123, v128, v128
	v_fmac_f32_e32 v123, v156, v156
	v_add_f32_e32 v122, v123, v122
	v_mul_f32_e32 v123, v129, v129
	v_fmac_f32_e32 v123, v157, v157
	v_add_f32_e32 v156, v123, v122
	v_mov_b64_e32 v[122:123], v[164:165]
	v_mov_b64_e32 v[124:125], v[166:167]
	s_waitcnt lgkmcnt(0)
	v_lshlrev_b32_e32 v126, 16, v122
	v_and_b32_e32 v127, 0xffff0000, v122
	v_lshlrev_b32_e32 v122, 16, v123
	v_and_b32_e32 v123, 0xffff0000, v123
	v_lshlrev_b32_e32 v128, 16, v124
	v_and_b32_e32 v129, 0xffff0000, v124
	v_lshlrev_b32_e32 v124, 16, v125
	v_and_b32_e32 v125, 0xffff0000, v125
	v_pk_fma_f32 v[120:121], v[142:143], v[120:121], v[122:123]
	v_pk_fma_f32 v[118:119], v[130:131], v[118:119], v[126:127]
	v_pk_fma_f32 v[122:123], v[142:143], v[116:117], v[124:125]
	v_pk_fma_f32 v[124:125], v[130:131], v[114:115], v[128:129]
	v_cvt_pk_bf16_f32 v114, v118, v119
	v_cvt_pk_bf16_f32 v115, v120, v121
	v_cvt_pk_bf16_f32 v116, v124, v125
	v_cvt_pk_bf16_f32 v117, v122, v123
	flat_store_dwordx4 v[150:151], v[114:117] offset:256
	s_nop 1
	v_mul_f32_e32 v114, v124, v124
	v_fmac_f32_e32 v114, v118, v118
	v_mul_f32_e32 v115, v125, v125
	v_add_f32_e32 v114, v114, v156
	v_fmac_f32_e32 v115, v119, v119
	v_add_f32_e32 v114, v115, v114
	v_mul_f32_e32 v115, v122, v122
	v_fmac_f32_e32 v115, v120, v120
	v_add_f32_e32 v114, v115, v114
	v_mul_f32_e32 v115, v123, v123
	v_fmac_f32_e32 v115, v121, v121
	v_add_f32_e32 v114, v115, v114
	ds_bpermute_b32 v115, v155, v114
	s_waitcnt lgkmcnt(0)
	v_add_f32_e32 v114, v114, v115
	ds_bpermute_b32 v115, v154, v114
	s_and_saveexec_b64 s[24:25], s[4:5]
	s_cbranch_execz .LBB0_1106
	s_waitcnt lgkmcnt(0)
	v_add_f32_e32 v116, v114, v115
	v_lshlrev_b64 v[114:115], 6, v[148:149]
	v_lshl_add_u64 v[114:115], s[38:39], 0, v[114:115]
	v_lshl_add_u64 v[114:115], s[48:49], 2, v[114:115]
	s_lshl_b32 s28, s53, 2
	s_mov_b32 s29, s93
	v_lshl_add_u64 v[114:115], v[114:115], 0, s[28:29]
	flat_store_dword v[114:115], v116
; __device__ __forceinline__ u32x4 pack8(f32x4 a, f32x4 b) { u32x4 w; w.x = pk2(a[0], a[1]); w.y = pk2(a[2], a[3]); w.z = pk2(b[0], b[1]); w.w = pk2(b[2], b[3]); return w; }
; __device__ __forceinline__ void unpack8(u32x4 w, f32x4& a, f32x4& b) { a = (f32x4){bflo(w.x), bfhi(w.x), bflo(w.y), bfhi(w.y)}; b = (f32x4){bflo(w.z), bfhi(w.z), bflo(w.w), bfhi(w.w)}; }
;     __device__ __forceinline__ void operator()(const Acc& acc, const Unit& u, int wr, int wc, int fr, int fq, const RsCtx& rc) const {
;     ...
;             for (int m = 0; m < 4; ++m) { const int row = EPI_ROW(u, ai, wr, m, fr); float s = 0.f;
; #pragma unroll
;                 for (int bj = 0; bj < 2; ++bj) { const size_t off = (size_t)row * DM + u.pn * 256 + bj * 128 + wc * 32 + 8 * fq;
;                     f32x4 x0, x1; unpack8(*(const u32x4*)(XB + off), x0, x1);
;                     x0 = x0 + acc[ai][bj][m][0] * alpha; x1 = x1 + acc[ai][bj][m][1] * alpha;
;                     *(u32x4*)(XB + off) = pack8(x0, x1);
; #pragma unroll
;                     for (int e = 0; e < 4; ++e) s += x0[e] * x0[e] + x1[e] * x1[e]; }
;                 s += __shfl_xor(s, 16); s += __shfl_xor(s, 32);
;                 if (fq == 0) ssq_x[(size_t)row * 16 + u.pn * 4 + wc] = s;
.LBB0_1106:
	s_or_b64 exec, exec, s[24:25]
	v_or_b32_e32 v114, 16, v148
	s_waitcnt lgkmcnt(0)
	v_ashrrev_i32_e32 v115, 31, v114
	v_lshlrev_b64 v[116:117], 11, v[114:115]
	v_lshl_add_u64 v[116:117], s[36:37], 0, v[116:117]
	v_lshl_add_u64 v[116:117], s[50:51], 1, v[116:117]
	v_lshl_add_u64 v[116:117], v[116:117], 0, s[92:93]
	v_lshl_add_u64 v[120:121], v[116:117], 0, v[0:1]
	v_mov_b64_e32 v[116:117], v[168:169]
	v_mov_b64_e32 v[118:119], v[170:171]
	s_waitcnt lgkmcnt(0)
	v_lshlrev_b32_e32 v122, 16, v116
	v_and_b32_e32 v123, 0xffff0000, v116
	v_lshlrev_b32_e32 v116, 16, v117
	v_and_b32_e32 v117, 0xffff0000, v117
	v_lshlrev_b32_e32 v124, 16, v118
	v_and_b32_e32 v125, 0xffff0000, v118
	v_lshlrev_b32_e32 v118, 16, v119
	v_and_b32_e32 v119, 0xffff0000, v119
	v_pk_fma_f32 v[112:113], v[142:143], v[112:113], v[116:117]
	v_pk_fma_f32 v[110:111], v[130:131], v[110:111], v[122:123]
	v_pk_fma_f32 v[116:117], v[142:143], v[108:109], v[118:119]
	v_pk_fma_f32 v[118:119], v[130:131], v[106:107], v[124:125]
	v_cvt_pk_bf16_f32 v106, v110, v111
	v_cvt_pk_bf16_f32 v107, v112, v113
	v_cvt_pk_bf16_f32 v108, v118, v119
	v_cvt_pk_bf16_f32 v109, v116, v117
	flat_store_dwordx4 v[120:121], v[106:109]
	s_nop 1
	v_mul_f32_e32 v106, v118, v118
	v_mul_f32_e32 v107, v119, v119
	v_fmac_f32_e32 v106, v110, v110
	v_fmac_f32_e32 v107, v111, v111
	v_add_f32_e32 v106, v106, v107
	v_mul_f32_e32 v107, v116, v116
	v_fmac_f32_e32 v107, v112, v112
	v_add_f32_e32 v106, v107, v106
	v_mul_f32_e32 v107, v117, v117
	v_fmac_f32_e32 v107, v113, v113
	v_add_f32_e32 v116, v107, v106
	v_mov_b64_e32 v[106:107], v[172:173]
	v_mov_b64_e32 v[108:109], v[174:175]
	s_waitcnt lgkmcnt(0)
	v_lshlrev_b32_e32 v110, 16, v106
	v_and_b32_e32 v111, 0xffff0000, v106
	v_lshlrev_b32_e32 v106, 16, v107
	v_and_b32_e32 v107, 0xffff0000, v107
	v_lshlrev_b32_e32 v112, 16, v108
	v_and_b32_e32 v113, 0xffff0000, v108
	v_lshlrev_b32_e32 v108, 16, v109
	v_and_b32_e32 v109, 0xffff0000, v109
	v_pk_fma_f32 v[104:105], v[142:143], v[104:105], v[106:107]
	v_pk_fma_f32 v[102:103], v[130:131], v[102:103], v[110:111]
	v_pk_fma_f32 v[106:107], v[142:143], v[100:101], v[108:109]
	v_pk_fma_f32 v[108:109], v[130:131], v[98:99], v[112:113]
	v_cvt_pk_bf16_f32 v98, v102, v103
	v_cvt_pk_bf16_f32 v99, v104, v105
	v_cvt_pk_bf16_f32 v100, v108, v109
	v_cvt_pk_bf16_f32 v101, v106, v107
	flat_store_dwordx4 v[120:121], v[98:101] offset:256
	s_nop 1
	v_mul_f32_e32 v98, v108, v108
	v_fmac_f32_e32 v98, v102, v102
	v_mul_f32_e32 v99, v109, v109
	v_add_f32_e32 v98, v98, v116
	v_fmac_f32_e32 v99, v103, v103
	v_add_f32_e32 v98, v99, v98
	v_mul_f32_e32 v99, v106, v106
	v_fmac_f32_e32 v99, v104, v104
	v_add_f32_e32 v98, v99, v98
	v_mul_f32_e32 v99, v107, v107
	v_fmac_f32_e32 v99, v105, v105
	v_add_f32_e32 v98, v99, v98
	ds_bpermute_b32 v99, v155, v98
	s_waitcnt lgkmcnt(0)
	v_add_f32_e32 v98, v98, v99
	ds_bpermute_b32 v99, v154, v98
	s_and_saveexec_b64 s[24:25], s[4:5]
	s_cbranch_execz .LBB0_1108
	s_waitcnt lgkmcnt(0)
	v_add_f32_e32 v100, v98, v99
	v_lshlrev_b64 v[98:99], 6, v[114:115]
	v_lshl_add_u64 v[98:99], s[38:39], 0, v[98:99]
	v_lshl_add_u64 v[98:99], s[48:49], 2, v[98:99]
	s_lshl_b32 s28, s53, 2
	s_mov_b32 s29, s93
	v_lshl_add_u64 v[98:99], v[98:99], 0, s[28:29]
	flat_store_dword v[98:99], v100
.LBB0_1108:
	s_or_b64 exec, exec, s[24:25]
	v_or_b32_e32 v98, 32, v148
	s_waitcnt lgkmcnt(0)
	v_ashrrev_i32_e32 v99, 31, v98
	v_lshlrev_b64 v[100:101], 11, v[98:99]
	v_lshl_add_u64 v[100:101], s[36:37], 0, v[100:101]
	v_lshl_add_u64 v[100:101], s[50:51], 1, v[100:101]
	v_lshl_add_u64 v[100:101], v[100:101], 0, s[92:93]
	v_lshl_add_u64 v[104:105], v[100:101], 0, v[0:1]
	v_mov_b64_e32 v[100:101], v[176:177]
	v_mov_b64_e32 v[102:103], v[178:179]
	s_waitcnt lgkmcnt(0)
	v_lshlrev_b32_e32 v106, 16, v100
	v_and_b32_e32 v107, 0xffff0000, v100
	v_lshlrev_b32_e32 v100, 16, v101
	v_and_b32_e32 v101, 0xffff0000, v101
	v_lshlrev_b32_e32 v108, 16, v102
	v_and_b32_e32 v109, 0xffff0000, v102
	v_lshlrev_b32_e32 v102, 16, v103
	v_and_b32_e32 v103, 0xffff0000, v103
	v_pk_fma_f32 v[96:97], v[142:143], v[96:97], v[100:101]
	v_pk_fma_f32 v[94:95], v[130:131], v[94:95], v[106:107]
	v_pk_fma_f32 v[100:101], v[142:143], v[92:93], v[102:103]
	v_pk_fma_f32 v[102:103], v[130:131], v[90:91], v[108:109]
	v_cvt_pk_bf16_f32 v90, v94, v95
	v_cvt_pk_bf16_f32 v91, v96, v97
	v_cvt_pk_bf16_f32 v92, v102, v103
	v_cvt_pk_bf16_f32 v93, v100, v101
	flat_store_dwordx4 v[104:105], v[90:93]
	s_nop 1
	v_mul_f32_e32 v90, v102, v102
	v_mul_f32_e32 v91, v103, v103
	v_fmac_f32_e32 v90, v94, v94
	v_fmac_f32_e32 v91, v95, v95
	v_add_f32_e32 v90, v90, v91
	v_mul_f32_e32 v91, v100, v100
	v_fmac_f32_e32 v91, v96, v96
	v_add_f32_e32 v90, v91, v90
	v_mul_f32_e32 v91, v101, v101
	v_fmac_f32_e32 v91, v97, v97
	v_add_f32_e32 v100, v91, v90
	v_mov_b64_e32 v[90:91], v[180:181]
	v_mov_b64_e32 v[92:93], v[182:183]
	s_waitcnt lgkmcnt(0)
	v_lshlrev_b32_e32 v94, 16, v90
	v_and_b32_e32 v95, 0xffff0000, v90
	v_lshlrev_b32_e32 v90, 16, v91
	v_and_b32_e32 v91, 0xffff0000, v91
	v_lshlrev_b32_e32 v96, 16, v92
	v_and_b32_e32 v97, 0xffff0000, v92
	v_lshlrev_b32_e32 v92, 16, v93
	v_and_b32_e32 v93, 0xffff0000, v93
	v_pk_fma_f32 v[88:89], v[142:143], v[88:89], v[90:91]
	v_pk_fma_f32 v[86:87], v[130:131], v[86:87], v[94:95]
	v_pk_fma_f32 v[90:91], v[142:143], v[84:85], v[92:93]
	v_pk_fma_f32 v[92:93], v[130:131], v[82:83], v[96:97]
	v_cvt_pk_bf16_f32 v82, v86, v87
	v_cvt_pk_bf16_f32 v83, v88, v89
	v_cvt_pk_bf16_f32 v84, v92, v93
	v_cvt_pk_bf16_f32 v85, v90, v91
	flat_store_dwordx4 v[104:105], v[82:85] offset:256
	s_nop 1
	v_mul_f32_e32 v82, v92, v92
	v_fmac_f32_e32 v82, v86, v86
	v_mul_f32_e32 v83, v93, v93
	v_add_f32_e32 v82, v82, v100
	v_fmac_f32_e32 v83, v87, v87
	v_add_f32_e32 v82, v83, v82
	v_mul_f32_e32 v83, v90, v90
	v_fmac_f32_e32 v83, v88, v88
	v_add_f32_e32 v82, v83, v82
	v_mul_f32_e32 v83, v91, v91
	v_fmac_f32_e32 v83, v89, v89
	v_add_f32_e32 v82, v83, v82
	ds_bpermute_b32 v83, v155, v82
	s_waitcnt lgkmcnt(0)
	v_add_f32_e32 v82, v82, v83
	ds_bpermute_b32 v83, v154, v82
	s_and_saveexec_b64 s[24:25], s[4:5]
	s_cbranch_execz .LBB0_1110
	s_waitcnt lgkmcnt(0)
	v_add_f32_e32 v84, v82, v83
	v_lshlrev_b64 v[82:83], 6, v[98:99]
	v_lshl_add_u64 v[82:83], s[38:39], 0, v[82:83]
	v_lshl_add_u64 v[82:83], s[48:49], 2, v[82:83]
	s_lshl_b32 s28, s53, 2
	s_mov_b32 s29, s93
	v_lshl_add_u64 v[82:83], v[82:83], 0, s[28:29]
	flat_store_dword v[82:83], v84
; __device__ __forceinline__ u32x4 pack8(f32x4 a, f32x4 b) { u32x4 w; w.x = pk2(a[0], a[1]); w.y = pk2(a[2], a[3]); w.z = pk2(b[0], b[1]); w.w = pk2(b[2], b[3]); return w; }
; __device__ __forceinline__ void unpack8(u32x4 w, f32x4& a, f32x4& b) { a = (f32x4){bflo(w.x), bfhi(w.x), bflo(w.y), bfhi(w.y)}; b = (f32x4){bflo(w.z), bfhi(w.z), bflo(w.w), bfhi(w.w)}; }
;     __device__ __forceinline__ void operator()(const Acc& acc, const Unit& u, int wr, int wc, int fr, int fq, const RsCtx& rc) const {
;     ...
;             for (int m = 0; m < 4; ++m) { const int row = EPI_ROW(u, ai, wr, m, fr); float s = 0.f;
; #pragma unroll
;                 for (int bj = 0; bj < 2; ++bj) { const size_t off = (size_t)row * DM + u.pn * 256 + bj * 128 + wc * 32 + 8 * fq;
;                     f32x4 x0, x1; unpack8(*(const u32x4*)(XB + off), x0, x1);
;                     x0 = x0 + acc[ai][bj][m][0] * alpha; x1 = x1 + acc[ai][bj][m][1] * alpha;
;                     *(u32x4*)(XB + off) = pack8(x0, x1);
; #pragma unroll
;                     for (int e = 0; e < 4; ++e) s += x0[e] * x0[e] + x1[e] * x1[e]; }
;                 s += __shfl_xor(s, 16); s += __shfl_xor(s, 32);
;                 if (fq == 0) ssq_x[(size_t)row * 16 + u.pn * 4 + wc] = s;
.LBB0_1110:
	s_or_b64 exec, exec, s[24:25]
	v_or_b32_e32 v82, 48, v148
	s_waitcnt lgkmcnt(0)
	v_ashrrev_i32_e32 v83, 31, v82
	v_lshlrev_b64 v[84:85], 11, v[82:83]
	v_lshl_add_u64 v[84:85], s[36:37], 0, v[84:85]
	v_lshl_add_u64 v[84:85], s[50:51], 1, v[84:85]
	v_lshl_add_u64 v[84:85], v[84:85], 0, s[92:93]
	v_lshl_add_u64 v[88:89], v[84:85], 0, v[0:1]
	v_mov_b64_e32 v[84:85], v[184:185]
	v_mov_b64_e32 v[86:87], v[186:187]
	s_waitcnt lgkmcnt(0)
	v_lshlrev_b32_e32 v90, 16, v84
	v_and_b32_e32 v91, 0xffff0000, v84
	v_lshlrev_b32_e32 v84, 16, v85
	v_and_b32_e32 v85, 0xffff0000, v85
	v_lshlrev_b32_e32 v92, 16, v86
	v_and_b32_e32 v93, 0xffff0000, v86
	v_lshlrev_b32_e32 v86, 16, v87
	v_and_b32_e32 v87, 0xffff0000, v87
	v_pk_fma_f32 v[80:81], v[142:143], v[80:81], v[84:85]
	v_pk_fma_f32 v[78:79], v[130:131], v[78:79], v[90:91]
	v_pk_fma_f32 v[84:85], v[142:143], v[76:77], v[86:87]
	v_pk_fma_f32 v[86:87], v[130:131], v[74:75], v[92:93]
	v_cvt_pk_bf16_f32 v74, v78, v79
	v_cvt_pk_bf16_f32 v75, v80, v81
	v_cvt_pk_bf16_f32 v76, v86, v87
	v_cvt_pk_bf16_f32 v77, v84, v85
	flat_store_dwordx4 v[88:89], v[74:77]
	s_nop 1
	v_mul_f32_e32 v74, v86, v86
	v_mul_f32_e32 v75, v87, v87
	v_fmac_f32_e32 v74, v78, v78
	v_fmac_f32_e32 v75, v79, v79
	v_add_f32_e32 v74, v74, v75
	v_mul_f32_e32 v75, v84, v84
	v_fmac_f32_e32 v75, v80, v80
	v_add_f32_e32 v74, v75, v74
	v_mul_f32_e32 v75, v85, v85
	v_fmac_f32_e32 v75, v81, v81
	v_add_f32_e32 v84, v75, v74
	v_mov_b64_e32 v[74:75], v[188:189]
	v_mov_b64_e32 v[76:77], v[190:191]
	s_waitcnt lgkmcnt(0)
	v_lshlrev_b32_e32 v78, 16, v74
	v_and_b32_e32 v79, 0xffff0000, v74
	v_lshlrev_b32_e32 v74, 16, v75
	v_and_b32_e32 v75, 0xffff0000, v75
	v_lshlrev_b32_e32 v80, 16, v76
	v_and_b32_e32 v81, 0xffff0000, v76
	v_lshlrev_b32_e32 v76, 16, v77
	v_and_b32_e32 v77, 0xffff0000, v77
	v_pk_fma_f32 v[72:73], v[142:143], v[72:73], v[74:75]
	v_pk_fma_f32 v[70:71], v[130:131], v[70:71], v[78:79]
	v_pk_fma_f32 v[74:75], v[142:143], v[68:69], v[76:77]
	v_pk_fma_f32 v[76:77], v[130:131], v[66:67], v[80:81]
	v_cvt_pk_bf16_f32 v66, v70, v71
	v_cvt_pk_bf16_f32 v67, v72, v73
	v_cvt_pk_bf16_f32 v68, v76, v77
	v_cvt_pk_bf16_f32 v69, v74, v75
	flat_store_dwordx4 v[88:89], v[66:69] offset:256
	s_nop 1
	v_mul_f32_e32 v66, v76, v76
	v_fmac_f32_e32 v66, v70, v70
	v_mul_f32_e32 v67, v77, v77
	v_add_f32_e32 v66, v66, v84
	v_fmac_f32_e32 v67, v71, v71
	v_add_f32_e32 v66, v67, v66
	v_mul_f32_e32 v67, v74, v74
	v_fmac_f32_e32 v67, v72, v72
	v_add_f32_e32 v66, v67, v66
	v_mul_f32_e32 v67, v75, v75
	v_fmac_f32_e32 v67, v73, v73
	v_add_f32_e32 v66, v67, v66
	ds_bpermute_b32 v67, v155, v66
	s_waitcnt lgkmcnt(0)
	v_add_f32_e32 v66, v66, v67
	ds_bpermute_b32 v67, v154, v66
	s_and_saveexec_b64 s[24:25], s[4:5]
	s_cbranch_execz .LBB0_1112
	s_waitcnt lgkmcnt(0)
	v_add_f32_e32 v68, v66, v67
	v_lshlrev_b64 v[66:67], 6, v[82:83]
	v_lshl_add_u64 v[66:67], s[38:39], 0, v[66:67]
	v_lshl_add_u64 v[66:67], s[48:49], 2, v[66:67]
	s_lshl_b32 s28, s53, 2
	s_mov_b32 s29, s93
	v_lshl_add_u64 v[66:67], v[66:67], 0, s[28:29]
	flat_store_dword v[66:67], v68
.LBB0_1112:
	s_or_b64 exec, exec, s[24:25]
	v_add_u32_e32 v66, 0x80, v148
	s_waitcnt lgkmcnt(0)
	v_ashrrev_i32_e32 v67, 31, v66
	v_lshlrev_b64 v[68:69], 11, v[66:67]
	v_lshl_add_u64 v[68:69], s[36:37], 0, v[68:69]
	v_lshl_add_u64 v[68:69], s[50:51], 1, v[68:69]
	v_lshl_add_u64 v[68:69], v[68:69], 0, s[92:93]
	v_lshl_add_u64 v[72:73], v[68:69], 0, v[0:1]
	v_mov_b64_e32 v[68:69], v[192:193]
	v_mov_b64_e32 v[70:71], v[194:195]
	s_waitcnt lgkmcnt(0)
	v_lshlrev_b32_e32 v74, 16, v68
	v_and_b32_e32 v75, 0xffff0000, v68
	v_lshlrev_b32_e32 v68, 16, v69
	v_and_b32_e32 v69, 0xffff0000, v69
	v_lshlrev_b32_e32 v76, 16, v70
	v_and_b32_e32 v77, 0xffff0000, v70
	v_lshlrev_b32_e32 v70, 16, v71
	v_and_b32_e32 v71, 0xffff0000, v71
	v_pk_fma_f32 v[64:65], v[142:143], v[64:65], v[68:69]
	v_pk_fma_f32 v[62:63], v[130:131], v[62:63], v[74:75]
	v_pk_fma_f32 v[68:69], v[142:143], v[60:61], v[70:71]
	v_pk_fma_f32 v[70:71], v[130:131], v[58:59], v[76:77]
	v_cvt_pk_bf16_f32 v58, v62, v63
	v_cvt_pk_bf16_f32 v59, v64, v65
	v_cvt_pk_bf16_f32 v60, v70, v71
	v_cvt_pk_bf16_f32 v61, v68, v69
	flat_store_dwordx4 v[72:73], v[58:61]
	s_nop 1
	v_mul_f32_e32 v58, v70, v70
	v_mul_f32_e32 v59, v71, v71
	v_fmac_f32_e32 v58, v62, v62
	v_fmac_f32_e32 v59, v63, v63
	v_add_f32_e32 v58, v58, v59
	v_mul_f32_e32 v59, v68, v68
	v_fmac_f32_e32 v59, v64, v64
	v_add_f32_e32 v58, v59, v58
	v_mul_f32_e32 v59, v69, v69
	v_fmac_f32_e32 v59, v65, v65
	v_add_f32_e32 v68, v59, v58
	v_mov_b64_e32 v[58:59], v[206:207]
	v_mov_b64_e32 v[60:61], v[208:209]
	s_waitcnt lgkmcnt(0)
	v_lshlrev_b32_e32 v62, 16, v58
	v_and_b32_e32 v63, 0xffff0000, v58
	v_lshlrev_b32_e32 v58, 16, v59
	v_and_b32_e32 v59, 0xffff0000, v59
	v_lshlrev_b32_e32 v64, 16, v60
	v_and_b32_e32 v65, 0xffff0000, v60
	v_lshlrev_b32_e32 v60, 16, v61
	v_and_b32_e32 v61, 0xffff0000, v61
	v_pk_fma_f32 v[56:57], v[142:143], v[56:57], v[58:59]
	v_pk_fma_f32 v[54:55], v[130:131], v[54:55], v[62:63]
	v_pk_fma_f32 v[58:59], v[142:143], v[52:53], v[60:61]
	v_pk_fma_f32 v[60:61], v[130:131], v[50:51], v[64:65]
	v_cvt_pk_bf16_f32 v50, v54, v55
	v_cvt_pk_bf16_f32 v51, v56, v57
	v_cvt_pk_bf16_f32 v52, v60, v61
	v_cvt_pk_bf16_f32 v53, v58, v59
	flat_store_dwordx4 v[72:73], v[50:53] offset:256
	s_nop 1
	v_mul_f32_e32 v50, v60, v60
	v_fmac_f32_e32 v50, v54, v54
	v_mul_f32_e32 v51, v61, v61
	v_add_f32_e32 v50, v50, v68
	v_fmac_f32_e32 v51, v55, v55
	v_add_f32_e32 v50, v51, v50
	v_mul_f32_e32 v51, v58, v58
	v_fmac_f32_e32 v51, v56, v56
	v_add_f32_e32 v50, v51, v50
	v_mul_f32_e32 v51, v59, v59
	v_fmac_f32_e32 v51, v57, v57
	v_add_f32_e32 v50, v51, v50
	ds_bpermute_b32 v51, v155, v50
	s_waitcnt lgkmcnt(0)
	v_add_f32_e32 v50, v50, v51
	ds_bpermute_b32 v51, v154, v50
	s_and_saveexec_b64 s[24:25], s[4:5]
	s_cbranch_execz .LBB0_1114
	s_waitcnt lgkmcnt(0)
	v_add_f32_e32 v52, v50, v51
	v_lshlrev_b64 v[50:51], 6, v[66:67]
	v_lshl_add_u64 v[50:51], s[38:39], 0, v[50:51]
	v_lshl_add_u64 v[50:51], s[48:49], 2, v[50:51]
	s_lshl_b32 s28, s53, 2
	s_mov_b32 s29, s93
	v_lshl_add_u64 v[50:51], v[50:51], 0, s[28:29]
	flat_store_dword v[50:51], v52
; __device__ __forceinline__ u32x4 pack8(f32x4 a, f32x4 b) { u32x4 w; w.x = pk2(a[0], a[1]); w.y = pk2(a[2], a[3]); w.z = pk2(b[0], b[1]); w.w = pk2(b[2], b[3]); return w; }
; __device__ __forceinline__ void unpack8(u32x4 w, f32x4& a, f32x4& b) { a = (f32x4){bflo(w.x), bfhi(w.x), bflo(w.y), bfhi(w.y)}; b = (f32x4){bflo(w.z), bfhi(w.z), bflo(w.w), bfhi(w.w)}; }
;     __device__ __forceinline__ void operator()(const Acc& acc, const Unit& u, int wr, int wc, int fr, int fq, const RsCtx& rc) const {
;     ...
;             for (int m = 0; m < 4; ++m) { const int row = EPI_ROW(u, ai, wr, m, fr); float s = 0.f;
; #pragma unroll
;                 for (int bj = 0; bj < 2; ++bj) { const size_t off = (size_t)row * DM + u.pn * 256 + bj * 128 + wc * 32 + 8 * fq;
;                     f32x4 x0, x1; unpack8(*(const u32x4*)(XB + off), x0, x1);
;                     x0 = x0 + acc[ai][bj][m][0] * alpha; x1 = x1 + acc[ai][bj][m][1] * alpha;
;                     *(u32x4*)(XB + off) = pack8(x0, x1);
; #pragma unroll
;                     for (int e = 0; e < 4; ++e) s += x0[e] * x0[e] + x1[e] * x1[e]; }
;                 s += __shfl_xor(s, 16); s += __shfl_xor(s, 32);
;                 if (fq == 0) ssq_x[(size_t)row * 16 + u.pn * 4 + wc] = s;
.LBB0_1114:
	s_or_b64 exec, exec, s[24:25]
	v_add_u32_e32 v50, 0x90, v148
	s_waitcnt lgkmcnt(0)
	v_ashrrev_i32_e32 v51, 31, v50
	v_lshlrev_b64 v[52:53], 11, v[50:51]
	v_lshl_add_u64 v[52:53], s[36:37], 0, v[52:53]
	v_lshl_add_u64 v[52:53], s[50:51], 1, v[52:53]
	v_lshl_add_u64 v[52:53], v[52:53], 0, s[92:93]
	v_lshl_add_u64 v[56:57], v[52:53], 0, v[0:1]
	v_mov_b64_e32 v[52:53], v[218:219]
	v_mov_b64_e32 v[54:55], v[220:221]
	s_waitcnt lgkmcnt(0)
	v_lshlrev_b32_e32 v58, 16, v52
	v_and_b32_e32 v59, 0xffff0000, v52
	v_lshlrev_b32_e32 v52, 16, v53
	v_and_b32_e32 v53, 0xffff0000, v53
	v_lshlrev_b32_e32 v60, 16, v54
	v_and_b32_e32 v61, 0xffff0000, v54
	v_lshlrev_b32_e32 v54, 16, v55
	v_and_b32_e32 v55, 0xffff0000, v55
	v_pk_fma_f32 v[48:49], v[142:143], v[48:49], v[52:53]
	v_pk_fma_f32 v[46:47], v[130:131], v[46:47], v[58:59]
	v_pk_fma_f32 v[52:53], v[142:143], v[44:45], v[54:55]
	v_pk_fma_f32 v[54:55], v[130:131], v[42:43], v[60:61]
	v_cvt_pk_bf16_f32 v42, v46, v47
	v_cvt_pk_bf16_f32 v43, v48, v49
	v_cvt_pk_bf16_f32 v44, v54, v55
	v_cvt_pk_bf16_f32 v45, v52, v53
	flat_store_dwordx4 v[56:57], v[42:45]
	s_nop 1
	v_mul_f32_e32 v42, v54, v54
	v_mul_f32_e32 v43, v55, v55
	v_fmac_f32_e32 v42, v46, v46
	v_fmac_f32_e32 v43, v47, v47
	v_add_f32_e32 v42, v42, v43
	v_mul_f32_e32 v43, v52, v52
	v_fmac_f32_e32 v43, v48, v48
	v_add_f32_e32 v42, v43, v42
	v_mul_f32_e32 v43, v53, v53
	v_fmac_f32_e32 v43, v49, v49
	v_add_f32_e32 v52, v43, v42
	v_mov_b64_e32 v[42:43], v[232:233]
	v_mov_b64_e32 v[44:45], v[234:235]
	s_waitcnt lgkmcnt(0)
	v_lshlrev_b32_e32 v46, 16, v42
	v_and_b32_e32 v47, 0xffff0000, v42
	v_lshlrev_b32_e32 v42, 16, v43
	v_and_b32_e32 v43, 0xffff0000, v43
	v_lshlrev_b32_e32 v48, 16, v44
	v_and_b32_e32 v49, 0xffff0000, v44
	v_lshlrev_b32_e32 v44, 16, v45
	v_and_b32_e32 v45, 0xffff0000, v45
	v_pk_fma_f32 v[40:41], v[142:143], v[40:41], v[42:43]
	v_pk_fma_f32 v[38:39], v[130:131], v[38:39], v[46:47]
	v_pk_fma_f32 v[42:43], v[142:143], v[36:37], v[44:45]
	v_pk_fma_f32 v[44:45], v[130:131], v[34:35], v[48:49]
	v_cvt_pk_bf16_f32 v34, v38, v39
	v_cvt_pk_bf16_f32 v35, v40, v41
	v_cvt_pk_bf16_f32 v36, v44, v45
	v_cvt_pk_bf16_f32 v37, v42, v43
	flat_store_dwordx4 v[56:57], v[34:37] offset:256
	s_nop 1
	v_mul_f32_e32 v34, v44, v44
	v_fmac_f32_e32 v34, v38, v38
	v_mul_f32_e32 v35, v45, v45
	v_add_f32_e32 v34, v34, v52
	v_fmac_f32_e32 v35, v39, v39
	v_add_f32_e32 v34, v35, v34
	v_mul_f32_e32 v35, v42, v42
	v_fmac_f32_e32 v35, v40, v40
	v_add_f32_e32 v34, v35, v34
	v_mul_f32_e32 v35, v43, v43
	v_fmac_f32_e32 v35, v41, v41
	v_add_f32_e32 v34, v35, v34
	ds_bpermute_b32 v35, v155, v34
	s_waitcnt lgkmcnt(0)
	v_add_f32_e32 v34, v34, v35
	ds_bpermute_b32 v35, v154, v34
	s_and_saveexec_b64 s[24:25], s[4:5]
	s_cbranch_execz .LBB0_1116
	s_waitcnt lgkmcnt(0)
	v_add_f32_e32 v36, v34, v35
	v_lshlrev_b64 v[34:35], 6, v[50:51]
	v_lshl_add_u64 v[34:35], s[38:39], 0, v[34:35]
	v_lshl_add_u64 v[34:35], s[48:49], 2, v[34:35]
	s_lshl_b32 s28, s53, 2
	s_mov_b32 s29, s93
	v_lshl_add_u64 v[34:35], v[34:35], 0, s[28:29]
	flat_store_dword v[34:35], v36
; __device__ __forceinline__ u32x4 pack8(f32x4 a, f32x4 b) { u32x4 w; w.x = pk2(a[0], a[1]); w.y = pk2(a[2], a[3]); w.z = pk2(b[0], b[1]); w.w = pk2(b[2], b[3]); return w; }
; __device__ __forceinline__ void unpack8(u32x4 w, f32x4& a, f32x4& b) { a = (f32x4){bflo(w.x), bfhi(w.x), bflo(w.y), bfhi(w.y)}; b = (f32x4){bflo(w.z), bfhi(w.z), bflo(w.w), bfhi(w.w)}; }
;     __device__ __forceinline__ void operator()(const Acc& acc, const Unit& u, int wr, int wc, int fr, int fq, const RsCtx& rc) const {
;     ...
;             for (int m = 0; m < 4; ++m) { const int row = EPI_ROW(u, ai, wr, m, fr); float s = 0.f;
; #pragma unroll
;                 for (int bj = 0; bj < 2; ++bj) { const size_t off = (size_t)row * DM + u.pn * 256 + bj * 128 + wc * 32 + 8 * fq;
;                     f32x4 x0, x1; unpack8(*(const u32x4*)(XB + off), x0, x1);
;                     x0 = x0 + acc[ai][bj][m][0] * alpha; x1 = x1 + acc[ai][bj][m][1] * alpha;
;                     *(u32x4*)(XB + off) = pack8(x0, x1);
; #pragma unroll
;                     for (int e = 0; e < 4; ++e) s += x0[e] * x0[e] + x1[e] * x1[e]; }
;                 s += __shfl_xor(s, 16); s += __shfl_xor(s, 32);
;                 if (fq == 0) ssq_x[(size_t)row * 16 + u.pn * 4 + wc] = s;
.LBB0_1116:
	s_or_b64 exec, exec, s[24:25]
	v_add_u32_e32 v34, 0xa0, v148
	s_waitcnt lgkmcnt(0)
	v_ashrrev_i32_e32 v35, 31, v34
	v_lshlrev_b64 v[36:37], 11, v[34:35]
	v_lshl_add_u64 v[36:37], s[36:37], 0, v[36:37]
	v_lshl_add_u64 v[36:37], s[50:51], 1, v[36:37]
	v_lshl_add_u64 v[36:37], v[36:37], 0, s[92:93]
	v_lshl_add_u64 v[40:41], v[36:37], 0, v[0:1]
	v_mov_b64_e32 v[36:37], v[236:237]
	v_mov_b64_e32 v[38:39], v[238:239]
	s_waitcnt lgkmcnt(0)
	v_lshlrev_b32_e32 v42, 16, v36
	v_and_b32_e32 v43, 0xffff0000, v36
	v_lshlrev_b32_e32 v36, 16, v37
	v_and_b32_e32 v37, 0xffff0000, v37
	v_lshlrev_b32_e32 v44, 16, v38
	v_and_b32_e32 v45, 0xffff0000, v38
	v_lshlrev_b32_e32 v38, 16, v39
	v_and_b32_e32 v39, 0xffff0000, v39
	v_pk_fma_f32 v[32:33], v[142:143], v[32:33], v[36:37]
	v_pk_fma_f32 v[30:31], v[130:131], v[30:31], v[42:43]
	v_pk_fma_f32 v[36:37], v[142:143], v[28:29], v[38:39]
	v_pk_fma_f32 v[38:39], v[130:131], v[26:27], v[44:45]
	v_cvt_pk_bf16_f32 v26, v30, v31
	v_cvt_pk_bf16_f32 v27, v32, v33
	v_cvt_pk_bf16_f32 v28, v38, v39
	v_cvt_pk_bf16_f32 v29, v36, v37
	flat_store_dwordx4 v[40:41], v[26:29]
	s_nop 1
	v_mul_f32_e32 v26, v38, v38
	v_mul_f32_e32 v27, v39, v39
	v_fmac_f32_e32 v26, v30, v30
	v_fmac_f32_e32 v27, v31, v31
	v_add_f32_e32 v26, v26, v27
	v_mul_f32_e32 v27, v36, v36
	v_fmac_f32_e32 v27, v32, v32
	v_add_f32_e32 v26, v27, v26
	v_mul_f32_e32 v27, v37, v37
	v_fmac_f32_e32 v27, v33, v33
	v_add_f32_e32 v36, v27, v26
	v_mov_b64_e32 v[26:27], v[240:241]
	v_mov_b64_e32 v[28:29], v[242:243]
	s_waitcnt lgkmcnt(0)
	v_lshlrev_b32_e32 v30, 16, v26
	v_and_b32_e32 v31, 0xffff0000, v26
	v_lshlrev_b32_e32 v26, 16, v27
	v_and_b32_e32 v27, 0xffff0000, v27
	v_lshlrev_b32_e32 v32, 16, v28
	v_and_b32_e32 v33, 0xffff0000, v28
	v_lshlrev_b32_e32 v28, 16, v29
	v_and_b32_e32 v29, 0xffff0000, v29
	v_pk_fma_f32 v[24:25], v[142:143], v[24:25], v[26:27]
	v_pk_fma_f32 v[22:23], v[130:131], v[22:23], v[30:31]
	v_pk_fma_f32 v[26:27], v[142:143], v[20:21], v[28:29]
	v_pk_fma_f32 v[28:29], v[130:131], v[18:19], v[32:33]
	v_cvt_pk_bf16_f32 v18, v22, v23
	v_cvt_pk_bf16_f32 v19, v24, v25
	v_cvt_pk_bf16_f32 v20, v28, v29
	v_cvt_pk_bf16_f32 v21, v26, v27
	flat_store_dwordx4 v[40:41], v[18:21] offset:256
	s_nop 1
	v_mul_f32_e32 v18, v28, v28
	v_fmac_f32_e32 v18, v22, v22
	v_mul_f32_e32 v19, v29, v29
	v_add_f32_e32 v18, v18, v36
	v_fmac_f32_e32 v19, v23, v23
	v_add_f32_e32 v18, v19, v18
	v_mul_f32_e32 v19, v26, v26
	v_fmac_f32_e32 v19, v24, v24
	v_add_f32_e32 v18, v19, v18
	v_mul_f32_e32 v19, v27, v27
	v_fmac_f32_e32 v19, v25, v25
	v_add_f32_e32 v18, v19, v18
	ds_bpermute_b32 v19, v155, v18
	s_waitcnt lgkmcnt(0)
	v_add_f32_e32 v18, v18, v19
	ds_bpermute_b32 v19, v154, v18
	s_and_saveexec_b64 s[24:25], s[4:5]
	s_cbranch_execz .LBB0_1118
	s_waitcnt lgkmcnt(0)
	v_add_f32_e32 v20, v18, v19
	v_lshlrev_b64 v[18:19], 6, v[34:35]
	v_lshl_add_u64 v[18:19], s[38:39], 0, v[18:19]
	v_lshl_add_u64 v[18:19], s[48:49], 2, v[18:19]
	s_lshl_b32 s28, s53, 2
	s_mov_b32 s29, s93
	v_lshl_add_u64 v[18:19], v[18:19], 0, s[28:29]
	flat_store_dword v[18:19], v20
.LBB0_1118:
	s_or_b64 exec, exec, s[24:25]
	v_add_u32_e32 v18, 0xb0, v148
	s_waitcnt lgkmcnt(0)
	v_ashrrev_i32_e32 v19, 31, v18
	v_lshlrev_b64 v[20:21], 11, v[18:19]
	v_lshl_add_u64 v[20:21], s[36:37], 0, v[20:21]
	v_lshl_add_u64 v[20:21], s[50:51], 1, v[20:21]
	v_lshl_add_u64 v[20:21], v[20:21], 0, s[92:93]
	v_lshl_add_u64 v[24:25], v[20:21], 0, v[0:1]
	v_mov_b64_e32 v[20:21], v[244:245]
	v_mov_b64_e32 v[22:23], v[246:247]
	s_waitcnt lgkmcnt(0)
	v_lshlrev_b32_e32 v26, 16, v20
	v_and_b32_e32 v27, 0xffff0000, v20
	v_lshlrev_b32_e32 v20, 16, v21
	v_and_b32_e32 v21, 0xffff0000, v21
	v_lshlrev_b32_e32 v28, 16, v22
	v_and_b32_e32 v29, 0xffff0000, v22
	v_lshlrev_b32_e32 v22, 16, v23
	v_and_b32_e32 v23, 0xffff0000, v23
	v_pk_fma_f32 v[16:17], v[142:143], v[16:17], v[20:21]
	v_pk_fma_f32 v[14:15], v[130:131], v[14:15], v[26:27]
	v_pk_fma_f32 v[20:21], v[142:143], v[12:13], v[22:23]
	v_pk_fma_f32 v[22:23], v[130:131], v[10:11], v[28:29]
	v_cvt_pk_bf16_f32 v10, v14, v15
	v_cvt_pk_bf16_f32 v11, v16, v17
	v_cvt_pk_bf16_f32 v12, v22, v23
	v_cvt_pk_bf16_f32 v13, v20, v21
	flat_store_dwordx4 v[24:25], v[10:13]
	v_mul_f32_e32 v0, v22, v22
	v_fmac_f32_e32 v0, v14, v14
	v_mul_f32_e32 v10, v23, v23
	v_fmac_f32_e32 v10, v15, v15
	v_add_f32_e32 v0, v0, v10
	v_mul_f32_e32 v10, v20, v20
	v_fmac_f32_e32 v10, v16, v16
	v_add_f32_e32 v0, v10, v0
	v_mul_f32_e32 v10, v21, v21
	v_fmac_f32_e32 v10, v17, v17
	v_add_f32_e32 v0, v10, v0
	v_mov_b64_e32 v[10:11], v[248:249]
	v_mov_b64_e32 v[12:13], v[250:251]
	s_waitcnt lgkmcnt(0)
	v_lshlrev_b32_e32 v14, 16, v10
	v_and_b32_e32 v15, 0xffff0000, v10
	v_lshlrev_b32_e32 v10, 16, v11
	v_and_b32_e32 v11, 0xffff0000, v11
	v_lshlrev_b32_e32 v16, 16, v12
	v_and_b32_e32 v17, 0xffff0000, v12
	v_lshlrev_b32_e32 v12, 16, v13
	v_and_b32_e32 v13, 0xffff0000, v13
	v_pk_fma_f32 v[8:9], v[142:143], v[8:9], v[10:11]
	v_pk_fma_f32 v[6:7], v[130:131], v[6:7], v[14:15]
	v_pk_fma_f32 v[10:11], v[142:143], v[4:5], v[12:13]
	v_pk_fma_f32 v[12:13], v[130:131], v[2:3], v[16:17]
	v_cvt_pk_bf16_f32 v2, v6, v7
	v_cvt_pk_bf16_f32 v3, v8, v9
	v_cvt_pk_bf16_f32 v4, v12, v13
	v_cvt_pk_bf16_f32 v5, v10, v11
	flat_store_dwordx4 v[24:25], v[2:5] offset:256
	s_nop 1
	v_mul_f32_e32 v2, v12, v12
	v_fmac_f32_e32 v2, v6, v6
	v_add_f32_e32 v0, v2, v0
	v_mul_f32_e32 v2, v13, v13
	v_fmac_f32_e32 v2, v7, v7
	v_add_f32_e32 v0, v2, v0
	v_mul_f32_e32 v2, v10, v10
	v_fmac_f32_e32 v2, v8, v8
	v_add_f32_e32 v0, v2, v0
	v_mul_f32_e32 v2, v11, v11
	v_fmac_f32_e32 v2, v9, v9
	v_add_f32_e32 v0, v2, v0
	ds_bpermute_b32 v2, v155, v0
	s_waitcnt lgkmcnt(0)
	v_add_f32_e32 v0, v0, v2
	ds_bpermute_b32 v2, v154, v0
	s_and_saveexec_b64 s[24:25], s[4:5]
	s_cbranch_execz .LBB0_1120
	s_waitcnt lgkmcnt(0)
	v_add_f32_e32 v0, v0, v2
	v_lshlrev_b64 v[2:3], 6, v[18:19]
	v_lshl_add_u64 v[2:3], s[38:39], 0, v[2:3]
	v_lshl_add_u64 v[2:3], s[48:49], 2, v[2:3]
	s_lshl_b32 s92, s53, 2
	v_lshl_add_u64 v[2:3], v[2:3], 0, s[92:93]
	flat_store_dword v[2:3], v0

; __device__ __forceinline__ unsigned pk2(float lo, float hi) { f32x2_t v = {lo, hi}; bf16x2_t b = __builtin_convertvector(v, bf16x2_t); return __builtin_bit_cast(unsigned, b); }
; __device__ __forceinline__ void conv_item(const float* W, int K, int N, int kind, int item, const float* gain, unsigned char* Wb, float* scr, int lane) {
;     ...
;     for (int j = 0; j < 4; ++j) { const int n = (lane >> 3) + 8 * j; const float* s = scr + (8 * c) * 33 + n;
;         u32x4 o; o.x = pk2(s[0] * gg[0], s[33] * gg[1]); o.y = pk2(s[2 * 33] * gg[2], s[3 * 33] * gg[3]); o.z = pk2(s[4 * 33] * gg[4], s[5 * 33] * gg[5]); o.w = pk2(s[6 * 33] * gg[6], s[7 * 33] * gg[7]);
;         *(u32x4*)(wdst(kind, n0 + n, Wb) + k0 + 8 * c) = o; }
;     __builtin_amdgcn_s_waitcnt(0); asm volatile("" ::: "memory");
.LBB0_1127:
	ds_read_b32 v14, v17
	ds_read_b32 v15, v17 offset:132
	ds_read_b32 v24, v17 offset:264
	ds_read_b32 v25, v17 offset:396
	ds_read_b32 v26, v17 offset:528
	ds_read_b32 v27, v17 offset:660
	ds_read_b32 v28, v17 offset:792
	ds_read_b32 v29, v17 offset:924
	s_waitcnt vmcnt(0) lgkmcnt(6)
	v_pk_mul_f32 v[14:15], v[6:7], v[14:15]
	v_add_u32_e32 v30, s22, v16
	v_cvt_pk_bf16_f32 v22, v14, v15
	s_waitcnt lgkmcnt(4)
	v_pk_mul_f32 v[14:15], v[8:9], v[24:25]
	s_movk_i32 s14, 0xaff
	v_cvt_pk_bf16_f32 v23, v14, v15
	s_waitcnt lgkmcnt(2)
	v_pk_mul_f32 v[14:15], v[10:11], v[26:27]
	v_add_u32_e32 v0, 0xfffff500, v30
	v_cmp_lt_i32_e32 vcc, s14, v30
	v_cvt_pk_bf16_f32 v24, v14, v15
	s_waitcnt lgkmcnt(0)
	v_pk_mul_f32 v[14:15], v[12:13], v[28:29]
	v_cndmask_b32_e32 v0, v30, v0, vcc
	v_cvt_pk_bf16_f32 v25, v14, v15
	v_lshlrev_b32_e32 v14, 1, v0
	v_and_b32_e32 v14, 0xffffff00, v14
	v_and_b32_e32 v0, 0x67, v0
	v_cndmask_b32_e32 v15, 0, v225, vcc
	v_or3_b32 v14, v0, v15, v14
	v_ashrrev_i32_e32 v15, 31, v14
	s_ashr_i32 s7, s6, 31
	v_lshlrev_b64 v[14:15], 11, v[14:15]
	v_lshl_add_u64 v[14:15], s[20:21], 0, v[14:15]
	s_lshl_b64 s[4:5], s[6:7], 1
	v_lshl_add_u64 v[14:15], v[14:15], 0, s[4:5]
	v_lshlrev_b32_e32 v0, 1, v4
	v_lshl_add_u64 v[14:15], v[14:15], 0, v[0:1]
	flat_store_dwordx4 v[14:15], v[22:25]
	ds_read_b32 v14, v17 offset:32
	ds_read_b32 v15, v17 offset:164
	ds_read_b32 v24, v17 offset:296
	ds_read_b32 v25, v17 offset:428
	ds_read_b32 v26, v17 offset:560
	ds_read_b32 v27, v17 offset:692
	ds_read_b32 v28, v17 offset:824
	ds_read_b32 v29, v17 offset:956
	s_waitcnt lgkmcnt(0)
	v_pk_mul_f32 v[14:15], v[6:7], v[14:15]
	s_nop 0
	v_cvt_pk_bf16_f32 v22, v14, v15
	v_pk_mul_f32 v[14:15], v[8:9], v[24:25]
	s_nop 0
	v_cvt_pk_bf16_f32 v23, v14, v15
	v_pk_mul_f32 v[14:15], v[10:11], v[26:27]
	s_nop 0
	v_cvt_pk_bf16_f32 v24, v14, v15
	v_pk_mul_f32 v[14:15], v[12:13], v[28:29]
	s_nop 0
	v_cvt_pk_bf16_f32 v25, v14, v15
	v_add_u32_e32 v14, 8, v30
	v_add_u32_e32 v15, 0xfffff508, v30
	v_cmp_lt_i32_e32 vcc, s14, v14
	s_nop 1
	v_cndmask_b32_e32 v14, v14, v15, vcc
	v_lshlrev_b32_e32 v15, 1, v14
	v_and_b32_e32 v15, 0xffffff00, v15
	v_and_b32_e32 v14, 0x6f, v14
	v_cndmask_b32_e32 v26, 0, v225, vcc
	v_or3_b32 v14, v14, v26, v15
	v_ashrrev_i32_e32 v15, 31, v14
	v_lshlrev_b64 v[14:15], 11, v[14:15]
	v_lshl_add_u64 v[14:15], s[20:21], 0, v[14:15]
	v_lshl_add_u64 v[14:15], v[14:15], 0, s[4:5]
	v_lshl_add_u64 v[14:15], v[14:15], 0, v[0:1]
	flat_store_dwordx4 v[14:15], v[22:25]
	ds_read_b32 v14, v17 offset:64
	ds_read_b32 v15, v17 offset:196
	ds_read_b32 v24, v17 offset:328
	ds_read_b32 v25, v17 offset:460
	ds_read_b32 v26, v17 offset:592
	ds_read_b32 v27, v17 offset:724
	ds_read_b32 v28, v17 offset:856
	ds_read_b32 v29, v17 offset:988
	s_waitcnt lgkmcnt(0)
	v_pk_mul_f32 v[14:15], v[6:7], v[14:15]
	s_nop 0
	v_cvt_pk_bf16_f32 v22, v14, v15
	v_pk_mul_f32 v[14:15], v[8:9], v[24:25]
	s_nop 0
	v_cvt_pk_bf16_f32 v23, v14, v15
	v_pk_mul_f32 v[14:15], v[10:11], v[26:27]
	s_nop 0
	v_cvt_pk_bf16_f32 v24, v14, v15
	v_pk_mul_f32 v[14:15], v[12:13], v[28:29]
	v_add_u32_e32 v28, 24, v30
	v_cvt_pk_bf16_f32 v25, v14, v15
	v_add_u32_e32 v14, 16, v30
	v_add_u32_e32 v15, 0xfffff510, v30
	v_cmp_lt_i32_e32 vcc, s14, v14
	v_add_u32_e32 v29, 0xfffff518, v30
	s_nop 0
	v_cndmask_b32_e32 v14, v14, v15, vcc
	v_lshlrev_b32_e32 v15, 1, v14
	v_and_b32_e32 v15, 0xffffff00, v15
	v_and_b32_e32 v14, 0x77, v14
	v_cndmask_b32_e32 v26, 0, v225, vcc
	v_or3_b32 v14, v14, v26, v15
	v_ashrrev_i32_e32 v15, 31, v14
	v_lshlrev_b64 v[14:15], 11, v[14:15]
	v_lshl_add_u64 v[14:15], s[20:21], 0, v[14:15]
	v_lshl_add_u64 v[14:15], v[14:15], 0, s[4:5]
	v_lshl_add_u64 v[14:15], v[14:15], 0, v[0:1]
	v_cmp_lt_i32_e32 vcc, s14, v28
	flat_store_dwordx4 v[14:15], v[22:25]
	ds_read_b32 v14, v17 offset:96
	ds_read_b32 v15, v17 offset:228
	ds_read_b32 v22, v17 offset:360
	ds_read_b32 v23, v17 offset:492
	ds_read_b32 v24, v17 offset:624
	ds_read_b32 v25, v17 offset:756
	ds_read_b32 v26, v17 offset:888
	ds_read_b32 v27, v17 offset:1020
	v_cndmask_b32_e32 v28, v28, v29, vcc
	v_lshlrev_b32_e32 v29, 1, v28
	v_and_b32_e32 v29, 0xffffff00, v29
	v_and_b32_e32 v28, 0x7f, v28
	v_cndmask_b32_e32 v30, 0, v225, vcc
	v_or3_b32 v28, v28, v30, v29
	v_ashrrev_i32_e32 v29, 31, v28
	v_lshlrev_b64 v[28:29], 11, v[28:29]
	s_waitcnt lgkmcnt(0)
	v_pk_mul_f32 v[6:7], v[6:7], v[14:15]
	v_pk_mul_f32 v[8:9], v[8:9], v[22:23]
	v_lshl_add_u64 v[28:29], s[20:21], 0, v[28:29]
	v_cvt_pk_bf16_f32 v6, v6, v7
	v_cvt_pk_bf16_f32 v7, v8, v9
	v_pk_mul_f32 v[8:9], v[10:11], v[24:25]
	v_pk_mul_f32 v[10:11], v[12:13], v[26:27]
	v_cvt_pk_bf16_f32 v8, v8, v9
	v_cvt_pk_bf16_f32 v9, v10, v11
	v_lshl_add_u64 v[10:11], v[28:29], 0, s[4:5]
	v_lshl_add_u64 v[10:11], v[10:11], 0, v[0:1]
	flat_store_dwordx4 v[10:11], v[6:9]
	s_waitcnt lgkmcnt(0)

; __device__ __forceinline__ void conv_item(const float* W, int K, int N, int kind, int item, const float* gain, unsigned char* Wb, float* scr, int lane) {
;     const int nblk = N / 32, kb = item / nblk, nb = item - kb * nblk, k0 = 64 * kb, n0 = 32 * nb;
;     float wv_[32];
; #pragma unroll
;     for (int i = 0; i < 32; ++i) wv_[i] = W[(size_t)(k0 + 2 * i + (lane >> 5)) * N + n0 + (lane & 31)];
; #pragma unroll
;     for (int i = 0; i < 32; ++i) scr[(2 * i + (lane >> 5)) * 33 + (lane & 31)] = wv_[i];
;     __builtin_amdgcn_s_waitcnt(0); asm volatile("" ::: "memory");
.LBB0_1129:
	s_cmpk_gt_i32 s13, 0xaff
	s_mov_b64 s[4:5], -1
	s_cbranch_scc0 .LBB0_1131
	v_readlane_b32 s4, v254, 40
	v_readlane_b32 s5, v254, 41
	s_load_dwordx2 s[4:5], s[4:5], 0x98
	v_readlane_b32 s6, v254, 46
	v_readlane_b32 s7, v254, 47
	s_mov_b32 s14, s6
	s_mul_i32 s6, s6, 0xb00000
	s_waitcnt lgkmcnt(0)
	s_add_u32 s7, s4, s6
	s_mul_hi_i32 s4, s14, 0xb00000
	s_addc_u32 s14, s5, s4
	s_lshl_b32 s4, s13, 1
	s_addk_i32 s4, 0xea00
	s_and_b32 s92, s4, 0xffffffc0
	s_lshl_b32 s4, s12, 5
	s_and_b32 s4, s4, 0xfffffc00
	s_sub_i32 s6, s3, s4
	s_add_i32 s4, s6, 0xfffea000
	s_ashr_i32 s5, s4, 31
	s_lshl_b64 s[4:5], s[4:5], 2
	s_add_u32 s4, s7, s4
	v_or_b32_e32 v8, s92, v3
	s_addc_u32 s5, s14, s5
	v_lshlrev_b32_e32 v0, 2, v2
	v_lshl_add_u64 v[6:7], s[4:5], 0, v[0:1]
	v_lshlrev_b32_e32 v0, 10, v8
	v_lshl_add_u64 v[6:7], v[0:1], 2, v[6:7]
	s_movk_i32 s4, 0x2000
	v_add_co_u32_e32 v8, vcc, s4, v6
	s_movk_i32 s4, 0x4000
	s_nop 0
	v_addc_co_u32_e32 v9, vcc, 0, v7, vcc
	global_load_dword v10, v[8:9], off
	v_add_co_u32_e32 v8, vcc, s4, v6
	s_movk_i32 s4, 0x6000
	s_nop 0
	v_addc_co_u32_e32 v9, vcc, 0, v7, vcc
	global_load_dword v11, v[8:9], off
	v_add_co_u32_e32 v8, vcc, s4, v6
	s_mov_b32 s4, 0x8000
	s_nop 0
	v_addc_co_u32_e32 v9, vcc, 0, v7, vcc
	global_load_dword v12, v[8:9], off
	v_add_co_u32_e32 v8, vcc, s4, v6
	s_mov_b32 s4, 0xa000
	s_nop 0
	v_addc_co_u32_e32 v9, vcc, 0, v7, vcc
	global_load_dword v13, v[8:9], off
	v_add_co_u32_e32 v8, vcc, s4, v6
	s_mov_b32 s4, 0xc000
	s_nop 0
	v_addc_co_u32_e32 v9, vcc, 0, v7, vcc
	global_load_dword v14, v[8:9], off
	v_add_co_u32_e32 v8, vcc, s4, v6
	s_mov_b32 s4, 0xe000
	s_nop 0
	v_addc_co_u32_e32 v9, vcc, 0, v7, vcc
	global_load_dword v15, v[8:9], off
	v_add_co_u32_e32 v8, vcc, s4, v6
	s_mov_b32 s4, 0x10000
	s_nop 0
	v_addc_co_u32_e32 v9, vcc, 0, v7, vcc
	global_load_dword v22, v[8:9], off
	v_add_co_u32_e32 v8, vcc, s4, v6
	s_mov_b32 s4, 0x12000
	s_nop 0
	v_addc_co_u32_e32 v9, vcc, 0, v7, vcc
	global_load_dword v23, v[8:9], off
	v_add_co_u32_e32 v8, vcc, s4, v6
	s_mov_b32 s4, 0x14000
	s_nop 0
	v_addc_co_u32_e32 v9, vcc, 0, v7, vcc
	global_load_dword v24, v[8:9], off
	v_add_co_u32_e32 v8, vcc, s4, v6
	s_mov_b32 s4, 0x16000
	s_nop 0
	v_addc_co_u32_e32 v9, vcc, 0, v7, vcc
	global_load_dword v25, v[8:9], off
	v_add_co_u32_e32 v8, vcc, s4, v6
	s_mov_b32 s4, 0x18000
	s_nop 0
	v_addc_co_u32_e32 v9, vcc, 0, v7, vcc
	global_load_dword v26, v[8:9], off
	v_add_co_u32_e32 v8, vcc, s4, v6
	s_mov_b32 s4, 0x1a000
	s_nop 0
	v_addc_co_u32_e32 v9, vcc, 0, v7, vcc
	global_load_dword v27, v[8:9], off
	v_add_co_u32_e32 v8, vcc, s4, v6
	s_mov_b32 s4, 0x1c000
	s_nop 0
	v_addc_co_u32_e32 v9, vcc, 0, v7, vcc
	global_load_dword v28, v[8:9], off
	v_add_co_u32_e32 v8, vcc, s4, v6
	s_mov_b32 s4, 0x1e000
	s_nop 0
	v_addc_co_u32_e32 v9, vcc, 0, v7, vcc
	global_load_dword v29, v[8:9], off
	v_add_co_u32_e32 v8, vcc, s4, v6
	s_mov_b32 s4, 0x20000
	s_nop 0
	v_addc_co_u32_e32 v9, vcc, 0, v7, vcc
	global_load_dword v30, v[8:9], off
	v_add_co_u32_e32 v8, vcc, s4, v6
	s_mov_b32 s4, 0x22000
	s_nop 0
	v_addc_co_u32_e32 v9, vcc, 0, v7, vcc
	global_load_dword v31, v[8:9], off
	v_add_co_u32_e32 v8, vcc, s4, v6
	s_mov_b32 s4, 0x24000
	s_nop 0
	v_addc_co_u32_e32 v9, vcc, 0, v7, vcc
	global_load_dword v32, v[8:9], off
	v_add_co_u32_e32 v8, vcc, s4, v6
	s_mov_b32 s4, 0x26000
	s_nop 0
	v_addc_co_u32_e32 v9, vcc, 0, v7, vcc
	global_load_dword v33, v[8:9], off
	v_add_co_u32_e32 v8, vcc, s4, v6
	s_mov_b32 s4, 0x28000
	s_nop 0
	v_addc_co_u32_e32 v9, vcc, 0, v7, vcc
	global_load_dword v34, v[8:9], off
	v_add_co_u32_e32 v8, vcc, s4, v6
	s_mov_b32 s4, 0x2a000
	s_nop 0
	v_addc_co_u32_e32 v9, vcc, 0, v7, vcc
	global_load_dword v35, v[8:9], off
	v_add_co_u32_e32 v8, vcc, s4, v6
	s_mov_b32 s4, 0x2c000
	s_nop 0
	v_addc_co_u32_e32 v9, vcc, 0, v7, vcc
	global_load_dword v36, v[8:9], off
	v_add_co_u32_e32 v8, vcc, s4, v6
	s_mov_b32 s4, 0x2e000
	s_nop 0
	v_addc_co_u32_e32 v9, vcc, 0, v7, vcc
	global_load_dword v37, v[8:9], off
	v_add_co_u32_e32 v8, vcc, s4, v6
	s_mov_b32 s4, 0x30000
	s_nop 0
	v_addc_co_u32_e32 v9, vcc, 0, v7, vcc
	global_load_dword v38, v[8:9], off
	v_add_co_u32_e32 v8, vcc, s4, v6
	s_mov_b32 s4, 0x32000
	s_nop 0
	v_addc_co_u32_e32 v9, vcc, 0, v7, vcc
	global_load_dword v39, v[8:9], off
	v_add_co_u32_e32 v8, vcc, s4, v6
	s_mov_b32 s4, 0x34000
	s_nop 0
	v_addc_co_u32_e32 v9, vcc, 0, v7, vcc
	global_load_dword v40, v[8:9], off
	v_add_co_u32_e32 v8, vcc, s4, v6
	s_mov_b32 s4, 0x36000
	s_nop 0
	v_addc_co_u32_e32 v9, vcc, 0, v7, vcc
	global_load_dword v41, v[8:9], off
	v_add_co_u32_e32 v8, vcc, s4, v6
	s_mov_b32 s4, 0x38000
	s_nop 0
	v_addc_co_u32_e32 v9, vcc, 0, v7, vcc
	global_load_dword v0, v[6:7], off
	global_load_dword v42, v[8:9], off
	v_add_co_u32_e32 v8, vcc, s4, v6
	s_mov_b32 s4, 0x3a000
	s_nop 0
	v_addc_co_u32_e32 v9, vcc, 0, v7, vcc
	global_load_dword v43, v[8:9], off
	v_add_co_u32_e32 v8, vcc, s4, v6
	s_mov_b32 s4, 0x3c000
	s_nop 0
	v_addc_co_u32_e32 v9, vcc, 0, v7, vcc
	global_load_dword v44, v[8:9], off
	v_add_co_u32_e32 v8, vcc, s4, v6
	s_mov_b32 s4, 0x3e000
	s_nop 0
	v_addc_co_u32_e32 v9, vcc, 0, v7, vcc
	v_add_co_u32_e32 v6, vcc, s4, v6
	global_load_dword v8, v[8:9], off
	s_nop 0
	v_addc_co_u32_e32 v7, vcc, 0, v7, vcc
	global_load_dword v6, v[6:7], off
	s_waitcnt vmcnt(0)
; __device__ __forceinline__ unsigned pk2(float lo, float hi) { f32x2_t v = {lo, hi}; bf16x2_t b = __builtin_convertvector(v, bf16x2_t); return __builtin_bit_cast(unsigned, b); }
; __device__ __forceinline__ void conv_item(const float* W, int K, int N, int kind, int item, const float* gain, unsigned char* Wb, float* scr, int lane) {
;     ...
;     for (int i = 0; i < 32; ++i) scr[(2 * i + (lane >> 5)) * 33 + (lane & 31)] = wv_[i];
;     __builtin_amdgcn_s_waitcnt(0); asm volatile("" ::: "memory");
;     const int c = lane & 7; float gg[8];
; #pragma unroll
;     for (int e = 0; e < 8; ++e) gg[e] = gain ? gain[k0 + 8 * c + e] : 1.0f;
; #pragma unroll
;     for (int j = 0; j < 4; ++j) { const int n = (lane >> 3) + 8 * j; const float* s = scr + (8 * c) * 33 + n;
;         u32x4 o; o.x = pk2(s[0] * gg[0], s[33] * gg[1]); o.y = pk2(s[2 * 33] * gg[2], s[3 * 33] * gg[3]); o.z = pk2(s[4 * 33] * gg[4], s[5 * 33] * gg[5]); o.w = pk2(s[6 * 33] * gg[6], s[7 * 33] * gg[7]);
;         *(u32x4*)(wdst(kind, n0 + n, Wb) + k0 + 8 * c) = o; }
;     __builtin_amdgcn_s_waitcnt(0); asm volatile("" ::: "memory");
	ds_write2_b32 v5, v0, v10 offset1:66
	ds_write2_b32 v5, v11, v12 offset0:132 offset1:198
	v_add_u32_e32 v0, 0x400, v5
	ds_write2_b32 v0, v13, v14 offset0:8 offset1:74
	ds_write2_b32 v0, v15, v22 offset0:140 offset1:206
	v_add_u32_e32 v0, 0x800, v5
	ds_write2_b32 v0, v23, v24 offset0:16 offset1:82
	ds_write2_b32 v0, v25, v26 offset0:148 offset1:214
	v_add_u32_e32 v0, 0xc00, v5
	ds_write2_b32 v0, v27, v28 offset0:24 offset1:90
	ds_write2_b32 v0, v29, v30 offset0:156 offset1:222
	v_add_u32_e32 v0, 0x1000, v5
	ds_write2_b32 v0, v31, v32 offset0:32 offset1:98
	ds_write2_b32 v0, v33, v34 offset0:164 offset1:230
	v_add_u32_e32 v0, 0x1400, v5
	ds_write2_b32 v0, v35, v36 offset0:40 offset1:106
	ds_write2_b32 v0, v37, v38 offset0:172 offset1:238
	v_add_u32_e32 v0, 0x1800, v5
	ds_write2_b32 v0, v39, v40 offset0:48 offset1:114
	ds_write2_b32 v0, v41, v42 offset0:180 offset1:246
	v_add_u32_e32 v0, 0x1c00, v5
	ds_write2_b32 v0, v43, v44 offset0:56 offset1:122
	ds_write2_b32 v0, v8, v6 offset0:188 offset1:254
	s_waitcnt vmcnt(0) expcnt(0) lgkmcnt(0)
	ds_read_b32 v0, v17
	ds_read_b32 v6, v17 offset:132
	v_mov_b64_e32 v[10:11], s[8:9]
	v_add_u32_e32 v22, s6, v21
	s_waitcnt lgkmcnt(0)
	v_cvt_pk_bf16_f32 v6, v0, v6
	ds_read_b32 v0, v17 offset:264
	ds_read_b32 v7, v17 offset:396
	s_waitcnt lgkmcnt(0)
	v_cvt_pk_bf16_f32 v7, v0, v7
	ds_read_b32 v0, v17 offset:528
	ds_read_b32 v8, v17 offset:660
	s_waitcnt lgkmcnt(0)
	v_cvt_pk_bf16_f32 v8, v0, v8
	ds_read_b32 v0, v17 offset:792
	ds_read_b32 v9, v17 offset:924
	s_waitcnt lgkmcnt(0)
	v_cvt_pk_bf16_f32 v9, v0, v9
	v_add_u32_e32 v0, s6, v18
	v_mad_i64_i32 v[12:13], s[4:5], v0, s64, v[10:11]
	s_lshl_b64 s[4:5], s[92:93], 1
	s_nop 0
	v_lshl_add_u64 v[12:13], v[12:13], 0, s[4:5]
	v_lshlrev_b32_e32 v0, 1, v4
	v_lshl_add_u64 v[12:13], v[12:13], 0, v[0:1]
	flat_store_dwordx4 v[12:13], v[6:9]
	ds_read_b32 v6, v17 offset:32
	ds_read_b32 v7, v17 offset:164
	s_waitcnt lgkmcnt(0)
	v_cvt_pk_bf16_f32 v6, v6, v7
	ds_read_b32 v7, v17 offset:296
	ds_read_b32 v8, v17 offset:428
	s_waitcnt lgkmcnt(0)
	v_cvt_pk_bf16_f32 v7, v7, v8
	ds_read_b32 v8, v17 offset:560
	ds_read_b32 v9, v17 offset:692
	s_waitcnt lgkmcnt(0)
	v_cvt_pk_bf16_f32 v8, v8, v9
	ds_read_b32 v9, v17 offset:824
	ds_read_b32 v12, v17 offset:956
	s_waitcnt lgkmcnt(0)
	v_cvt_pk_bf16_f32 v9, v9, v12
	v_add_u32_e32 v12, s6, v19
	v_mad_i64_i32 v[12:13], s[14:15], v12, s64, v[10:11]
	v_lshl_add_u64 v[12:13], v[12:13], 0, s[4:5]
	v_lshl_add_u64 v[12:13], v[12:13], 0, v[0:1]
	flat_store_dwordx4 v[12:13], v[6:9]
	ds_read_b32 v6, v17 offset:64
	ds_read_b32 v7, v17 offset:196
	s_waitcnt lgkmcnt(0)
	v_cvt_pk_bf16_f32 v6, v6, v7
	ds_read_b32 v7, v17 offset:328
	ds_read_b32 v8, v17 offset:460
	s_waitcnt lgkmcnt(0)
	v_cvt_pk_bf16_f32 v7, v7, v8
	ds_read_b32 v8, v17 offset:592
	ds_read_b32 v9, v17 offset:724
	s_waitcnt lgkmcnt(0)
	v_cvt_pk_bf16_f32 v8, v8, v9
	ds_read_b32 v9, v17 offset:856
	ds_read_b32 v12, v17 offset:988
	s_waitcnt lgkmcnt(0)
	v_cvt_pk_bf16_f32 v9, v9, v12
	v_add_u32_e32 v12, s6, v20
	v_mad_i64_i32 v[12:13], s[14:15], v12, s64, v[10:11]
	v_lshl_add_u64 v[12:13], v[12:13], 0, s[4:5]
	v_lshl_add_u64 v[12:13], v[12:13], 0, v[0:1]
	flat_store_dwordx4 v[12:13], v[6:9]
	ds_read_b32 v6, v17 offset:96
	ds_read_b32 v7, v17 offset:228
	ds_read_b32 v8, v17 offset:360
	ds_read_b32 v9, v17 offset:492
	ds_read_b32 v12, v17 offset:624
	ds_read_b32 v13, v17 offset:756
	ds_read_b32 v14, v17 offset:888
	ds_read_b32 v15, v17 offset:1020
	v_mad_i64_i32 v[10:11], s[6:7], v22, s64, v[10:11]
	v_lshl_add_u64 v[10:11], v[10:11], 0, s[4:5]
	s_waitcnt lgkmcnt(0)
	v_cvt_pk_bf16_f32 v6, v6, v7
	v_cvt_pk_bf16_f32 v7, v8, v9
	v_cvt_pk_bf16_f32 v8, v12, v13
	v_cvt_pk_bf16_f32 v9, v14, v15
	v_lshl_add_u64 v[10:11], v[10:11], 0, v[0:1]
	flat_store_dwordx4 v[10:11], v[6:9]
	s_waitcnt lgkmcnt(0)
	s_mov_b64 s[4:5], 0

; __device__ __forceinline__ unsigned pk2(float lo, float hi) { f32x2_t v = {lo, hi}; bf16x2_t b = __builtin_convertvector(v, bf16x2_t); return __builtin_bit_cast(unsigned, b); }
; __device__ __forceinline__ bf16_t* wdst(int kind, int n, unsigned char* Wb) {
;     ...
;     case 0: case 2: { const int up = n >= FF, j = up ? n - FF : n; const int row = 256 * (j >> 7) + (j & 127) + (up ? 128 : 0); return (bf16_t*)(Wb + (kind == 0 ? O_GU1 : O_GU2)) + (size_t)row * 1024; }
; __device__ __forceinline__ void conv_item(const float* W, int K, int N, int kind, int item, const float* gain, unsigned char* Wb, float* scr, int lane) {
;     ...
;     for (int j = 0; j < 4; ++j) { const int n = (lane >> 3) + 8 * j; const float* s = scr + (8 * c) * 33 + n;
;         u32x4 o; o.x = pk2(s[0] * gg[0], s[33] * gg[1]); o.y = pk2(s[2 * 33] * gg[2], s[3 * 33] * gg[3]); o.z = pk2(s[4 * 33] * gg[4], s[5 * 33] * gg[5]); o.w = pk2(s[6 * 33] * gg[6], s[7 * 33] * gg[7]);
;         *(u32x4*)(wdst(kind, n0 + n, Wb) + k0 + 8 * c) = o; }
;     __builtin_amdgcn_s_waitcnt(0); asm volatile("" ::: "memory");
.LBB0_1151:
	ds_read_b32 v14, v29
	ds_read_b32 v15, v29 offset:132
	ds_read_b32 v16, v29 offset:264
	ds_read_b32 v17, v29 offset:396
	ds_read_b32 v18, v29 offset:528
	ds_read_b32 v19, v29 offset:660
	ds_read_b32 v20, v29 offset:792
	ds_read_b32 v21, v29 offset:924
	v_add_u32_e32 v22, s16, v28
	s_movk_i32 s12, 0xaff
	s_waitcnt vmcnt(0) lgkmcnt(6)
	v_pk_mul_f32 v[14:15], v[6:7], v[14:15]
	s_waitcnt lgkmcnt(4)
	v_pk_mul_f32 v[16:17], v[8:9], v[16:17]
	v_add_u32_e32 v0, 0xfffff500, v22
	v_cmp_lt_i32_e32 vcc, s12, v22
	v_cvt_pk_bf16_f32 v14, v14, v15
	v_cvt_pk_bf16_f32 v15, v16, v17
	s_waitcnt lgkmcnt(2)
	v_pk_mul_f32 v[16:17], v[10:11], v[18:19]
	s_waitcnt lgkmcnt(0)
	v_pk_mul_f32 v[18:19], v[12:13], v[20:21]
	v_cndmask_b32_e32 v0, v22, v0, vcc
	v_cvt_pk_bf16_f32 v16, v16, v17
	v_cvt_pk_bf16_f32 v17, v18, v19
	v_lshlrev_b32_e32 v18, 1, v0
	v_and_b32_e32 v18, 0xffffff00, v18
	v_and_b32_e32 v0, 0x67, v0
	v_cndmask_b32_e32 v19, 0, v225, vcc
	v_or3_b32 v18, v0, v19, v18
	v_ashrrev_i32_e32 v19, 31, v18
	v_readlane_b32 s14, v254, 52
	s_ashr_i32 s7, s6, 31
	v_lshlrev_b64 v[18:19], 11, v[18:19]
	v_readlane_b32 s15, v254, 53
	s_lshl_b64 s[4:5], s[6:7], 1
	v_lshlrev_b32_e32 v0, 1, v4
	v_lshl_add_u64 v[18:19], s[14:15], 0, v[18:19]
	v_lshl_add_u64 v[18:19], v[18:19], 0, s[4:5]
	v_lshl_add_u64 v[18:19], v[18:19], 0, v[0:1]
	flat_store_dwordx4 v[18:19], v[14:17]
	ds_read_b32 v14, v29 offset:32
	ds_read_b32 v15, v29 offset:164
	ds_read_b32 v16, v29 offset:296
	ds_read_b32 v17, v29 offset:428
	ds_read_b32 v18, v29 offset:560
	ds_read_b32 v19, v29 offset:692
	ds_read_b32 v20, v29 offset:824
	ds_read_b32 v21, v29 offset:956
	s_waitcnt lgkmcnt(0)
	v_pk_mul_f32 v[14:15], v[6:7], v[14:15]
	v_pk_mul_f32 v[16:17], v[8:9], v[16:17]
	v_cvt_pk_bf16_f32 v14, v14, v15
	v_cvt_pk_bf16_f32 v15, v16, v17
	v_pk_mul_f32 v[16:17], v[10:11], v[18:19]
	v_pk_mul_f32 v[18:19], v[12:13], v[20:21]
	v_cvt_pk_bf16_f32 v16, v16, v17
	v_cvt_pk_bf16_f32 v17, v18, v19
	v_add_u32_e32 v18, 8, v22
	v_add_u32_e32 v19, 0xfffff508, v22
	v_cmp_lt_i32_e32 vcc, s12, v18
	v_add_u32_e32 v23, 24, v22
	s_nop 0
	v_cndmask_b32_e32 v18, v18, v19, vcc
	v_lshlrev_b32_e32 v19, 1, v18
	v_and_b32_e32 v19, 0xffffff00, v19
	v_and_b32_e32 v18, 0x6f, v18
	v_cndmask_b32_e32 v20, 0, v225, vcc
	v_or3_b32 v18, v18, v20, v19
	v_ashrrev_i32_e32 v19, 31, v18
	v_lshlrev_b64 v[18:19], 11, v[18:19]
	v_lshl_add_u64 v[18:19], s[14:15], 0, v[18:19]
	v_lshl_add_u64 v[18:19], v[18:19], 0, s[4:5]
	v_lshl_add_u64 v[18:19], v[18:19], 0, v[0:1]
	flat_store_dwordx4 v[18:19], v[14:17]
	ds_read_b32 v14, v29 offset:64
	ds_read_b32 v15, v29 offset:196
	ds_read_b32 v16, v29 offset:328
	ds_read_b32 v17, v29 offset:460
	ds_read_b32 v18, v29 offset:592
	ds_read_b32 v19, v29 offset:724
	ds_read_b32 v20, v29 offset:856
	ds_read_b32 v21, v29 offset:988
	s_waitcnt lgkmcnt(0)
	v_pk_mul_f32 v[14:15], v[6:7], v[14:15]
	v_pk_mul_f32 v[16:17], v[8:9], v[16:17]
	v_cvt_pk_bf16_f32 v14, v14, v15
	v_cvt_pk_bf16_f32 v15, v16, v17
	v_pk_mul_f32 v[16:17], v[10:11], v[18:19]
	v_pk_mul_f32 v[18:19], v[12:13], v[20:21]
	v_cvt_pk_bf16_f32 v16, v16, v17
	v_cvt_pk_bf16_f32 v17, v18, v19
	v_add_u32_e32 v18, 16, v22
	v_add_u32_e32 v19, 0xfffff510, v22
	v_cmp_lt_i32_e32 vcc, s12, v18
	v_add_u32_e32 v22, 0xfffff518, v22
	s_nop 0
	v_cndmask_b32_e32 v18, v18, v19, vcc
	v_lshlrev_b32_e32 v19, 1, v18
	v_and_b32_e32 v19, 0xffffff00, v19
	v_and_b32_e32 v18, 0x77, v18
	v_cndmask_b32_e32 v20, 0, v225, vcc
	v_or3_b32 v18, v18, v20, v19
	v_ashrrev_i32_e32 v19, 31, v18
	v_lshlrev_b64 v[18:19], 11, v[18:19]
	v_lshl_add_u64 v[18:19], s[14:15], 0, v[18:19]
	v_lshl_add_u64 v[18:19], v[18:19], 0, s[4:5]
	v_lshl_add_u64 v[18:19], v[18:19], 0, v[0:1]
	v_cmp_lt_i32_e32 vcc, s12, v23
	flat_store_dwordx4 v[18:19], v[14:17]
	ds_read_b32 v14, v29 offset:96
	ds_read_b32 v15, v29 offset:228
	ds_read_b32 v16, v29 offset:360
	ds_read_b32 v17, v29 offset:492
	ds_read_b32 v18, v29 offset:624
	ds_read_b32 v19, v29 offset:756
	ds_read_b32 v20, v29 offset:888
	ds_read_b32 v21, v29 offset:1020
	v_cndmask_b32_e32 v22, v23, v22, vcc
	v_lshlrev_b32_e32 v23, 1, v22
	v_and_b32_e32 v23, 0xffffff00, v23
	v_and_b32_e32 v22, 0x7f, v22
	v_cndmask_b32_e32 v24, 0, v225, vcc
	v_or3_b32 v22, v22, v24, v23
	v_ashrrev_i32_e32 v23, 31, v22
	v_lshlrev_b64 v[22:23], 11, v[22:23]
	s_waitcnt lgkmcnt(0)
	v_pk_mul_f32 v[6:7], v[6:7], v[14:15]
	v_pk_mul_f32 v[8:9], v[8:9], v[16:17]
	v_lshl_add_u64 v[22:23], s[14:15], 0, v[22:23]
	v_cvt_pk_bf16_f32 v6, v6, v7
	v_cvt_pk_bf16_f32 v7, v8, v9
	v_pk_mul_f32 v[8:9], v[10:11], v[18:19]
	v_pk_mul_f32 v[10:11], v[12:13], v[20:21]
	v_cvt_pk_bf16_f32 v8, v8, v9
	v_cvt_pk_bf16_f32 v9, v10, v11
	v_lshl_add_u64 v[10:11], v[22:23], 0, s[4:5]
	v_lshl_add_u64 v[10:11], v[10:11], 0, v[0:1]
	flat_store_dwordx4 v[10:11], v[6:9]
	s_waitcnt lgkmcnt(0)

; __device__ __forceinline__ unsigned pk2(float lo, float hi) { f32x2_t v = {lo, hi}; bf16x2_t b = __builtin_convertvector(v, bf16x2_t); return __builtin_bit_cast(unsigned, b); }
; __device__ __forceinline__ bf16_t* wdst(int kind, int n, unsigned char* Wb) {
;     ...
;     case 6: { const int hd = n >> 7, d = n & 127; return d < 64 ? (bf16_t*)(Wb + O_WUK) + (size_t)(hd * 64 + d) * 128 : (bf16_t*)(Wb + O_WUV) + (size_t)(hd * 64 + d - 64) * 128; }
; __device__ __forceinline__ void conv_item(const float* W, int K, int N, int kind, int item, const float* gain, unsigned char* Wb, float* scr, int lane) {
;     ...
;     for (int j = 0; j < 4; ++j) { const int n = (lane >> 3) + 8 * j; const float* s = scr + (8 * c) * 33 + n;
;         u32x4 o; o.x = pk2(s[0] * gg[0], s[33] * gg[1]); o.y = pk2(s[2 * 33] * gg[2], s[3 * 33] * gg[3]); o.z = pk2(s[4 * 33] * gg[4], s[5 * 33] * gg[5]); o.w = pk2(s[6 * 33] * gg[6], s[7 * 33] * gg[7]);
;         *(u32x4*)(wdst(kind, n0 + n, Wb) + k0 + 8 * c) = o; }
;     __builtin_amdgcn_s_waitcnt(0); asm volatile("" ::: "memory");
.LBB0_1179:
	ds_read_b32 v14, v29
	ds_read_b32 v15, v29 offset:132
	ds_read_b32 v16, v29 offset:264
	ds_read_b32 v17, v29 offset:396
	ds_read_b32 v18, v29 offset:528
	ds_read_b32 v19, v29 offset:660
	ds_read_b32 v20, v29 offset:792
	ds_read_b32 v21, v29 offset:924
	s_lshl_b32 s4, s13, 4
	s_and_b32 s7, s4, 0xffffffc0
	s_sub_i32 s13, s7, 64
	s_waitcnt vmcnt(0) lgkmcnt(6)
	v_pk_mul_f32 v[14:15], v[6:7], v[14:15]
	s_waitcnt lgkmcnt(4)
	v_pk_mul_f32 v[16:17], v[8:9], v[16:17]
	s_and_b32 s6, s6, 0x60
	v_cvt_pk_bf16_f32 v14, v14, v15
	v_cvt_pk_bf16_f32 v15, v16, v17
	s_waitcnt lgkmcnt(2)
	v_pk_mul_f32 v[16:17], v[10:11], v[18:19]
	s_waitcnt lgkmcnt(0)
	v_pk_mul_f32 v[18:19], v[12:13], v[20:21]
	v_or_b32_e32 v0, s6, v28
	s_cmp_lt_u32 s6, 64
	v_cvt_pk_bf16_f32 v16, v16, v17
	v_cvt_pk_bf16_f32 v17, v18, v19
	v_add_u32_e32 v18, s13, v0
	v_or_b32_e32 v0, s7, v0
	s_cselect_b64 vcc, -1, 0
	v_cndmask_b32_e32 v18, v18, v0, vcc
	s_and_b64 s[4:5], vcc, exec
	v_readlane_b32 s4, v254, 60
	v_ashrrev_i32_e32 v19, 31, v18
	s_cselect_b32 s5, s3, s24
	s_cselect_b32 s4, s25, s4
	v_lshlrev_b64 v[18:19], 8, v[18:19]
	v_lshl_add_u64 v[18:19], s[4:5], 0, v[18:19]
	s_lshl_b32 s92, s12, 1
	v_lshl_add_u64 v[18:19], v[18:19], 0, s[92:93]
	v_lshlrev_b32_e32 v0, 1, v4
	v_lshl_add_u64 v[18:19], v[18:19], 0, v[0:1]
	flat_store_dwordx4 v[18:19], v[14:17]
	ds_read_b32 v14, v29 offset:32
	ds_read_b32 v15, v29 offset:164
	ds_read_b32 v16, v29 offset:296
	ds_read_b32 v17, v29 offset:428
	ds_read_b32 v18, v29 offset:560
	ds_read_b32 v19, v29 offset:692
	ds_read_b32 v20, v29 offset:824
	ds_read_b32 v21, v29 offset:956
	s_waitcnt lgkmcnt(0)
	v_pk_mul_f32 v[14:15], v[6:7], v[14:15]
	v_pk_mul_f32 v[16:17], v[8:9], v[16:17]
	v_cvt_pk_bf16_f32 v14, v14, v15
	v_cvt_pk_bf16_f32 v15, v16, v17
	v_pk_mul_f32 v[16:17], v[10:11], v[18:19]
	v_pk_mul_f32 v[18:19], v[12:13], v[20:21]
	v_cvt_pk_bf16_f32 v16, v16, v17
	v_cvt_pk_bf16_f32 v17, v18, v19
	v_or_b32_e32 v18, s6, v30
	v_or_b32_e32 v19, s7, v18
	v_add_u32_e32 v18, s13, v18
	v_cndmask_b32_e32 v18, v18, v19, vcc
	v_ashrrev_i32_e32 v19, 31, v18
	v_lshlrev_b64 v[18:19], 8, v[18:19]
	v_lshl_add_u64 v[18:19], s[4:5], 0, v[18:19]
	v_lshl_add_u64 v[18:19], v[18:19], 0, s[92:93]
	v_lshl_add_u64 v[18:19], v[18:19], 0, v[0:1]
	flat_store_dwordx4 v[18:19], v[14:17]
	ds_read_b32 v14, v29 offset:64
	ds_read_b32 v15, v29 offset:196
	ds_read_b32 v16, v29 offset:328
	ds_read_b32 v17, v29 offset:460
	ds_read_b32 v18, v29 offset:592
	ds_read_b32 v19, v29 offset:724
	ds_read_b32 v20, v29 offset:856
	ds_read_b32 v21, v29 offset:988
	s_waitcnt lgkmcnt(0)
	v_pk_mul_f32 v[14:15], v[6:7], v[14:15]
	v_pk_mul_f32 v[16:17], v[8:9], v[16:17]
	v_cvt_pk_bf16_f32 v14, v14, v15
	v_cvt_pk_bf16_f32 v15, v16, v17
	v_pk_mul_f32 v[16:17], v[10:11], v[18:19]
	v_pk_mul_f32 v[18:19], v[12:13], v[20:21]
	v_cvt_pk_bf16_f32 v16, v16, v17
	v_cvt_pk_bf16_f32 v17, v18, v19
	v_or_b32_e32 v18, s6, v31
	v_or_b32_e32 v19, s7, v18
	v_add_u32_e32 v18, s13, v18
	v_cndmask_b32_e32 v18, v18, v19, vcc
	v_ashrrev_i32_e32 v19, 31, v18
	v_lshlrev_b64 v[18:19], 8, v[18:19]
	v_lshl_add_u64 v[18:19], s[4:5], 0, v[18:19]
	v_lshl_add_u64 v[18:19], v[18:19], 0, s[92:93]
	v_lshl_add_u64 v[18:19], v[18:19], 0, v[0:1]
	flat_store_dwordx4 v[18:19], v[14:17]
	ds_read_b32 v14, v29 offset:96
	ds_read_b32 v15, v29 offset:228
	ds_read_b32 v16, v29 offset:360
	ds_read_b32 v17, v29 offset:492
	ds_read_b32 v18, v29 offset:624
	ds_read_b32 v19, v29 offset:756
	ds_read_b32 v20, v29 offset:888
	ds_read_b32 v21, v29 offset:1020
	v_or_b32_e32 v22, s6, v32
	v_add_u32_e32 v23, s13, v22
	v_or_b32_e32 v22, s7, v22
	v_cndmask_b32_e32 v22, v23, v22, vcc
	v_ashrrev_i32_e32 v23, 31, v22
	v_lshlrev_b64 v[22:23], 8, v[22:23]
	s_waitcnt lgkmcnt(0)
	v_pk_mul_f32 v[6:7], v[6:7], v[14:15]
	v_pk_mul_f32 v[8:9], v[8:9], v[16:17]
	v_lshl_add_u64 v[22:23], s[4:5], 0, v[22:23]
	v_cvt_pk_bf16_f32 v6, v6, v7
	v_cvt_pk_bf16_f32 v7, v8, v9
	v_pk_mul_f32 v[8:9], v[10:11], v[18:19]
	v_pk_mul_f32 v[10:11], v[12:13], v[20:21]
	v_cvt_pk_bf16_f32 v8, v8, v9
	v_cvt_pk_bf16_f32 v9, v10, v11
	v_lshl_add_u64 v[10:11], v[22:23], 0, s[92:93]
	v_lshl_add_u64 v[10:11], v[10:11], 0, v[0:1]
	flat_store_dwordx4 v[10:11], v[6:9]
	s_waitcnt lgkmcnt(0)
	s_mov_b64 s[4:5], 0

; __device__ __forceinline__ unsigned pk2(float lo, float hi) { f32x2_t v = {lo, hi}; bf16x2_t b = __builtin_convertvector(v, bf16x2_t); return __builtin_bit_cast(unsigned, b); }
; __device__ __forceinline__ bf16_t* wdst(int kind, int n, unsigned char* Wb) {
;     ...
;     case 5: { const int hd = n / 96, d = n - hd * 96; int row = n; if (d >= 64) { const int c = d - 64; row = hd * 96 + 64 + 2 * (c & 15) + (c >> 4); } return (bf16_t*)(Wb + O_WUQ) + (size_t)row * 256; }
; __device__ __forceinline__ void conv_item(const float* W, int K, int N, int kind, int item, const float* gain, unsigned char* Wb, float* scr, int lane) {
;     ...
;     for (int j = 0; j < 4; ++j) { const int n = (lane >> 3) + 8 * j; const float* s = scr + (8 * c) * 33 + n;
;         u32x4 o; o.x = pk2(s[0] * gg[0], s[33] * gg[1]); o.y = pk2(s[2 * 33] * gg[2], s[3 * 33] * gg[3]); o.z = pk2(s[4 * 33] * gg[4], s[5 * 33] * gg[5]); o.w = pk2(s[6 * 33] * gg[6], s[7 * 33] * gg[7]);
;         *(u32x4*)(wdst(kind, n0 + n, Wb) + k0 + 8 * c) = o; }
;     __builtin_amdgcn_s_waitcnt(0); asm volatile("" ::: "memory");
.LBB0_1197:
	s_mulk_i32 s14, 0xffe8
	s_add_i32 s4, s82, s14
	s_lshl_b32 s6, s4, 5
	ds_read2_b32 v[22:23], v29 offset1:33
	ds_read2_b32 v[20:21], v29 offset0:66 offset1:99
	ds_read2_b32 v[18:19], v29 offset0:132 offset1:165
	ds_read2_b32 v[14:15], v29 offset0:198 offset1:231
	v_add_u32_e32 v16, s12, v47
	s_mov_b32 s4, 0x2aaaaaab
	v_mul_hi_i32 v0, v16, s4
	v_lshrrev_b32_e32 v17, 31, v0
	v_lshrrev_b32_e32 v0, 4, v0
	v_add_u32_e32 v0, v0, v17
	s_movk_i32 s4, 0x60
	v_mul_lo_u32 v0, v0, s4
	v_sub_u32_e32 v0, v16, v0
	s_add_i32 s6, s6, 0xfff9d600
	v_cmp_lt_i32_e32 vcc, 63, v0
	s_and_saveexec_b64 s[4:5], vcc
	v_or_b32_e32 v16, s6, v28
	v_lshlrev_b32_e32 v24, 1, v0
	v_subrev_u32_e32 v17, 64, v0
	v_and_b32_e32 v24, 14, v24
	v_sub_u32_e32 v0, v16, v0
	v_lshrrev_b32_e32 v17, 4, v17
	v_add_u32_e32 v0, v0, v24
	v_add3_u32 v16, v0, v17, 64
	s_or_b64 exec, exec, s[4:5]
	s_waitcnt vmcnt(0) lgkmcnt(0)
	v_pk_mul_f32 v[14:15], v[12:13], v[14:15]
	v_ashrrev_i32_e32 v17, 31, v16
	v_cvt_pk_bf16_f32 v25, v14, v15
	v_lshlrev_b64 v[14:15], 9, v[16:17]
	v_lshl_add_u64 v[14:15], s[44:45], 0, v[14:15]
	s_lshl_b32 s92, s13, 1
	v_pk_mul_f32 v[22:23], v[6:7], v[22:23]
	v_pk_mul_f32 v[20:21], v[8:9], v[20:21]
	v_pk_mul_f32 v[18:19], v[10:11], v[18:19]
	v_lshl_add_u64 v[14:15], v[14:15], 0, s[92:93]
	v_lshlrev_b32_e32 v0, 1, v4
	v_cvt_pk_bf16_f32 v22, v22, v23
	v_cvt_pk_bf16_f32 v23, v20, v21
	v_cvt_pk_bf16_f32 v24, v18, v19
	v_lshl_add_u64 v[14:15], v[14:15], 0, v[0:1]
	flat_store_dwordx4 v[14:15], v[22:25]
	ds_read2_b32 v[22:23], v29 offset0:8 offset1:41
	ds_read2_b32 v[18:19], v29 offset0:74 offset1:107
	ds_read2_b32 v[16:17], v29 offset0:140 offset1:173
	ds_read2_b32 v[14:15], v29 offset0:206 offset1:239
	v_add_u32_e32 v20, s12, v46
	s_mov_b32 s4, 0x2aaaaaab
	v_mul_hi_i32 v21, v20, s4
	v_lshrrev_b32_e32 v24, 31, v21
	v_lshrrev_b32_e32 v21, 4, v21
	v_add_u32_e32 v21, v21, v24
	s_movk_i32 s4, 0x60
	v_mul_lo_u32 v21, v21, s4
	v_sub_u32_e32 v21, v20, v21
	v_cmp_lt_i32_e32 vcc, 63, v21
	s_and_saveexec_b64 s[4:5], vcc
	v_or_b32_e32 v20, s6, v30
	v_lshlrev_b32_e32 v25, 1, v21
	v_subrev_u32_e32 v24, 64, v21
	v_and_b32_e32 v25, 30, v25
	v_sub_u32_e32 v20, v20, v21
	v_lshrrev_b32_e32 v24, 4, v24
	v_add_u32_e32 v20, v20, v25
	v_add3_u32 v20, v20, v24, 64
	s_or_b64 exec, exec, s[4:5]
	s_waitcnt lgkmcnt(0)
	v_pk_mul_f32 v[14:15], v[12:13], v[14:15]
	v_ashrrev_i32_e32 v21, 31, v20
	v_cvt_pk_bf16_f32 v25, v14, v15
	v_lshlrev_b64 v[14:15], 9, v[20:21]
	v_lshl_add_u64 v[14:15], s[44:45], 0, v[14:15]
	v_pk_mul_f32 v[22:23], v[6:7], v[22:23]
	v_pk_mul_f32 v[18:19], v[8:9], v[18:19]
	v_pk_mul_f32 v[16:17], v[10:11], v[16:17]
	v_lshl_add_u64 v[14:15], v[14:15], 0, s[92:93]
	v_cvt_pk_bf16_f32 v22, v22, v23
	v_cvt_pk_bf16_f32 v23, v18, v19
	v_cvt_pk_bf16_f32 v24, v16, v17
	v_lshl_add_u64 v[14:15], v[14:15], 0, v[0:1]
	flat_store_dwordx4 v[14:15], v[22:25]
	ds_read2_b32 v[22:23], v29 offset0:16 offset1:49
	ds_read2_b32 v[18:19], v29 offset0:82 offset1:115
	ds_read2_b32 v[16:17], v29 offset0:148 offset1:181
	ds_read2_b32 v[14:15], v29 offset0:214 offset1:247
	v_add_u32_e32 v20, s12, v45
	s_mov_b32 s4, 0x2aaaaaab
	v_mul_hi_i32 v21, v20, s4
	v_lshrrev_b32_e32 v24, 31, v21
	v_lshrrev_b32_e32 v21, 4, v21
	v_add_u32_e32 v21, v21, v24
	s_movk_i32 s4, 0x60
	v_mul_lo_u32 v21, v21, s4
	v_sub_u32_e32 v21, v20, v21
	v_cmp_lt_i32_e32 vcc, 63, v21
	s_and_saveexec_b64 s[4:5], vcc
	v_or_b32_e32 v20, s6, v31
	v_lshlrev_b32_e32 v25, 1, v21
	v_subrev_u32_e32 v24, 64, v21
	v_and_b32_e32 v25, 14, v25
	v_sub_u32_e32 v20, v20, v21
	v_lshrrev_b32_e32 v24, 4, v24
	v_add_u32_e32 v20, v20, v25
	v_add3_u32 v20, v20, v24, 64
	s_or_b64 exec, exec, s[4:5]
	s_waitcnt lgkmcnt(0)
	v_pk_mul_f32 v[14:15], v[12:13], v[14:15]
	v_ashrrev_i32_e32 v21, 31, v20
	v_cvt_pk_bf16_f32 v25, v14, v15
	v_lshlrev_b64 v[14:15], 9, v[20:21]
	v_lshl_add_u64 v[14:15], s[44:45], 0, v[14:15]
	v_pk_mul_f32 v[22:23], v[6:7], v[22:23]
	v_pk_mul_f32 v[18:19], v[8:9], v[18:19]
	v_pk_mul_f32 v[16:17], v[10:11], v[16:17]
	v_lshl_add_u64 v[14:15], v[14:15], 0, s[92:93]
	v_cvt_pk_bf16_f32 v22, v22, v23
	v_cvt_pk_bf16_f32 v23, v18, v19
	v_cvt_pk_bf16_f32 v24, v16, v17
	v_lshl_add_u64 v[14:15], v[14:15], 0, v[0:1]
	flat_store_dwordx4 v[14:15], v[22:25]
	ds_read2_b32 v[20:21], v29 offset0:24 offset1:57
	ds_read2_b32 v[18:19], v29 offset0:90 offset1:123
	ds_read2_b32 v[16:17], v29 offset0:156 offset1:189
	ds_read2_b32 v[14:15], v29 offset0:222 offset1:255
	v_add_u32_e32 v22, s12, v44
	s_mov_b32 s4, 0x2aaaaaab
	v_mul_hi_i32 v23, v22, s4
	v_lshrrev_b32_e32 v24, 31, v23
	v_lshrrev_b32_e32 v23, 4, v23
	v_add_u32_e32 v23, v23, v24
	s_movk_i32 s4, 0x60
	v_mul_lo_u32 v23, v23, s4
	v_sub_u32_e32 v23, v22, v23
	v_cmp_lt_i32_e32 vcc, 63, v23
	s_and_saveexec_b64 s[4:5], vcc
	v_or_b32_e32 v22, s6, v32
	v_lshlrev_b32_e32 v25, 1, v23
	v_subrev_u32_e32 v24, 64, v23
	v_and_b32_e32 v25, 30, v25
	v_sub_u32_e32 v22, v22, v23
	v_lshrrev_b32_e32 v24, 4, v24
	v_add_u32_e32 v22, v22, v25
	v_add3_u32 v22, v22, v24, 64
	s_or_b64 exec, exec, s[4:5]
	v_ashrrev_i32_e32 v23, 31, v22
	v_lshlrev_b64 v[22:23], 9, v[22:23]
	s_waitcnt lgkmcnt(0)
	v_pk_mul_f32 v[6:7], v[6:7], v[20:21]
	v_pk_mul_f32 v[8:9], v[8:9], v[18:19]
	v_lshl_add_u64 v[22:23], s[44:45], 0, v[22:23]
	v_cvt_pk_bf16_f32 v6, v6, v7
	v_cvt_pk_bf16_f32 v7, v8, v9
	v_pk_mul_f32 v[8:9], v[10:11], v[16:17]
	v_pk_mul_f32 v[10:11], v[12:13], v[14:15]
	v_cvt_pk_bf16_f32 v8, v8, v9
	v_cvt_pk_bf16_f32 v9, v10, v11
	v_lshl_add_u64 v[10:11], v[22:23], 0, s[92:93]
	v_lshl_add_u64 v[10:11], v[10:11], 0, v[0:1]
	flat_store_dwordx4 v[10:11], v[6:9]
	s_waitcnt lgkmcnt(0)

; __device__ __forceinline__ void conv_item(const float* W, int K, int N, int kind, int item, const float* gain, unsigned char* Wb, float* scr, int lane) {
;     const int nblk = N / 32, kb = item / nblk, nb = item - kb * nblk, k0 = 64 * kb, n0 = 32 * nb;
;     float wv_[32];
; #pragma unroll
;     for (int i = 0; i < 32; ++i) wv_[i] = W[(size_t)(k0 + 2 * i + (lane >> 5)) * N + n0 + (lane & 31)];
; #pragma unroll
;     for (int i = 0; i < 32; ++i) scr[(2 * i + (lane >> 5)) * 33 + (lane & 31)] = wv_[i];
;     __builtin_amdgcn_s_waitcnt(0); asm volatile("" ::: "memory");
.LBB0_1207:
	s_andn2_b64 vcc, exec, s[4:5]
	s_cbranch_vccnz .LBB0_1209
	s_lshl_b32 s4, s76, 5
	s_and_b32 s6, s4, 0xfffffc00
	v_readlane_b32 s4, v254, 40
	v_readlane_b32 s5, v254, 41
	s_load_dwordx2 s[4:5], s[4:5], 0x78
	s_lshl_b32 s7, s73, 1
	v_lshlrev_b32_e32 v0, 2, v2
	s_waitcnt lgkmcnt(0)
	s_add_u32 s12, s4, s46
	s_addc_u32 s13, s5, s47
	s_add_i32 s4, s7, 0x2c0
	s_and_b32 s92, s4, 0xffffffc0
	s_sub_i32 s4, s75, s6
	s_add_i32 s4, s4, 0xfff9f600
	s_ashr_i32 s5, s4, 31
	s_lshl_b64 s[6:7], s[4:5], 2
	s_add_u32 s6, s12, s6
	v_or_b32_e32 v8, s92, v3
	s_addc_u32 s7, s13, s7
	v_lshl_add_u64 v[6:7], s[6:7], 0, v[0:1]
	v_lshlrev_b32_e32 v0, 10, v8
	v_lshl_add_u64 v[6:7], v[0:1], 2, v[6:7]
	s_movk_i32 s5, 0x2000
	v_add_co_u32_e32 v8, vcc, s5, v6
	s_movk_i32 s5, 0x4000
	s_nop 0
	v_addc_co_u32_e32 v9, vcc, 0, v7, vcc
	global_load_dword v0, v[6:7], off
	global_load_dword v10, v[8:9], off
	v_add_co_u32_e32 v8, vcc, s5, v6
	s_movk_i32 s5, 0x6000
	s_nop 0
	v_addc_co_u32_e32 v9, vcc, 0, v7, vcc
	global_load_dword v11, v[8:9], off
	v_add_co_u32_e32 v8, vcc, s5, v6
	s_mov_b32 s5, 0x8000
	s_nop 0
	v_addc_co_u32_e32 v9, vcc, 0, v7, vcc
	global_load_dword v12, v[8:9], off
	v_add_co_u32_e32 v8, vcc, s5, v6
	s_mov_b32 s5, 0xa000
	s_nop 0
	v_addc_co_u32_e32 v9, vcc, 0, v7, vcc
	global_load_dword v13, v[8:9], off
	v_add_co_u32_e32 v8, vcc, s5, v6
	s_mov_b32 s5, 0xc000
	s_nop 0
	v_addc_co_u32_e32 v9, vcc, 0, v7, vcc
	global_load_dword v14, v[8:9], off
	v_add_co_u32_e32 v8, vcc, s5, v6
	s_mov_b32 s5, 0xe000
	s_nop 0
	v_addc_co_u32_e32 v9, vcc, 0, v7, vcc
	global_load_dword v15, v[8:9], off
	v_add_co_u32_e32 v8, vcc, s5, v6
	s_mov_b32 s5, 0x10000
	s_nop 0
	v_addc_co_u32_e32 v9, vcc, 0, v7, vcc
	global_load_dword v16, v[8:9], off
	v_add_co_u32_e32 v8, vcc, s5, v6
	s_mov_b32 s5, 0x12000
	s_nop 0
	v_addc_co_u32_e32 v9, vcc, 0, v7, vcc
	global_load_dword v17, v[8:9], off
	v_add_co_u32_e32 v8, vcc, s5, v6
	s_mov_b32 s5, 0x14000
	s_nop 0
	v_addc_co_u32_e32 v9, vcc, 0, v7, vcc
	global_load_dword v18, v[8:9], off
	v_add_co_u32_e32 v8, vcc, s5, v6
	s_mov_b32 s5, 0x16000
	s_nop 0
	v_addc_co_u32_e32 v9, vcc, 0, v7, vcc
	global_load_dword v19, v[8:9], off
	v_add_co_u32_e32 v8, vcc, s5, v6
	s_mov_b32 s5, 0x18000
	s_nop 0
	v_addc_co_u32_e32 v9, vcc, 0, v7, vcc
	global_load_dword v20, v[8:9], off
	v_add_co_u32_e32 v8, vcc, s5, v6
	s_mov_b32 s5, 0x1a000
	s_nop 0
	v_addc_co_u32_e32 v9, vcc, 0, v7, vcc
	global_load_dword v21, v[8:9], off
	v_add_co_u32_e32 v8, vcc, s5, v6
	s_mov_b32 s5, 0x1c000
	s_nop 0
	v_addc_co_u32_e32 v9, vcc, 0, v7, vcc
	global_load_dword v22, v[8:9], off
	v_add_co_u32_e32 v8, vcc, s5, v6
	s_mov_b32 s5, 0x1e000
	s_nop 0
	v_addc_co_u32_e32 v9, vcc, 0, v7, vcc
	global_load_dword v23, v[8:9], off
	v_add_co_u32_e32 v8, vcc, s5, v6
	s_mov_b32 s5, 0x20000
	s_nop 0
	v_addc_co_u32_e32 v9, vcc, 0, v7, vcc
	global_load_dword v24, v[8:9], off
	v_add_co_u32_e32 v8, vcc, s5, v6
	s_mov_b32 s5, 0x22000
	s_nop 0
	v_addc_co_u32_e32 v9, vcc, 0, v7, vcc
	global_load_dword v25, v[8:9], off
	v_add_co_u32_e32 v8, vcc, s5, v6
	s_mov_b32 s5, 0x24000
	s_nop 0
	v_addc_co_u32_e32 v9, vcc, 0, v7, vcc
	global_load_dword v26, v[8:9], off
	v_add_co_u32_e32 v8, vcc, s5, v6
	s_mov_b32 s5, 0x26000
	s_nop 0
	v_addc_co_u32_e32 v9, vcc, 0, v7, vcc
	global_load_dword v27, v[8:9], off
	v_add_co_u32_e32 v8, vcc, s5, v6
	s_mov_b32 s5, 0x28000
	s_nop 0
	v_addc_co_u32_e32 v9, vcc, 0, v7, vcc
	global_load_dword v103, v[8:9], off
	v_add_co_u32_e32 v8, vcc, s5, v6
	s_mov_b32 s5, 0x2a000
	s_nop 0
	v_addc_co_u32_e32 v9, vcc, 0, v7, vcc
	global_load_dword v104, v[8:9], off
	v_add_co_u32_e32 v8, vcc, s5, v6
	s_mov_b32 s5, 0x2c000
	s_nop 0
	v_addc_co_u32_e32 v9, vcc, 0, v7, vcc
	global_load_dword v105, v[8:9], off
	v_add_co_u32_e32 v8, vcc, s5, v6
	s_mov_b32 s5, 0x2e000
	s_nop 0
	v_addc_co_u32_e32 v9, vcc, 0, v7, vcc
	global_load_dword v106, v[8:9], off
	v_add_co_u32_e32 v8, vcc, s5, v6
	s_mov_b32 s5, 0x30000
	s_nop 0
	v_addc_co_u32_e32 v9, vcc, 0, v7, vcc
	global_load_dword v107, v[8:9], off
	v_add_co_u32_e32 v8, vcc, s5, v6
	s_mov_b32 s5, 0x32000
	s_nop 0
	v_addc_co_u32_e32 v9, vcc, 0, v7, vcc
	global_load_dword v108, v[8:9], off
	v_add_co_u32_e32 v8, vcc, s5, v6
	s_mov_b32 s5, 0x34000
	s_nop 0
	v_addc_co_u32_e32 v9, vcc, 0, v7, vcc
	global_load_dword v109, v[8:9], off
	v_add_co_u32_e32 v8, vcc, s5, v6
	s_mov_b32 s5, 0x36000
	s_nop 0
	v_addc_co_u32_e32 v9, vcc, 0, v7, vcc
	global_load_dword v110, v[8:9], off
	v_add_co_u32_e32 v8, vcc, s5, v6
	s_mov_b32 s5, 0x38000
	s_nop 0
	v_addc_co_u32_e32 v9, vcc, 0, v7, vcc
	global_load_dword v111, v[8:9], off
	v_add_co_u32_e32 v8, vcc, s5, v6
	s_mov_b32 s5, 0x3a000
	s_nop 0
	v_addc_co_u32_e32 v9, vcc, 0, v7, vcc
	global_load_dword v112, v[8:9], off
	v_add_co_u32_e32 v8, vcc, s5, v6
	s_mov_b32 s5, 0x3c000
	s_nop 0
	v_addc_co_u32_e32 v9, vcc, 0, v7, vcc
	global_load_dword v113, v[8:9], off
	v_add_co_u32_e32 v8, vcc, s5, v6
	s_mov_b32 s5, 0x3e000
	s_nop 0
	v_addc_co_u32_e32 v9, vcc, 0, v7, vcc
	v_add_co_u32_e32 v6, vcc, s5, v6
	global_load_dword v8, v[8:9], off
	s_nop 0
	v_addc_co_u32_e32 v7, vcc, 0, v7, vcc
	global_load_dword v6, v[6:7], off
	s_waitcnt vmcnt(0)
; __device__ __forceinline__ unsigned pk2(float lo, float hi) { f32x2_t v = {lo, hi}; bf16x2_t b = __builtin_convertvector(v, bf16x2_t); return __builtin_bit_cast(unsigned, b); }
; __device__ __forceinline__ void conv_item(const float* W, int K, int N, int kind, int item, const float* gain, unsigned char* Wb, float* scr, int lane) {
;     ...
;     for (int i = 0; i < 32; ++i) scr[(2 * i + (lane >> 5)) * 33 + (lane & 31)] = wv_[i];
;     __builtin_amdgcn_s_waitcnt(0); asm volatile("" ::: "memory");
;     const int c = lane & 7; float gg[8];
; #pragma unroll
;     for (int e = 0; e < 8; ++e) gg[e] = gain ? gain[k0 + 8 * c + e] : 1.0f;
; #pragma unroll
;     for (int j = 0; j < 4; ++j) { const int n = (lane >> 3) + 8 * j; const float* s = scr + (8 * c) * 33 + n;
;         u32x4 o; o.x = pk2(s[0] * gg[0], s[33] * gg[1]); o.y = pk2(s[2 * 33] * gg[2], s[3 * 33] * gg[3]); o.z = pk2(s[4 * 33] * gg[4], s[5 * 33] * gg[5]); o.w = pk2(s[6 * 33] * gg[6], s[7 * 33] * gg[7]);
;         *(u32x4*)(wdst(kind, n0 + n, Wb) + k0 + 8 * c) = o; }
;     __builtin_amdgcn_s_waitcnt(0); asm volatile("" ::: "memory");
	ds_write2_b32 v5, v0, v10 offset1:66
	ds_write2_b32 v5, v11, v12 offset0:132 offset1:198
	v_add_u32_e32 v0, 0x400, v5
	ds_write2_b32 v0, v13, v14 offset0:8 offset1:74
	ds_write2_b32 v0, v15, v16 offset0:140 offset1:206
	v_add_u32_e32 v0, 0x800, v5
	ds_write2_b32 v0, v17, v18 offset0:16 offset1:82
	ds_write2_b32 v0, v19, v20 offset0:148 offset1:214
	v_add_u32_e32 v0, 0xc00, v5
	ds_write2_b32 v0, v21, v22 offset0:24 offset1:90
	ds_write2_b32 v0, v23, v24 offset0:156 offset1:222
	v_add_u32_e32 v0, 0x1000, v5
	ds_write2_b32 v0, v25, v26 offset0:32 offset1:98
	ds_write2_b32 v0, v27, v103 offset0:164 offset1:230
	v_add_u32_e32 v0, 0x1400, v5
	ds_write2_b32 v0, v104, v105 offset0:40 offset1:106
	ds_write2_b32 v0, v106, v107 offset0:172 offset1:238
	v_add_u32_e32 v0, 0x1800, v5
	ds_write2_b32 v0, v108, v109 offset0:48 offset1:114
	ds_write2_b32 v0, v110, v111 offset0:180 offset1:246
	v_add_u32_e32 v0, 0x1c00, v5
	ds_write2_b32 v0, v112, v113 offset0:56 offset1:122
	ds_write2_b32 v0, v8, v6 offset0:188 offset1:254
	s_waitcnt vmcnt(0) expcnt(0) lgkmcnt(0)
	ds_read_b32 v0, v29
	ds_read_b32 v6, v29 offset:132
	s_lshl_b64 s[6:7], s[92:93], 1
	s_waitcnt lgkmcnt(0)
	v_cvt_pk_bf16_f32 v6, v0, v6
	ds_read_b32 v0, v29 offset:264
	ds_read_b32 v7, v29 offset:396
	s_waitcnt lgkmcnt(0)
	v_cvt_pk_bf16_f32 v7, v0, v7
	ds_read_b32 v0, v29 offset:528
	ds_read_b32 v8, v29 offset:660
	s_waitcnt lgkmcnt(0)
	v_cvt_pk_bf16_f32 v8, v0, v8
	ds_read_b32 v0, v29 offset:792
	ds_read_b32 v9, v29 offset:924
	s_waitcnt lgkmcnt(0)
	v_cvt_pk_bf16_f32 v9, v0, v9
	v_add_u32_e32 v0, s4, v48
	v_add_u32_e32 v10, 0x60a00, v0
	v_ashrrev_i32_e32 v11, 31, v10
	v_lshlrev_b64 v[10:11], 10, v[10:11]
	v_lshl_add_u64 v[10:11], s[48:49], 0, v[10:11]
	v_lshl_add_u64 v[10:11], v[10:11], 0, s[6:7]
	v_lshlrev_b32_e32 v0, 1, v4
	v_lshl_add_u64 v[10:11], v[10:11], 0, v[0:1]
	flat_store_dwordx4 v[10:11], v[6:9]
	ds_read_b32 v6, v29 offset:32
	ds_read_b32 v7, v29 offset:164
	s_waitcnt lgkmcnt(0)
	v_cvt_pk_bf16_f32 v6, v6, v7
	ds_read_b32 v7, v29 offset:296
	ds_read_b32 v8, v29 offset:428
	s_waitcnt lgkmcnt(0)
	v_cvt_pk_bf16_f32 v7, v7, v8
	ds_read_b32 v8, v29 offset:560
	ds_read_b32 v9, v29 offset:692
	s_waitcnt lgkmcnt(0)
	v_cvt_pk_bf16_f32 v8, v8, v9
	ds_read_b32 v9, v29 offset:824
	ds_read_b32 v10, v29 offset:956
	s_waitcnt lgkmcnt(0)
	v_cvt_pk_bf16_f32 v9, v9, v10
	v_add_u32_e32 v10, s4, v49
	v_add_u32_e32 v10, 0x60a00, v10
	v_ashrrev_i32_e32 v11, 31, v10
	v_lshlrev_b64 v[10:11], 10, v[10:11]
	v_lshl_add_u64 v[10:11], s[48:49], 0, v[10:11]
	v_lshl_add_u64 v[10:11], v[10:11], 0, s[6:7]
	v_lshl_add_u64 v[10:11], v[10:11], 0, v[0:1]
	flat_store_dwordx4 v[10:11], v[6:9]
	ds_read_b32 v6, v29 offset:64
	ds_read_b32 v7, v29 offset:196
	s_waitcnt lgkmcnt(0)
	v_cvt_pk_bf16_f32 v6, v6, v7
	ds_read_b32 v7, v29 offset:328
	ds_read_b32 v8, v29 offset:460
	s_waitcnt lgkmcnt(0)
	v_cvt_pk_bf16_f32 v7, v7, v8
	ds_read_b32 v8, v29 offset:592
	ds_read_b32 v9, v29 offset:724
	s_waitcnt lgkmcnt(0)
	v_cvt_pk_bf16_f32 v8, v8, v9
	ds_read_b32 v9, v29 offset:856
	ds_read_b32 v10, v29 offset:988
	s_waitcnt lgkmcnt(0)
	v_cvt_pk_bf16_f32 v9, v9, v10
	v_add_u32_e32 v10, s4, v50
	v_add_u32_e32 v10, 0x60a00, v10
	v_ashrrev_i32_e32 v11, 31, v10
	v_lshlrev_b64 v[10:11], 10, v[10:11]
	v_lshl_add_u64 v[10:11], s[48:49], 0, v[10:11]
	v_lshl_add_u64 v[10:11], v[10:11], 0, s[6:7]
	v_lshl_add_u64 v[10:11], v[10:11], 0, v[0:1]
	flat_store_dwordx4 v[10:11], v[6:9]
	ds_read_b32 v8, v29 offset:96
	ds_read_b32 v9, v29 offset:228
	ds_read_b32 v12, v29 offset:360
	ds_read_b32 v13, v29 offset:492
	ds_read_b32 v14, v29 offset:624
	ds_read_b32 v15, v29 offset:756
	ds_read_b32 v16, v29 offset:888
	ds_read_b32 v17, v29 offset:1020
	v_add_u32_e32 v6, s4, v51
	v_add_u32_e32 v6, 0x60a00, v6
	v_ashrrev_i32_e32 v7, 31, v6
	v_lshlrev_b64 v[6:7], 10, v[6:7]
	v_lshl_add_u64 v[10:11], s[48:49], 0, v[6:7]
	v_lshl_add_u64 v[10:11], v[10:11], 0, s[6:7]
	s_waitcnt lgkmcnt(0)
	v_cvt_pk_bf16_f32 v6, v8, v9
	v_cvt_pk_bf16_f32 v7, v12, v13
	v_cvt_pk_bf16_f32 v8, v14, v15
	v_cvt_pk_bf16_f32 v9, v16, v17
	v_lshl_add_u64 v[10:11], v[10:11], 0, v[0:1]
	flat_store_dwordx4 v[10:11], v[6:9]
	s_waitcnt lgkmcnt(0)

; __device__ __forceinline__ void conv_item(const float* W, int K, int N, int kind, int item, const float* gain, unsigned char* Wb, float* scr, int lane) {
;     const int nblk = N / 32, kb = item / nblk, nb = item - kb * nblk, k0 = 64 * kb, n0 = 32 * nb;
;     float wv_[32];
; #pragma unroll
;     for (int i = 0; i < 32; ++i) wv_[i] = W[(size_t)(k0 + 2 * i + (lane >> 5)) * N + n0 + (lane & 31)];
; #pragma unroll
;     for (int i = 0; i < 32; ++i) scr[(2 * i + (lane >> 5)) * 33 + (lane & 31)] = wv_[i];
;     __builtin_amdgcn_s_waitcnt(0); asm volatile("" ::: "memory");
.LBB0_1210:
	s_andn2_b64 vcc, exec, s[4:5]
	s_cbranch_vccnz .LBB0_1212
	s_lshl_b32 s4, s77, 5
	s_and_b32 s6, s4, 0xfffffc00
	v_readlane_b32 s4, v254, 40
	v_readlane_b32 s5, v254, 41
	s_load_dwordx2 s[4:5], s[4:5], 0x68
	s_lshl_b32 s7, s73, 1
	v_lshlrev_b32_e32 v0, 2, v2
	s_waitcnt lgkmcnt(0)
	s_add_u32 s12, s4, s46
	s_addc_u32 s13, s5, s47
	s_add_i32 s4, s7, 0x4c0
	s_and_b32 s92, s4, 0xffffffc0
	s_sub_i32 s4, s75, s6
	s_add_i32 s4, s4, 0xfffa1600
	s_ashr_i32 s5, s4, 31
	s_lshl_b64 s[6:7], s[4:5], 2
	s_add_u32 s6, s12, s6
	v_or_b32_e32 v8, s92, v3
	s_addc_u32 s7, s13, s7
	v_lshl_add_u64 v[6:7], s[6:7], 0, v[0:1]
	v_lshlrev_b32_e32 v0, 10, v8
	v_lshl_add_u64 v[6:7], v[0:1], 2, v[6:7]
	s_movk_i32 s5, 0x2000
	v_add_co_u32_e32 v8, vcc, s5, v6
	s_movk_i32 s5, 0x4000
	s_nop 0
	v_addc_co_u32_e32 v9, vcc, 0, v7, vcc
	global_load_dword v0, v[6:7], off
	global_load_dword v10, v[8:9], off
	v_add_co_u32_e32 v8, vcc, s5, v6
	s_movk_i32 s5, 0x6000
	s_nop 0
	v_addc_co_u32_e32 v9, vcc, 0, v7, vcc
	global_load_dword v11, v[8:9], off
	v_add_co_u32_e32 v8, vcc, s5, v6
	s_mov_b32 s5, 0x8000
	s_nop 0
	v_addc_co_u32_e32 v9, vcc, 0, v7, vcc
	global_load_dword v12, v[8:9], off
	v_add_co_u32_e32 v8, vcc, s5, v6
	s_mov_b32 s5, 0xa000
	s_nop 0
	v_addc_co_u32_e32 v9, vcc, 0, v7, vcc
	global_load_dword v13, v[8:9], off
	v_add_co_u32_e32 v8, vcc, s5, v6
	s_mov_b32 s5, 0xc000
	s_nop 0
	v_addc_co_u32_e32 v9, vcc, 0, v7, vcc
	global_load_dword v14, v[8:9], off
	v_add_co_u32_e32 v8, vcc, s5, v6
	s_mov_b32 s5, 0xe000
	s_nop 0
	v_addc_co_u32_e32 v9, vcc, 0, v7, vcc
	global_load_dword v15, v[8:9], off
	v_add_co_u32_e32 v8, vcc, s5, v6
	s_mov_b32 s5, 0x10000
	s_nop 0
	v_addc_co_u32_e32 v9, vcc, 0, v7, vcc
	global_load_dword v16, v[8:9], off
	v_add_co_u32_e32 v8, vcc, s5, v6
	s_mov_b32 s5, 0x12000
	s_nop 0
	v_addc_co_u32_e32 v9, vcc, 0, v7, vcc
	global_load_dword v17, v[8:9], off
	v_add_co_u32_e32 v8, vcc, s5, v6
	s_mov_b32 s5, 0x14000
	s_nop 0
	v_addc_co_u32_e32 v9, vcc, 0, v7, vcc
	global_load_dword v18, v[8:9], off
	v_add_co_u32_e32 v8, vcc, s5, v6
	s_mov_b32 s5, 0x16000
	s_nop 0
	v_addc_co_u32_e32 v9, vcc, 0, v7, vcc
	global_load_dword v19, v[8:9], off
	v_add_co_u32_e32 v8, vcc, s5, v6
	s_mov_b32 s5, 0x18000
	s_nop 0
	v_addc_co_u32_e32 v9, vcc, 0, v7, vcc
	global_load_dword v20, v[8:9], off
	v_add_co_u32_e32 v8, vcc, s5, v6
	s_mov_b32 s5, 0x1a000
	s_nop 0
	v_addc_co_u32_e32 v9, vcc, 0, v7, vcc
	global_load_dword v21, v[8:9], off
	v_add_co_u32_e32 v8, vcc, s5, v6
	s_mov_b32 s5, 0x1c000
	s_nop 0
	v_addc_co_u32_e32 v9, vcc, 0, v7, vcc
	global_load_dword v22, v[8:9], off
	v_add_co_u32_e32 v8, vcc, s5, v6
	s_mov_b32 s5, 0x1e000
	s_nop 0
	v_addc_co_u32_e32 v9, vcc, 0, v7, vcc
	global_load_dword v23, v[8:9], off
	v_add_co_u32_e32 v8, vcc, s5, v6
	s_mov_b32 s5, 0x20000
	s_nop 0
	v_addc_co_u32_e32 v9, vcc, 0, v7, vcc
	global_load_dword v24, v[8:9], off
	v_add_co_u32_e32 v8, vcc, s5, v6
	s_mov_b32 s5, 0x22000
	s_nop 0
	v_addc_co_u32_e32 v9, vcc, 0, v7, vcc
	global_load_dword v25, v[8:9], off
	v_add_co_u32_e32 v8, vcc, s5, v6
	s_mov_b32 s5, 0x24000
	s_nop 0
	v_addc_co_u32_e32 v9, vcc, 0, v7, vcc
	global_load_dword v26, v[8:9], off
	v_add_co_u32_e32 v8, vcc, s5, v6
	s_mov_b32 s5, 0x26000
	s_nop 0
	v_addc_co_u32_e32 v9, vcc, 0, v7, vcc
	global_load_dword v27, v[8:9], off
	v_add_co_u32_e32 v8, vcc, s5, v6
	s_mov_b32 s5, 0x28000
	s_nop 0
	v_addc_co_u32_e32 v9, vcc, 0, v7, vcc
	global_load_dword v103, v[8:9], off
	v_add_co_u32_e32 v8, vcc, s5, v6
	s_mov_b32 s5, 0x2a000
	s_nop 0
	v_addc_co_u32_e32 v9, vcc, 0, v7, vcc
	global_load_dword v104, v[8:9], off
	v_add_co_u32_e32 v8, vcc, s5, v6
	s_mov_b32 s5, 0x2c000
	s_nop 0
	v_addc_co_u32_e32 v9, vcc, 0, v7, vcc
	global_load_dword v105, v[8:9], off
	v_add_co_u32_e32 v8, vcc, s5, v6
	s_mov_b32 s5, 0x2e000
	s_nop 0
	v_addc_co_u32_e32 v9, vcc, 0, v7, vcc
	global_load_dword v106, v[8:9], off
	v_add_co_u32_e32 v8, vcc, s5, v6
	s_mov_b32 s5, 0x30000
	s_nop 0
	v_addc_co_u32_e32 v9, vcc, 0, v7, vcc
	global_load_dword v107, v[8:9], off
	v_add_co_u32_e32 v8, vcc, s5, v6
	s_mov_b32 s5, 0x32000
	s_nop 0
	v_addc_co_u32_e32 v9, vcc, 0, v7, vcc
	global_load_dword v108, v[8:9], off
	v_add_co_u32_e32 v8, vcc, s5, v6
	s_mov_b32 s5, 0x34000
	s_nop 0
	v_addc_co_u32_e32 v9, vcc, 0, v7, vcc
	global_load_dword v109, v[8:9], off
	v_add_co_u32_e32 v8, vcc, s5, v6
	s_mov_b32 s5, 0x36000
	s_nop 0
	v_addc_co_u32_e32 v9, vcc, 0, v7, vcc
	global_load_dword v110, v[8:9], off
	v_add_co_u32_e32 v8, vcc, s5, v6
	s_mov_b32 s5, 0x38000
	s_nop 0
	v_addc_co_u32_e32 v9, vcc, 0, v7, vcc
	global_load_dword v111, v[8:9], off
	v_add_co_u32_e32 v8, vcc, s5, v6
	s_mov_b32 s5, 0x3a000
	s_nop 0
	v_addc_co_u32_e32 v9, vcc, 0, v7, vcc
	global_load_dword v112, v[8:9], off
	v_add_co_u32_e32 v8, vcc, s5, v6
	s_mov_b32 s5, 0x3c000
	s_nop 0
	v_addc_co_u32_e32 v9, vcc, 0, v7, vcc
	global_load_dword v113, v[8:9], off
	v_add_co_u32_e32 v8, vcc, s5, v6
	s_mov_b32 s5, 0x3e000
	s_nop 0
	v_addc_co_u32_e32 v9, vcc, 0, v7, vcc
	v_add_co_u32_e32 v6, vcc, s5, v6
	global_load_dword v8, v[8:9], off
	s_nop 0
	v_addc_co_u32_e32 v7, vcc, 0, v7, vcc
	global_load_dword v6, v[6:7], off
	s_waitcnt vmcnt(0)
; __device__ __forceinline__ unsigned pk2(float lo, float hi) { f32x2_t v = {lo, hi}; bf16x2_t b = __builtin_convertvector(v, bf16x2_t); return __builtin_bit_cast(unsigned, b); }
; __device__ __forceinline__ void conv_item(const float* W, int K, int N, int kind, int item, const float* gain, unsigned char* Wb, float* scr, int lane) {
;     ...
;     for (int i = 0; i < 32; ++i) scr[(2 * i + (lane >> 5)) * 33 + (lane & 31)] = wv_[i];
;     __builtin_amdgcn_s_waitcnt(0); asm volatile("" ::: "memory");
;     const int c = lane & 7; float gg[8];
; #pragma unroll
;     for (int e = 0; e < 8; ++e) gg[e] = gain ? gain[k0 + 8 * c + e] : 1.0f;
; #pragma unroll
;     for (int j = 0; j < 4; ++j) { const int n = (lane >> 3) + 8 * j; const float* s = scr + (8 * c) * 33 + n;
;         u32x4 o; o.x = pk2(s[0] * gg[0], s[33] * gg[1]); o.y = pk2(s[2 * 33] * gg[2], s[3 * 33] * gg[3]); o.z = pk2(s[4 * 33] * gg[4], s[5 * 33] * gg[5]); o.w = pk2(s[6 * 33] * gg[6], s[7 * 33] * gg[7]);
;         *(u32x4*)(wdst(kind, n0 + n, Wb) + k0 + 8 * c) = o; }
;     __builtin_amdgcn_s_waitcnt(0); asm volatile("" ::: "memory");
	ds_write2_b32 v5, v0, v10 offset1:66
	ds_write2_b32 v5, v11, v12 offset0:132 offset1:198
	v_add_u32_e32 v0, 0x400, v5
	ds_write2_b32 v0, v13, v14 offset0:8 offset1:74
	ds_write2_b32 v0, v15, v16 offset0:140 offset1:206
	v_add_u32_e32 v0, 0x800, v5
	ds_write2_b32 v0, v17, v18 offset0:16 offset1:82
	ds_write2_b32 v0, v19, v20 offset0:148 offset1:214
	v_add_u32_e32 v0, 0xc00, v5
	ds_write2_b32 v0, v21, v22 offset0:24 offset1:90
	ds_write2_b32 v0, v23, v24 offset0:156 offset1:222
	v_add_u32_e32 v0, 0x1000, v5
	ds_write2_b32 v0, v25, v26 offset0:32 offset1:98
	ds_write2_b32 v0, v27, v103 offset0:164 offset1:230
	v_add_u32_e32 v0, 0x1400, v5
	ds_write2_b32 v0, v104, v105 offset0:40 offset1:106
	ds_write2_b32 v0, v106, v107 offset0:172 offset1:238
	v_add_u32_e32 v0, 0x1800, v5
	ds_write2_b32 v0, v108, v109 offset0:48 offset1:114
	ds_write2_b32 v0, v110, v111 offset0:180 offset1:246
	v_add_u32_e32 v0, 0x1c00, v5
	ds_write2_b32 v0, v112, v113 offset0:56 offset1:122
	ds_write2_b32 v0, v8, v6 offset0:188 offset1:254
	s_waitcnt vmcnt(0) expcnt(0) lgkmcnt(0)
	ds_read_b32 v0, v29
	ds_read_b32 v6, v29 offset:132
	s_lshl_b64 s[6:7], s[92:93], 1
	s_waitcnt lgkmcnt(0)
	v_cvt_pk_bf16_f32 v6, v0, v6
	ds_read_b32 v0, v29 offset:264
	ds_read_b32 v7, v29 offset:396
	s_waitcnt lgkmcnt(0)
	v_cvt_pk_bf16_f32 v7, v0, v7
	ds_read_b32 v0, v29 offset:528
	ds_read_b32 v8, v29 offset:660
	s_waitcnt lgkmcnt(0)
	v_cvt_pk_bf16_f32 v8, v0, v8
	ds_read_b32 v0, v29 offset:792
	ds_read_b32 v9, v29 offset:924
	s_waitcnt lgkmcnt(0)
	v_cvt_pk_bf16_f32 v9, v0, v9
	v_add_u32_e32 v0, s4, v52
	v_add_u32_e32 v10, 0x5ea00, v0
	v_ashrrev_i32_e32 v11, 31, v10
	v_lshlrev_b64 v[10:11], 10, v[10:11]
	v_lshl_add_u64 v[10:11], s[50:51], 0, v[10:11]
	v_lshl_add_u64 v[10:11], v[10:11], 0, s[6:7]
	v_lshlrev_b32_e32 v0, 1, v4
	v_lshl_add_u64 v[10:11], v[10:11], 0, v[0:1]
	flat_store_dwordx4 v[10:11], v[6:9]
	ds_read_b32 v6, v29 offset:32
	ds_read_b32 v7, v29 offset:164
	s_waitcnt lgkmcnt(0)
	v_cvt_pk_bf16_f32 v6, v6, v7
	ds_read_b32 v7, v29 offset:296
	ds_read_b32 v8, v29 offset:428
	s_waitcnt lgkmcnt(0)
	v_cvt_pk_bf16_f32 v7, v7, v8
	ds_read_b32 v8, v29 offset:560
	ds_read_b32 v9, v29 offset:692
	s_waitcnt lgkmcnt(0)
	v_cvt_pk_bf16_f32 v8, v8, v9
	ds_read_b32 v9, v29 offset:824
	ds_read_b32 v10, v29 offset:956
	s_waitcnt lgkmcnt(0)
	v_cvt_pk_bf16_f32 v9, v9, v10
	v_add_u32_e32 v10, s4, v53
	v_add_u32_e32 v10, 0x5ea00, v10
	v_ashrrev_i32_e32 v11, 31, v10
	v_lshlrev_b64 v[10:11], 10, v[10:11]
	v_lshl_add_u64 v[10:11], s[50:51], 0, v[10:11]
	v_lshl_add_u64 v[10:11], v[10:11], 0, s[6:7]
	v_lshl_add_u64 v[10:11], v[10:11], 0, v[0:1]
	flat_store_dwordx4 v[10:11], v[6:9]
	ds_read_b32 v6, v29 offset:64
	ds_read_b32 v7, v29 offset:196
	s_waitcnt lgkmcnt(0)
	v_cvt_pk_bf16_f32 v6, v6, v7
	ds_read_b32 v7, v29 offset:328
	ds_read_b32 v8, v29 offset:460
	s_waitcnt lgkmcnt(0)
	v_cvt_pk_bf16_f32 v7, v7, v8
	ds_read_b32 v8, v29 offset:592
	ds_read_b32 v9, v29 offset:724
	s_waitcnt lgkmcnt(0)
	v_cvt_pk_bf16_f32 v8, v8, v9
	ds_read_b32 v9, v29 offset:856
	ds_read_b32 v10, v29 offset:988
	s_waitcnt lgkmcnt(0)
	v_cvt_pk_bf16_f32 v9, v9, v10
	v_add_u32_e32 v10, s4, v54
	v_add_u32_e32 v10, 0x5ea00, v10
	v_ashrrev_i32_e32 v11, 31, v10
	v_lshlrev_b64 v[10:11], 10, v[10:11]
	v_lshl_add_u64 v[10:11], s[50:51], 0, v[10:11]
	v_lshl_add_u64 v[10:11], v[10:11], 0, s[6:7]
	v_lshl_add_u64 v[10:11], v[10:11], 0, v[0:1]
	flat_store_dwordx4 v[10:11], v[6:9]
	ds_read_b32 v8, v29 offset:96
	ds_read_b32 v9, v29 offset:228
	ds_read_b32 v12, v29 offset:360
	ds_read_b32 v13, v29 offset:492
	ds_read_b32 v14, v29 offset:624
	ds_read_b32 v15, v29 offset:756
	ds_read_b32 v16, v29 offset:888
	ds_read_b32 v17, v29 offset:1020
	v_add_u32_e32 v6, s4, v55
	v_add_u32_e32 v6, 0x5ea00, v6
	v_ashrrev_i32_e32 v7, 31, v6
	v_lshlrev_b64 v[6:7], 10, v[6:7]
	v_lshl_add_u64 v[10:11], s[50:51], 0, v[6:7]
	v_lshl_add_u64 v[10:11], v[10:11], 0, s[6:7]
	s_waitcnt lgkmcnt(0)
	v_cvt_pk_bf16_f32 v6, v8, v9
	v_cvt_pk_bf16_f32 v7, v12, v13
	v_cvt_pk_bf16_f32 v8, v14, v15
	v_cvt_pk_bf16_f32 v9, v16, v17
	v_lshl_add_u64 v[10:11], v[10:11], 0, v[0:1]
	flat_store_dwordx4 v[10:11], v[6:9]
	s_waitcnt lgkmcnt(0)

; __device__ __forceinline__ void conv_item(const float* W, int K, int N, int kind, int item, const float* gain, unsigned char* Wb, float* scr, int lane) {
;     const int nblk = N / 32, kb = item / nblk, nb = item - kb * nblk, k0 = 64 * kb, n0 = 32 * nb;
;     float wv_[32];
; #pragma unroll
;     for (int i = 0; i < 32; ++i) wv_[i] = W[(size_t)(k0 + 2 * i + (lane >> 5)) * N + n0 + (lane & 31)];
; #pragma unroll
;     for (int i = 0; i < 32; ++i) scr[(2 * i + (lane >> 5)) * 33 + (lane & 31)] = wv_[i];
;     __builtin_amdgcn_s_waitcnt(0); asm volatile("" ::: "memory");
.LBB0_1213:
	s_andn2_b64 vcc, exec, s[4:5]
	s_cbranch_vccnz .LBB0_1215
	s_lshl_b32 s4, s78, 5
	s_and_b32 s6, s4, 0xfffffc00
	v_readlane_b32 s4, v254, 40
	v_readlane_b32 s5, v254, 41
	s_load_dwordx2 s[4:5], s[4:5], 0x58
	s_lshl_b32 s7, s73, 1
	v_lshlrev_b32_e32 v0, 2, v2
	s_waitcnt lgkmcnt(0)
	s_add_u32 s12, s4, s46
	s_addc_u32 s13, s5, s47
	s_add_i32 s4, s7, 0x6c0
	s_and_b32 s92, s4, 0xffffffc0
	s_sub_i32 s4, s75, s6
	s_add_i32 s4, s4, 0xfffa3600
	s_ashr_i32 s5, s4, 31
	s_lshl_b64 s[6:7], s[4:5], 2
	s_add_u32 s6, s12, s6
	v_or_b32_e32 v8, s92, v3
	s_addc_u32 s7, s13, s7
	v_lshl_add_u64 v[6:7], s[6:7], 0, v[0:1]
	v_lshlrev_b32_e32 v0, 10, v8
	v_lshl_add_u64 v[6:7], v[0:1], 2, v[6:7]
	s_movk_i32 s5, 0x2000
	v_add_co_u32_e32 v8, vcc, s5, v6
	s_movk_i32 s5, 0x4000
	s_nop 0
	v_addc_co_u32_e32 v9, vcc, 0, v7, vcc
	global_load_dword v0, v[6:7], off
	global_load_dword v10, v[8:9], off
	v_add_co_u32_e32 v8, vcc, s5, v6
	s_movk_i32 s5, 0x6000
	s_nop 0
	v_addc_co_u32_e32 v9, vcc, 0, v7, vcc
	global_load_dword v11, v[8:9], off
	v_add_co_u32_e32 v8, vcc, s5, v6
	s_mov_b32 s5, 0x8000
	s_nop 0
	v_addc_co_u32_e32 v9, vcc, 0, v7, vcc
	global_load_dword v12, v[8:9], off
	v_add_co_u32_e32 v8, vcc, s5, v6
	s_mov_b32 s5, 0xa000
	s_nop 0
	v_addc_co_u32_e32 v9, vcc, 0, v7, vcc
	global_load_dword v13, v[8:9], off
	v_add_co_u32_e32 v8, vcc, s5, v6
	s_mov_b32 s5, 0xc000
	s_nop 0
	v_addc_co_u32_e32 v9, vcc, 0, v7, vcc
	global_load_dword v14, v[8:9], off
	v_add_co_u32_e32 v8, vcc, s5, v6
	s_mov_b32 s5, 0xe000
	s_nop 0
	v_addc_co_u32_e32 v9, vcc, 0, v7, vcc
	global_load_dword v15, v[8:9], off
	v_add_co_u32_e32 v8, vcc, s5, v6
	s_mov_b32 s5, 0x10000
	s_nop 0
	v_addc_co_u32_e32 v9, vcc, 0, v7, vcc
	global_load_dword v16, v[8:9], off
	v_add_co_u32_e32 v8, vcc, s5, v6
	s_mov_b32 s5, 0x12000
	s_nop 0
	v_addc_co_u32_e32 v9, vcc, 0, v7, vcc
	global_load_dword v17, v[8:9], off
	v_add_co_u32_e32 v8, vcc, s5, v6
	s_mov_b32 s5, 0x14000
	s_nop 0
	v_addc_co_u32_e32 v9, vcc, 0, v7, vcc
	global_load_dword v18, v[8:9], off
	v_add_co_u32_e32 v8, vcc, s5, v6
	s_mov_b32 s5, 0x16000
	s_nop 0
	v_addc_co_u32_e32 v9, vcc, 0, v7, vcc
	global_load_dword v19, v[8:9], off
	v_add_co_u32_e32 v8, vcc, s5, v6
	s_mov_b32 s5, 0x18000
	s_nop 0
	v_addc_co_u32_e32 v9, vcc, 0, v7, vcc
	global_load_dword v20, v[8:9], off
	v_add_co_u32_e32 v8, vcc, s5, v6
	s_mov_b32 s5, 0x1a000
	s_nop 0
	v_addc_co_u32_e32 v9, vcc, 0, v7, vcc
	global_load_dword v21, v[8:9], off
	v_add_co_u32_e32 v8, vcc, s5, v6
	s_mov_b32 s5, 0x1c000
	s_nop 0
	v_addc_co_u32_e32 v9, vcc, 0, v7, vcc
	global_load_dword v22, v[8:9], off
	v_add_co_u32_e32 v8, vcc, s5, v6
	s_mov_b32 s5, 0x1e000
	s_nop 0
	v_addc_co_u32_e32 v9, vcc, 0, v7, vcc
	global_load_dword v23, v[8:9], off
	v_add_co_u32_e32 v8, vcc, s5, v6
	s_mov_b32 s5, 0x20000
	s_nop 0
	v_addc_co_u32_e32 v9, vcc, 0, v7, vcc
	global_load_dword v24, v[8:9], off
	v_add_co_u32_e32 v8, vcc, s5, v6
	s_mov_b32 s5, 0x22000
	s_nop 0
	v_addc_co_u32_e32 v9, vcc, 0, v7, vcc
	global_load_dword v25, v[8:9], off
	v_add_co_u32_e32 v8, vcc, s5, v6
	s_mov_b32 s5, 0x24000
	s_nop 0
	v_addc_co_u32_e32 v9, vcc, 0, v7, vcc
	global_load_dword v26, v[8:9], off
	v_add_co_u32_e32 v8, vcc, s5, v6
	s_mov_b32 s5, 0x26000
	s_nop 0
	v_addc_co_u32_e32 v9, vcc, 0, v7, vcc
	global_load_dword v27, v[8:9], off
	v_add_co_u32_e32 v8, vcc, s5, v6
	s_mov_b32 s5, 0x28000
	s_nop 0
	v_addc_co_u32_e32 v9, vcc, 0, v7, vcc
	global_load_dword v103, v[8:9], off
	v_add_co_u32_e32 v8, vcc, s5, v6
	s_mov_b32 s5, 0x2a000
	s_nop 0
	v_addc_co_u32_e32 v9, vcc, 0, v7, vcc
	global_load_dword v104, v[8:9], off
	v_add_co_u32_e32 v8, vcc, s5, v6
	s_mov_b32 s5, 0x2c000
	s_nop 0
	v_addc_co_u32_e32 v9, vcc, 0, v7, vcc
	global_load_dword v105, v[8:9], off
	v_add_co_u32_e32 v8, vcc, s5, v6
	s_mov_b32 s5, 0x2e000
	s_nop 0
	v_addc_co_u32_e32 v9, vcc, 0, v7, vcc
	global_load_dword v106, v[8:9], off
	v_add_co_u32_e32 v8, vcc, s5, v6
	s_mov_b32 s5, 0x30000
	s_nop 0
	v_addc_co_u32_e32 v9, vcc, 0, v7, vcc
	global_load_dword v107, v[8:9], off
	v_add_co_u32_e32 v8, vcc, s5, v6
	s_mov_b32 s5, 0x32000
	s_nop 0
	v_addc_co_u32_e32 v9, vcc, 0, v7, vcc
	global_load_dword v108, v[8:9], off
	v_add_co_u32_e32 v8, vcc, s5, v6
	s_mov_b32 s5, 0x34000
	s_nop 0
	v_addc_co_u32_e32 v9, vcc, 0, v7, vcc
	global_load_dword v109, v[8:9], off
	v_add_co_u32_e32 v8, vcc, s5, v6
	s_mov_b32 s5, 0x36000
	s_nop 0
	v_addc_co_u32_e32 v9, vcc, 0, v7, vcc
	global_load_dword v110, v[8:9], off
	v_add_co_u32_e32 v8, vcc, s5, v6
	s_mov_b32 s5, 0x38000
	s_nop 0
	v_addc_co_u32_e32 v9, vcc, 0, v7, vcc
	global_load_dword v111, v[8:9], off
	v_add_co_u32_e32 v8, vcc, s5, v6
	s_mov_b32 s5, 0x3a000
	s_nop 0
	v_addc_co_u32_e32 v9, vcc, 0, v7, vcc
	global_load_dword v112, v[8:9], off
	v_add_co_u32_e32 v8, vcc, s5, v6
	s_mov_b32 s5, 0x3c000
	s_nop 0
	v_addc_co_u32_e32 v9, vcc, 0, v7, vcc
	global_load_dword v113, v[8:9], off
	v_add_co_u32_e32 v8, vcc, s5, v6
	s_mov_b32 s5, 0x3e000
	s_nop 0
	v_addc_co_u32_e32 v9, vcc, 0, v7, vcc
	v_add_co_u32_e32 v6, vcc, s5, v6
	global_load_dword v8, v[8:9], off
	s_nop 0
	v_addc_co_u32_e32 v7, vcc, 0, v7, vcc
	global_load_dword v6, v[6:7], off
	s_waitcnt vmcnt(0)
; __device__ __forceinline__ unsigned pk2(float lo, float hi) { f32x2_t v = {lo, hi}; bf16x2_t b = __builtin_convertvector(v, bf16x2_t); return __builtin_bit_cast(unsigned, b); }
; __device__ __forceinline__ void conv_item(const float* W, int K, int N, int kind, int item, const float* gain, unsigned char* Wb, float* scr, int lane) {
;     ...
;     for (int i = 0; i < 32; ++i) scr[(2 * i + (lane >> 5)) * 33 + (lane & 31)] = wv_[i];
;     __builtin_amdgcn_s_waitcnt(0); asm volatile("" ::: "memory");
;     const int c = lane & 7; float gg[8];
; #pragma unroll
;     for (int e = 0; e < 8; ++e) gg[e] = gain ? gain[k0 + 8 * c + e] : 1.0f;
; #pragma unroll
;     for (int j = 0; j < 4; ++j) { const int n = (lane >> 3) + 8 * j; const float* s = scr + (8 * c) * 33 + n;
;         u32x4 o; o.x = pk2(s[0] * gg[0], s[33] * gg[1]); o.y = pk2(s[2 * 33] * gg[2], s[3 * 33] * gg[3]); o.z = pk2(s[4 * 33] * gg[4], s[5 * 33] * gg[5]); o.w = pk2(s[6 * 33] * gg[6], s[7 * 33] * gg[7]);
;         *(u32x4*)(wdst(kind, n0 + n, Wb) + k0 + 8 * c) = o; }
;     __builtin_amdgcn_s_waitcnt(0); asm volatile("" ::: "memory");
	ds_write2_b32 v5, v0, v10 offset1:66
	ds_write2_b32 v5, v11, v12 offset0:132 offset1:198
	v_add_u32_e32 v0, 0x400, v5
	ds_write2_b32 v0, v13, v14 offset0:8 offset1:74
	ds_write2_b32 v0, v15, v16 offset0:140 offset1:206
	v_add_u32_e32 v0, 0x800, v5
	ds_write2_b32 v0, v17, v18 offset0:16 offset1:82
	ds_write2_b32 v0, v19, v20 offset0:148 offset1:214
	v_add_u32_e32 v0, 0xc00, v5
	ds_write2_b32 v0, v21, v22 offset0:24 offset1:90
	ds_write2_b32 v0, v23, v24 offset0:156 offset1:222
	v_add_u32_e32 v0, 0x1000, v5
	ds_write2_b32 v0, v25, v26 offset0:32 offset1:98
	ds_write2_b32 v0, v27, v103 offset0:164 offset1:230
	v_add_u32_e32 v0, 0x1400, v5
	ds_write2_b32 v0, v104, v105 offset0:40 offset1:106
	ds_write2_b32 v0, v106, v107 offset0:172 offset1:238
	v_add_u32_e32 v0, 0x1800, v5
	ds_write2_b32 v0, v108, v109 offset0:48 offset1:114
	ds_write2_b32 v0, v110, v111 offset0:180 offset1:246
	v_add_u32_e32 v0, 0x1c00, v5
	ds_write2_b32 v0, v112, v113 offset0:56 offset1:122
	ds_write2_b32 v0, v8, v6 offset0:188 offset1:254
	s_waitcnt vmcnt(0) expcnt(0) lgkmcnt(0)
	ds_read_b32 v0, v29
	ds_read_b32 v6, v29 offset:132
	s_lshl_b64 s[6:7], s[92:93], 1
	s_waitcnt lgkmcnt(0)
	v_cvt_pk_bf16_f32 v6, v0, v6
	ds_read_b32 v0, v29 offset:264
	ds_read_b32 v7, v29 offset:396
	s_waitcnt lgkmcnt(0)
	v_cvt_pk_bf16_f32 v7, v0, v7
	ds_read_b32 v0, v29 offset:528
	ds_read_b32 v8, v29 offset:660
	s_waitcnt lgkmcnt(0)
	v_cvt_pk_bf16_f32 v8, v0, v8
	ds_read_b32 v0, v29 offset:792
	ds_read_b32 v9, v29 offset:924
	s_waitcnt lgkmcnt(0)
	v_cvt_pk_bf16_f32 v9, v0, v9
	v_add_u32_e32 v0, s4, v56
	v_add_u32_e32 v10, 0x5ca00, v0
	v_ashrrev_i32_e32 v11, 31, v10
	v_lshlrev_b64 v[10:11], 10, v[10:11]
	v_lshl_add_u64 v[10:11], s[52:53], 0, v[10:11]
	v_lshl_add_u64 v[10:11], v[10:11], 0, s[6:7]
	v_lshlrev_b32_e32 v0, 1, v4
	v_lshl_add_u64 v[10:11], v[10:11], 0, v[0:1]
	flat_store_dwordx4 v[10:11], v[6:9]
	ds_read_b32 v6, v29 offset:32
	ds_read_b32 v7, v29 offset:164
	s_waitcnt lgkmcnt(0)
	v_cvt_pk_bf16_f32 v6, v6, v7
	ds_read_b32 v7, v29 offset:296
	ds_read_b32 v8, v29 offset:428
	s_waitcnt lgkmcnt(0)
	v_cvt_pk_bf16_f32 v7, v7, v8
	ds_read_b32 v8, v29 offset:560
	ds_read_b32 v9, v29 offset:692
	s_waitcnt lgkmcnt(0)
	v_cvt_pk_bf16_f32 v8, v8, v9
	ds_read_b32 v9, v29 offset:824
	ds_read_b32 v10, v29 offset:956
	s_waitcnt lgkmcnt(0)
	v_cvt_pk_bf16_f32 v9, v9, v10
	v_add_u32_e32 v10, s4, v57
	v_add_u32_e32 v10, 0x5ca00, v10
	v_ashrrev_i32_e32 v11, 31, v10
	v_lshlrev_b64 v[10:11], 10, v[10:11]
	v_lshl_add_u64 v[10:11], s[52:53], 0, v[10:11]
	v_lshl_add_u64 v[10:11], v[10:11], 0, s[6:7]
	v_lshl_add_u64 v[10:11], v[10:11], 0, v[0:1]
	flat_store_dwordx4 v[10:11], v[6:9]
	ds_read_b32 v6, v29 offset:64
	ds_read_b32 v7, v29 offset:196
	s_waitcnt lgkmcnt(0)
	v_cvt_pk_bf16_f32 v6, v6, v7
	ds_read_b32 v7, v29 offset:328
	ds_read_b32 v8, v29 offset:460
	s_waitcnt lgkmcnt(0)
	v_cvt_pk_bf16_f32 v7, v7, v8
	ds_read_b32 v8, v29 offset:592
	ds_read_b32 v9, v29 offset:724
	s_waitcnt lgkmcnt(0)
	v_cvt_pk_bf16_f32 v8, v8, v9
	ds_read_b32 v9, v29 offset:856
	ds_read_b32 v10, v29 offset:988
	s_waitcnt lgkmcnt(0)
	v_cvt_pk_bf16_f32 v9, v9, v10
	v_add_u32_e32 v10, s4, v58
	v_add_u32_e32 v10, 0x5ca00, v10
	v_ashrrev_i32_e32 v11, 31, v10
	v_lshlrev_b64 v[10:11], 10, v[10:11]
	v_lshl_add_u64 v[10:11], s[52:53], 0, v[10:11]
	v_lshl_add_u64 v[10:11], v[10:11], 0, s[6:7]
	v_lshl_add_u64 v[10:11], v[10:11], 0, v[0:1]
	flat_store_dwordx4 v[10:11], v[6:9]
	ds_read_b32 v8, v29 offset:96
	ds_read_b32 v9, v29 offset:228
	ds_read_b32 v12, v29 offset:360
	ds_read_b32 v13, v29 offset:492
	ds_read_b32 v14, v29 offset:624
	ds_read_b32 v15, v29 offset:756
	ds_read_b32 v16, v29 offset:888
	ds_read_b32 v17, v29 offset:1020
	v_add_u32_e32 v6, s4, v59
	v_add_u32_e32 v6, 0x5ca00, v6
	v_ashrrev_i32_e32 v7, 31, v6
	v_lshlrev_b64 v[6:7], 10, v[6:7]
	v_lshl_add_u64 v[10:11], s[52:53], 0, v[6:7]
	v_lshl_add_u64 v[10:11], v[10:11], 0, s[6:7]
	s_waitcnt lgkmcnt(0)
	v_cvt_pk_bf16_f32 v6, v8, v9
	v_cvt_pk_bf16_f32 v7, v12, v13
	v_cvt_pk_bf16_f32 v8, v14, v15
	v_cvt_pk_bf16_f32 v9, v16, v17
	v_lshl_add_u64 v[10:11], v[10:11], 0, v[0:1]
	flat_store_dwordx4 v[10:11], v[6:9]
	s_waitcnt lgkmcnt(0)

; __device__ __forceinline__ void conv_item(const float* W, int K, int N, int kind, int item, const float* gain, unsigned char* Wb, float* scr, int lane) {
;     const int nblk = N / 32, kb = item / nblk, nb = item - kb * nblk, k0 = 64 * kb, n0 = 32 * nb;
;     float wv_[32];
; #pragma unroll
;     for (int i = 0; i < 32; ++i) wv_[i] = W[(size_t)(k0 + 2 * i + (lane >> 5)) * N + n0 + (lane & 31)];
; #pragma unroll
;     for (int i = 0; i < 32; ++i) scr[(2 * i + (lane >> 5)) * 33 + (lane & 31)] = wv_[i];
;     __builtin_amdgcn_s_waitcnt(0); asm volatile("" ::: "memory");
.LBB0_1216:
	s_andn2_b64 vcc, exec, s[4:5]
	s_cbranch_vccnz .LBB0_1218
	s_lshl_b32 s4, s79, 5
	s_and_b32 s6, s4, 0xfffffc00
	v_readlane_b32 s4, v254, 40
	v_readlane_b32 s5, v254, 41
	s_load_dwordx2 s[4:5], s[4:5], 0x80
	s_lshl_b32 s7, s73, 1
	v_lshlrev_b32_e32 v0, 2, v2
	s_waitcnt lgkmcnt(0)
	s_add_u32 s12, s4, s54
	s_addc_u32 s13, s5, s55
	s_add_i32 s4, s7, 0xac0
	s_and_b32 s92, s4, 0xffffffc0
	s_sub_i32 s4, s75, s6
	s_add_i32 s4, s4, 0xfffa7600
	s_ashr_i32 s5, s4, 31
	s_lshl_b64 s[6:7], s[4:5], 2
	s_add_u32 s6, s12, s6
	v_or_b32_e32 v8, s92, v3
	s_addc_u32 s7, s13, s7
	v_lshl_add_u64 v[6:7], s[6:7], 0, v[0:1]
	v_lshlrev_b32_e32 v0, 10, v8
	v_lshl_add_u64 v[6:7], v[0:1], 2, v[6:7]
	s_movk_i32 s5, 0x2000
	v_add_co_u32_e32 v8, vcc, s5, v6
	s_movk_i32 s5, 0x4000
	s_nop 0
	v_addc_co_u32_e32 v9, vcc, 0, v7, vcc
	global_load_dword v0, v[6:7], off
	global_load_dword v10, v[8:9], off
	v_add_co_u32_e32 v8, vcc, s5, v6
	s_movk_i32 s5, 0x6000
	s_nop 0
	v_addc_co_u32_e32 v9, vcc, 0, v7, vcc
	global_load_dword v11, v[8:9], off
	v_add_co_u32_e32 v8, vcc, s5, v6
	s_mov_b32 s5, 0x8000
	s_nop 0
	v_addc_co_u32_e32 v9, vcc, 0, v7, vcc
	global_load_dword v12, v[8:9], off
	v_add_co_u32_e32 v8, vcc, s5, v6
	s_mov_b32 s5, 0xa000
	s_nop 0
	v_addc_co_u32_e32 v9, vcc, 0, v7, vcc
	global_load_dword v13, v[8:9], off
	v_add_co_u32_e32 v8, vcc, s5, v6
	s_mov_b32 s5, 0xc000
	s_nop 0
	v_addc_co_u32_e32 v9, vcc, 0, v7, vcc
	global_load_dword v14, v[8:9], off
	v_add_co_u32_e32 v8, vcc, s5, v6
	s_mov_b32 s5, 0xe000
	s_nop 0
	v_addc_co_u32_e32 v9, vcc, 0, v7, vcc
	global_load_dword v15, v[8:9], off
	v_add_co_u32_e32 v8, vcc, s5, v6
	s_mov_b32 s5, 0x10000
	s_nop 0
	v_addc_co_u32_e32 v9, vcc, 0, v7, vcc
	global_load_dword v16, v[8:9], off
	v_add_co_u32_e32 v8, vcc, s5, v6
	s_mov_b32 s5, 0x12000
	s_nop 0
	v_addc_co_u32_e32 v9, vcc, 0, v7, vcc
	global_load_dword v17, v[8:9], off
	v_add_co_u32_e32 v8, vcc, s5, v6
	s_mov_b32 s5, 0x14000
	s_nop 0
	v_addc_co_u32_e32 v9, vcc, 0, v7, vcc
	global_load_dword v18, v[8:9], off
	v_add_co_u32_e32 v8, vcc, s5, v6
	s_mov_b32 s5, 0x16000
	s_nop 0
	v_addc_co_u32_e32 v9, vcc, 0, v7, vcc
	global_load_dword v19, v[8:9], off
	v_add_co_u32_e32 v8, vcc, s5, v6
	s_mov_b32 s5, 0x18000
	s_nop 0
	v_addc_co_u32_e32 v9, vcc, 0, v7, vcc
	global_load_dword v20, v[8:9], off
	v_add_co_u32_e32 v8, vcc, s5, v6
	s_mov_b32 s5, 0x1a000
	s_nop 0
	v_addc_co_u32_e32 v9, vcc, 0, v7, vcc
	global_load_dword v21, v[8:9], off
	v_add_co_u32_e32 v8, vcc, s5, v6
	s_mov_b32 s5, 0x1c000
	s_nop 0
	v_addc_co_u32_e32 v9, vcc, 0, v7, vcc
	global_load_dword v22, v[8:9], off
	v_add_co_u32_e32 v8, vcc, s5, v6
	s_mov_b32 s5, 0x1e000
	s_nop 0
	v_addc_co_u32_e32 v9, vcc, 0, v7, vcc
	global_load_dword v23, v[8:9], off
	v_add_co_u32_e32 v8, vcc, s5, v6
	s_mov_b32 s5, 0x20000
	s_nop 0
	v_addc_co_u32_e32 v9, vcc, 0, v7, vcc
	global_load_dword v24, v[8:9], off
	v_add_co_u32_e32 v8, vcc, s5, v6
	s_mov_b32 s5, 0x22000
	s_nop 0
	v_addc_co_u32_e32 v9, vcc, 0, v7, vcc
	global_load_dword v25, v[8:9], off
	v_add_co_u32_e32 v8, vcc, s5, v6
	s_mov_b32 s5, 0x24000
	s_nop 0
	v_addc_co_u32_e32 v9, vcc, 0, v7, vcc
	global_load_dword v26, v[8:9], off
	v_add_co_u32_e32 v8, vcc, s5, v6
	s_mov_b32 s5, 0x26000
	s_nop 0
	v_addc_co_u32_e32 v9, vcc, 0, v7, vcc
	global_load_dword v27, v[8:9], off
	v_add_co_u32_e32 v8, vcc, s5, v6
	s_mov_b32 s5, 0x28000
	s_nop 0
	v_addc_co_u32_e32 v9, vcc, 0, v7, vcc
	global_load_dword v103, v[8:9], off
	v_add_co_u32_e32 v8, vcc, s5, v6
	s_mov_b32 s5, 0x2a000
	s_nop 0
	v_addc_co_u32_e32 v9, vcc, 0, v7, vcc
	global_load_dword v104, v[8:9], off
	v_add_co_u32_e32 v8, vcc, s5, v6
	s_mov_b32 s5, 0x2c000
	s_nop 0
	v_addc_co_u32_e32 v9, vcc, 0, v7, vcc
	global_load_dword v105, v[8:9], off
	v_add_co_u32_e32 v8, vcc, s5, v6
	s_mov_b32 s5, 0x2e000
	s_nop 0
	v_addc_co_u32_e32 v9, vcc, 0, v7, vcc
	global_load_dword v106, v[8:9], off
	v_add_co_u32_e32 v8, vcc, s5, v6
	s_mov_b32 s5, 0x30000
	s_nop 0
	v_addc_co_u32_e32 v9, vcc, 0, v7, vcc
	global_load_dword v107, v[8:9], off
	v_add_co_u32_e32 v8, vcc, s5, v6
	s_mov_b32 s5, 0x32000
	s_nop 0
	v_addc_co_u32_e32 v9, vcc, 0, v7, vcc
	global_load_dword v108, v[8:9], off
	v_add_co_u32_e32 v8, vcc, s5, v6
	s_mov_b32 s5, 0x34000
	s_nop 0
	v_addc_co_u32_e32 v9, vcc, 0, v7, vcc
	global_load_dword v109, v[8:9], off
	v_add_co_u32_e32 v8, vcc, s5, v6
	s_mov_b32 s5, 0x36000
	s_nop 0
	v_addc_co_u32_e32 v9, vcc, 0, v7, vcc
	global_load_dword v110, v[8:9], off
	v_add_co_u32_e32 v8, vcc, s5, v6
	s_mov_b32 s5, 0x38000
	s_nop 0
	v_addc_co_u32_e32 v9, vcc, 0, v7, vcc
	global_load_dword v111, v[8:9], off
	v_add_co_u32_e32 v8, vcc, s5, v6
	s_mov_b32 s5, 0x3a000
	s_nop 0
	v_addc_co_u32_e32 v9, vcc, 0, v7, vcc
	global_load_dword v112, v[8:9], off
	v_add_co_u32_e32 v8, vcc, s5, v6
	s_mov_b32 s5, 0x3c000
	s_nop 0
	v_addc_co_u32_e32 v9, vcc, 0, v7, vcc
	global_load_dword v113, v[8:9], off
	v_add_co_u32_e32 v8, vcc, s5, v6
	s_mov_b32 s5, 0x3e000
	s_nop 0
	v_addc_co_u32_e32 v9, vcc, 0, v7, vcc
	v_add_co_u32_e32 v6, vcc, s5, v6
	global_load_dword v8, v[8:9], off
	s_nop 0
	v_addc_co_u32_e32 v7, vcc, 0, v7, vcc
	global_load_dword v6, v[6:7], off
	s_waitcnt vmcnt(0)
; __device__ __forceinline__ unsigned pk2(float lo, float hi) { f32x2_t v = {lo, hi}; bf16x2_t b = __builtin_convertvector(v, bf16x2_t); return __builtin_bit_cast(unsigned, b); }
; __device__ __forceinline__ void conv_item(const float* W, int K, int N, int kind, int item, const float* gain, unsigned char* Wb, float* scr, int lane) {
;     ...
;     for (int i = 0; i < 32; ++i) scr[(2 * i + (lane >> 5)) * 33 + (lane & 31)] = wv_[i];
;     __builtin_amdgcn_s_waitcnt(0); asm volatile("" ::: "memory");
;     const int c = lane & 7; float gg[8];
; #pragma unroll
;     for (int e = 0; e < 8; ++e) gg[e] = gain ? gain[k0 + 8 * c + e] : 1.0f;
; #pragma unroll
;     for (int j = 0; j < 4; ++j) { const int n = (lane >> 3) + 8 * j; const float* s = scr + (8 * c) * 33 + n;
;         u32x4 o; o.x = pk2(s[0] * gg[0], s[33] * gg[1]); o.y = pk2(s[2 * 33] * gg[2], s[3 * 33] * gg[3]); o.z = pk2(s[4 * 33] * gg[4], s[5 * 33] * gg[5]); o.w = pk2(s[6 * 33] * gg[6], s[7 * 33] * gg[7]);
;         *(u32x4*)(wdst(kind, n0 + n, Wb) + k0 + 8 * c) = o; }
;     __builtin_amdgcn_s_waitcnt(0); asm volatile("" ::: "memory");
	ds_write2_b32 v5, v0, v10 offset1:66
	ds_write2_b32 v5, v11, v12 offset0:132 offset1:198
	v_add_u32_e32 v0, 0x400, v5
	ds_write2_b32 v0, v13, v14 offset0:8 offset1:74
	ds_write2_b32 v0, v15, v16 offset0:140 offset1:206
	v_add_u32_e32 v0, 0x800, v5
	ds_write2_b32 v0, v17, v18 offset0:16 offset1:82
	ds_write2_b32 v0, v19, v20 offset0:148 offset1:214
	v_add_u32_e32 v0, 0xc00, v5
	ds_write2_b32 v0, v21, v22 offset0:24 offset1:90
	ds_write2_b32 v0, v23, v24 offset0:156 offset1:222
	v_add_u32_e32 v0, 0x1000, v5
	ds_write2_b32 v0, v25, v26 offset0:32 offset1:98
	ds_write2_b32 v0, v27, v103 offset0:164 offset1:230
	v_add_u32_e32 v0, 0x1400, v5
	ds_write2_b32 v0, v104, v105 offset0:40 offset1:106
	ds_write2_b32 v0, v106, v107 offset0:172 offset1:238
	v_add_u32_e32 v0, 0x1800, v5
	ds_write2_b32 v0, v108, v109 offset0:48 offset1:114
	ds_write2_b32 v0, v110, v111 offset0:180 offset1:246
	v_add_u32_e32 v0, 0x1c00, v5
	ds_write2_b32 v0, v112, v113 offset0:56 offset1:122
	ds_write2_b32 v0, v8, v6 offset0:188 offset1:254
	s_waitcnt vmcnt(0) expcnt(0) lgkmcnt(0)
	ds_read_b32 v0, v29
	ds_read_b32 v6, v29 offset:132
	s_lshl_b64 s[6:7], s[92:93], 1
	s_waitcnt lgkmcnt(0)
	v_cvt_pk_bf16_f32 v6, v0, v6
	ds_read_b32 v0, v29 offset:264
	ds_read_b32 v7, v29 offset:396
	s_waitcnt lgkmcnt(0)
	v_cvt_pk_bf16_f32 v7, v0, v7
	ds_read_b32 v0, v29 offset:528
	ds_read_b32 v8, v29 offset:660
	s_waitcnt lgkmcnt(0)
	v_cvt_pk_bf16_f32 v8, v0, v8
	ds_read_b32 v0, v29 offset:792
	ds_read_b32 v9, v29 offset:924
	s_waitcnt lgkmcnt(0)
	v_cvt_pk_bf16_f32 v9, v0, v9
	v_add_u32_e32 v0, s4, v60
	v_add_u32_e32 v10, 0x58a00, v0
	v_ashrrev_i32_e32 v11, 31, v10
	v_lshlrev_b64 v[10:11], 11, v[10:11]
	v_lshl_add_u64 v[10:11], s[56:57], 0, v[10:11]
	v_lshl_add_u64 v[10:11], v[10:11], 0, s[6:7]
	v_lshlrev_b32_e32 v0, 1, v4
	v_lshl_add_u64 v[10:11], v[10:11], 0, v[0:1]
	flat_store_dwordx4 v[10:11], v[6:9]
	ds_read_b32 v6, v29 offset:32
	ds_read_b32 v7, v29 offset:164
	s_waitcnt lgkmcnt(0)
	v_cvt_pk_bf16_f32 v6, v6, v7
	ds_read_b32 v7, v29 offset:296
	ds_read_b32 v8, v29 offset:428
	s_waitcnt lgkmcnt(0)
	v_cvt_pk_bf16_f32 v7, v7, v8
	ds_read_b32 v8, v29 offset:560
	ds_read_b32 v9, v29 offset:692
	s_waitcnt lgkmcnt(0)
	v_cvt_pk_bf16_f32 v8, v8, v9
	ds_read_b32 v9, v29 offset:824
	ds_read_b32 v10, v29 offset:956
	s_waitcnt lgkmcnt(0)
	v_cvt_pk_bf16_f32 v9, v9, v10
	v_add_u32_e32 v10, s4, v61
	v_add_u32_e32 v10, 0x58a00, v10
	v_ashrrev_i32_e32 v11, 31, v10
	v_lshlrev_b64 v[10:11], 11, v[10:11]
	v_lshl_add_u64 v[10:11], s[56:57], 0, v[10:11]
	v_lshl_add_u64 v[10:11], v[10:11], 0, s[6:7]
	v_lshl_add_u64 v[10:11], v[10:11], 0, v[0:1]
	flat_store_dwordx4 v[10:11], v[6:9]
	ds_read_b32 v6, v29 offset:64
	ds_read_b32 v7, v29 offset:196
	s_waitcnt lgkmcnt(0)
	v_cvt_pk_bf16_f32 v6, v6, v7
	ds_read_b32 v7, v29 offset:328
	ds_read_b32 v8, v29 offset:460
	s_waitcnt lgkmcnt(0)
	v_cvt_pk_bf16_f32 v7, v7, v8
	ds_read_b32 v8, v29 offset:592
	ds_read_b32 v9, v29 offset:724
	s_waitcnt lgkmcnt(0)
	v_cvt_pk_bf16_f32 v8, v8, v9
	ds_read_b32 v9, v29 offset:856
	ds_read_b32 v10, v29 offset:988
	s_waitcnt lgkmcnt(0)
	v_cvt_pk_bf16_f32 v9, v9, v10
	v_add_u32_e32 v10, s4, v62
	v_add_u32_e32 v10, 0x58a00, v10
	v_ashrrev_i32_e32 v11, 31, v10
	v_lshlrev_b64 v[10:11], 11, v[10:11]
	v_lshl_add_u64 v[10:11], s[56:57], 0, v[10:11]
	v_lshl_add_u64 v[10:11], v[10:11], 0, s[6:7]
	v_lshl_add_u64 v[10:11], v[10:11], 0, v[0:1]
	flat_store_dwordx4 v[10:11], v[6:9]
	ds_read_b32 v8, v29 offset:96
	ds_read_b32 v9, v29 offset:228
	ds_read_b32 v12, v29 offset:360
	ds_read_b32 v13, v29 offset:492
	ds_read_b32 v14, v29 offset:624
	ds_read_b32 v15, v29 offset:756
	ds_read_b32 v16, v29 offset:888
	ds_read_b32 v17, v29 offset:1020
	v_add_u32_e32 v6, s4, v63
	v_add_u32_e32 v6, 0x58a00, v6
	v_ashrrev_i32_e32 v7, 31, v6
	v_lshlrev_b64 v[6:7], 11, v[6:7]
	v_lshl_add_u64 v[10:11], s[56:57], 0, v[6:7]
	v_lshl_add_u64 v[10:11], v[10:11], 0, s[6:7]
	s_waitcnt lgkmcnt(0)
	v_cvt_pk_bf16_f32 v6, v8, v9
	v_cvt_pk_bf16_f32 v7, v12, v13
	v_cvt_pk_bf16_f32 v8, v14, v15
	v_cvt_pk_bf16_f32 v9, v16, v17
	v_lshl_add_u64 v[10:11], v[10:11], 0, v[0:1]
	flat_store_dwordx4 v[10:11], v[6:9]
	s_waitcnt lgkmcnt(0)

; __device__ __forceinline__ void conv_item(const float* W, int K, int N, int kind, int item, const float* gain, unsigned char* Wb, float* scr, int lane) {
;     const int nblk = N / 32, kb = item / nblk, nb = item - kb * nblk, k0 = 64 * kb, n0 = 32 * nb;
;     float wv_[32];
; #pragma unroll
;     for (int i = 0; i < 32; ++i) wv_[i] = W[(size_t)(k0 + 2 * i + (lane >> 5)) * N + n0 + (lane & 31)];
; #pragma unroll
;     for (int i = 0; i < 32; ++i) scr[(2 * i + (lane >> 5)) * 33 + (lane & 31)] = wv_[i];
;     __builtin_amdgcn_s_waitcnt(0); asm volatile("" ::: "memory");
.LBB0_1219:
	s_andn2_b64 vcc, exec, s[4:5]
	s_cbranch_vccnz .LBB0_1221
	s_lshl_b32 s4, s80, 5
	s_and_b32 s6, s4, 0xfffffc00
	v_readlane_b32 s4, v254, 40
	v_readlane_b32 s5, v254, 41
	s_load_dwordx2 s[4:5], s[4:5], 0x20
	s_lshl_b32 s7, s73, 1
	v_lshlrev_b32_e32 v0, 2, v2
	s_waitcnt lgkmcnt(0)
	s_add_u32 s12, s4, s68
	s_addc_u32 s13, s5, s29
	s_add_i32 s4, s7, 0x20c0
	s_and_b32 s92, s4, 0xffffffc0
	s_sub_i32 s4, s75, s6
	s_add_i32 s4, s4, 0xfffbd600
	s_ashr_i32 s5, s4, 31
	s_lshl_b64 s[6:7], s[4:5], 2
	s_add_u32 s6, s12, s6
	v_or_b32_e32 v8, s92, v3
	s_addc_u32 s7, s13, s7
	v_lshl_add_u64 v[6:7], s[6:7], 0, v[0:1]
	v_lshlrev_b32_e32 v0, 10, v8
	v_lshl_add_u64 v[6:7], v[0:1], 2, v[6:7]
	s_movk_i32 s5, 0x2000
	v_add_co_u32_e32 v8, vcc, s5, v6
	s_movk_i32 s5, 0x4000
	s_nop 0
	v_addc_co_u32_e32 v9, vcc, 0, v7, vcc
	global_load_dword v0, v[6:7], off
	global_load_dword v10, v[8:9], off
	v_add_co_u32_e32 v8, vcc, s5, v6
	s_movk_i32 s5, 0x6000
	s_nop 0
	v_addc_co_u32_e32 v9, vcc, 0, v7, vcc
	global_load_dword v11, v[8:9], off
	v_add_co_u32_e32 v8, vcc, s5, v6
	s_mov_b32 s5, 0x8000
	s_nop 0
	v_addc_co_u32_e32 v9, vcc, 0, v7, vcc
	global_load_dword v12, v[8:9], off
	v_add_co_u32_e32 v8, vcc, s5, v6
	s_mov_b32 s5, 0xa000
	s_nop 0
	v_addc_co_u32_e32 v9, vcc, 0, v7, vcc
	global_load_dword v13, v[8:9], off
	v_add_co_u32_e32 v8, vcc, s5, v6
	s_mov_b32 s5, 0xc000
	s_nop 0
	v_addc_co_u32_e32 v9, vcc, 0, v7, vcc
	global_load_dword v14, v[8:9], off
	v_add_co_u32_e32 v8, vcc, s5, v6
	s_mov_b32 s5, 0xe000
	s_nop 0
	v_addc_co_u32_e32 v9, vcc, 0, v7, vcc
	global_load_dword v15, v[8:9], off
	v_add_co_u32_e32 v8, vcc, s5, v6
	s_mov_b32 s5, 0x10000
	s_nop 0
	v_addc_co_u32_e32 v9, vcc, 0, v7, vcc
	global_load_dword v16, v[8:9], off
	v_add_co_u32_e32 v8, vcc, s5, v6
	s_mov_b32 s5, 0x12000
	s_nop 0
	v_addc_co_u32_e32 v9, vcc, 0, v7, vcc
	global_load_dword v17, v[8:9], off
	v_add_co_u32_e32 v8, vcc, s5, v6
	s_mov_b32 s5, 0x14000
	s_nop 0
	v_addc_co_u32_e32 v9, vcc, 0, v7, vcc
	global_load_dword v18, v[8:9], off
	v_add_co_u32_e32 v8, vcc, s5, v6
	s_mov_b32 s5, 0x16000
	s_nop 0
	v_addc_co_u32_e32 v9, vcc, 0, v7, vcc
	global_load_dword v19, v[8:9], off
	v_add_co_u32_e32 v8, vcc, s5, v6
	s_mov_b32 s5, 0x18000
	s_nop 0
	v_addc_co_u32_e32 v9, vcc, 0, v7, vcc
	global_load_dword v20, v[8:9], off
	v_add_co_u32_e32 v8, vcc, s5, v6
	s_mov_b32 s5, 0x1a000
	s_nop 0
	v_addc_co_u32_e32 v9, vcc, 0, v7, vcc
	global_load_dword v21, v[8:9], off
	v_add_co_u32_e32 v8, vcc, s5, v6
	s_mov_b32 s5, 0x1c000
	s_nop 0
	v_addc_co_u32_e32 v9, vcc, 0, v7, vcc
	global_load_dword v22, v[8:9], off
	v_add_co_u32_e32 v8, vcc, s5, v6
	s_mov_b32 s5, 0x1e000
	s_nop 0
	v_addc_co_u32_e32 v9, vcc, 0, v7, vcc
	global_load_dword v23, v[8:9], off
	v_add_co_u32_e32 v8, vcc, s5, v6
	s_mov_b32 s5, 0x20000
	s_nop 0
	v_addc_co_u32_e32 v9, vcc, 0, v7, vcc
	global_load_dword v24, v[8:9], off
	v_add_co_u32_e32 v8, vcc, s5, v6
	s_mov_b32 s5, 0x22000
	s_nop 0
	v_addc_co_u32_e32 v9, vcc, 0, v7, vcc
	global_load_dword v25, v[8:9], off
	v_add_co_u32_e32 v8, vcc, s5, v6
	s_mov_b32 s5, 0x24000
	s_nop 0
	v_addc_co_u32_e32 v9, vcc, 0, v7, vcc
	global_load_dword v26, v[8:9], off
	v_add_co_u32_e32 v8, vcc, s5, v6
	s_mov_b32 s5, 0x26000
	s_nop 0
	v_addc_co_u32_e32 v9, vcc, 0, v7, vcc
	global_load_dword v27, v[8:9], off
	v_add_co_u32_e32 v8, vcc, s5, v6
	s_mov_b32 s5, 0x28000
	s_nop 0
	v_addc_co_u32_e32 v9, vcc, 0, v7, vcc
	global_load_dword v103, v[8:9], off
	v_add_co_u32_e32 v8, vcc, s5, v6
	s_mov_b32 s5, 0x2a000
	s_nop 0
	v_addc_co_u32_e32 v9, vcc, 0, v7, vcc
	global_load_dword v104, v[8:9], off
	v_add_co_u32_e32 v8, vcc, s5, v6
	s_mov_b32 s5, 0x2c000
	s_nop 0
	v_addc_co_u32_e32 v9, vcc, 0, v7, vcc
	global_load_dword v105, v[8:9], off
	v_add_co_u32_e32 v8, vcc, s5, v6
	s_mov_b32 s5, 0x2e000
	s_nop 0
	v_addc_co_u32_e32 v9, vcc, 0, v7, vcc
	global_load_dword v106, v[8:9], off
	v_add_co_u32_e32 v8, vcc, s5, v6
	s_mov_b32 s5, 0x30000
	s_nop 0
	v_addc_co_u32_e32 v9, vcc, 0, v7, vcc
	global_load_dword v107, v[8:9], off
	v_add_co_u32_e32 v8, vcc, s5, v6
	s_mov_b32 s5, 0x32000
	s_nop 0
	v_addc_co_u32_e32 v9, vcc, 0, v7, vcc
	global_load_dword v108, v[8:9], off
	v_add_co_u32_e32 v8, vcc, s5, v6
	s_mov_b32 s5, 0x34000
	s_nop 0
	v_addc_co_u32_e32 v9, vcc, 0, v7, vcc
	global_load_dword v109, v[8:9], off
	v_add_co_u32_e32 v8, vcc, s5, v6
	s_mov_b32 s5, 0x36000
	s_nop 0
	v_addc_co_u32_e32 v9, vcc, 0, v7, vcc
	global_load_dword v110, v[8:9], off
	v_add_co_u32_e32 v8, vcc, s5, v6
	s_mov_b32 s5, 0x38000
	s_nop 0
	v_addc_co_u32_e32 v9, vcc, 0, v7, vcc
	global_load_dword v111, v[8:9], off
	v_add_co_u32_e32 v8, vcc, s5, v6
	s_mov_b32 s5, 0x3a000
	s_nop 0
	v_addc_co_u32_e32 v9, vcc, 0, v7, vcc
	global_load_dword v112, v[8:9], off
	v_add_co_u32_e32 v8, vcc, s5, v6
	s_mov_b32 s5, 0x3c000
	s_nop 0
	v_addc_co_u32_e32 v9, vcc, 0, v7, vcc
	global_load_dword v113, v[8:9], off
	v_add_co_u32_e32 v8, vcc, s5, v6
	s_mov_b32 s5, 0x3e000
	s_nop 0
	v_addc_co_u32_e32 v9, vcc, 0, v7, vcc
	v_add_co_u32_e32 v6, vcc, s5, v6
	global_load_dword v8, v[8:9], off
	s_nop 0
	v_addc_co_u32_e32 v7, vcc, 0, v7, vcc
	global_load_dword v6, v[6:7], off
	s_waitcnt vmcnt(0)
; __device__ __forceinline__ unsigned pk2(float lo, float hi) { f32x2_t v = {lo, hi}; bf16x2_t b = __builtin_convertvector(v, bf16x2_t); return __builtin_bit_cast(unsigned, b); }
; __device__ __forceinline__ void conv_item(const float* W, int K, int N, int kind, int item, const float* gain, unsigned char* Wb, float* scr, int lane) {
;     ...
;     for (int i = 0; i < 32; ++i) scr[(2 * i + (lane >> 5)) * 33 + (lane & 31)] = wv_[i];
;     __builtin_amdgcn_s_waitcnt(0); asm volatile("" ::: "memory");
;     const int c = lane & 7; float gg[8];
; #pragma unroll
;     for (int e = 0; e < 8; ++e) gg[e] = gain ? gain[k0 + 8 * c + e] : 1.0f;
; #pragma unroll
;     for (int j = 0; j < 4; ++j) { const int n = (lane >> 3) + 8 * j; const float* s = scr + (8 * c) * 33 + n;
;         u32x4 o; o.x = pk2(s[0] * gg[0], s[33] * gg[1]); o.y = pk2(s[2 * 33] * gg[2], s[3 * 33] * gg[3]); o.z = pk2(s[4 * 33] * gg[4], s[5 * 33] * gg[5]); o.w = pk2(s[6 * 33] * gg[6], s[7 * 33] * gg[7]);
;         *(u32x4*)(wdst(kind, n0 + n, Wb) + k0 + 8 * c) = o; }
;     __builtin_amdgcn_s_waitcnt(0); asm volatile("" ::: "memory");
	ds_write2_b32 v5, v0, v10 offset1:66
	ds_write2_b32 v5, v11, v12 offset0:132 offset1:198
	v_add_u32_e32 v0, 0x400, v5
	ds_write2_b32 v0, v13, v14 offset0:8 offset1:74
	ds_write2_b32 v0, v15, v16 offset0:140 offset1:206
	v_add_u32_e32 v0, 0x800, v5
	ds_write2_b32 v0, v17, v18 offset0:16 offset1:82
	ds_write2_b32 v0, v19, v20 offset0:148 offset1:214
	v_add_u32_e32 v0, 0xc00, v5
	ds_write2_b32 v0, v21, v22 offset0:24 offset1:90
	ds_write2_b32 v0, v23, v24 offset0:156 offset1:222
	v_add_u32_e32 v0, 0x1000, v5
	ds_write2_b32 v0, v25, v26 offset0:32 offset1:98
	ds_write2_b32 v0, v27, v103 offset0:164 offset1:230
	v_add_u32_e32 v0, 0x1400, v5
	ds_write2_b32 v0, v104, v105 offset0:40 offset1:106
	ds_write2_b32 v0, v106, v107 offset0:172 offset1:238
	v_add_u32_e32 v0, 0x1800, v5
	ds_write2_b32 v0, v108, v109 offset0:48 offset1:114
	ds_write2_b32 v0, v110, v111 offset0:180 offset1:246
	v_add_u32_e32 v0, 0x1c00, v5
	ds_write2_b32 v0, v112, v113 offset0:56 offset1:122
	ds_write2_b32 v0, v8, v6 offset0:188 offset1:254
	s_waitcnt vmcnt(0) expcnt(0) lgkmcnt(0)
	ds_read_b32 v0, v29
	ds_read_b32 v6, v29 offset:132
	v_mov_b64_e32 v[10:11], s[58:59]
	s_movk_i32 s5, 0x1600
	v_add_u32_e32 v16, s4, v67
	v_add_u32_e32 v16, 0x42a00, v16
	s_waitcnt lgkmcnt(0)
	v_cvt_pk_bf16_f32 v6, v0, v6
	ds_read_b32 v0, v29 offset:264
	ds_read_b32 v7, v29 offset:396
	s_waitcnt lgkmcnt(0)
	v_cvt_pk_bf16_f32 v7, v0, v7
	ds_read_b32 v0, v29 offset:528
	ds_read_b32 v8, v29 offset:660
	s_waitcnt lgkmcnt(0)
	v_cvt_pk_bf16_f32 v8, v0, v8
	ds_read_b32 v0, v29 offset:792
	ds_read_b32 v9, v29 offset:924
	s_waitcnt lgkmcnt(0)
	v_cvt_pk_bf16_f32 v9, v0, v9
	v_add_u32_e32 v0, s4, v64
	v_add_u32_e32 v0, 0x42a00, v0
	v_mad_i64_i32 v[12:13], s[6:7], v0, s5, v[10:11]
	s_lshl_b64 s[6:7], s[92:93], 1
	s_nop 0
	v_lshl_add_u64 v[12:13], v[12:13], 0, s[6:7]
	v_lshlrev_b32_e32 v0, 1, v4
	v_lshl_add_u64 v[12:13], v[12:13], 0, v[0:1]
	flat_store_dwordx4 v[12:13], v[6:9]
	ds_read_b32 v6, v29 offset:32
	ds_read_b32 v7, v29 offset:164
	s_waitcnt lgkmcnt(0)
	v_cvt_pk_bf16_f32 v6, v6, v7
	ds_read_b32 v7, v29 offset:296
	ds_read_b32 v8, v29 offset:428
	s_waitcnt lgkmcnt(0)
	v_cvt_pk_bf16_f32 v7, v7, v8
	ds_read_b32 v8, v29 offset:560
	ds_read_b32 v9, v29 offset:692
	s_waitcnt lgkmcnt(0)
	v_cvt_pk_bf16_f32 v8, v8, v9
	ds_read_b32 v9, v29 offset:824
	ds_read_b32 v12, v29 offset:956
	s_waitcnt lgkmcnt(0)
	v_cvt_pk_bf16_f32 v9, v9, v12
	v_add_u32_e32 v12, s4, v65
	v_add_u32_e32 v12, 0x42a00, v12
	v_mad_i64_i32 v[12:13], s[12:13], v12, s5, v[10:11]
	v_lshl_add_u64 v[12:13], v[12:13], 0, s[6:7]
	v_lshl_add_u64 v[12:13], v[12:13], 0, v[0:1]
	flat_store_dwordx4 v[12:13], v[6:9]
	ds_read_b32 v6, v29 offset:64
	ds_read_b32 v7, v29 offset:196
	s_waitcnt lgkmcnt(0)
	v_cvt_pk_bf16_f32 v6, v6, v7
	ds_read_b32 v7, v29 offset:328
	ds_read_b32 v8, v29 offset:460
	s_waitcnt lgkmcnt(0)
	v_cvt_pk_bf16_f32 v7, v7, v8
	ds_read_b32 v8, v29 offset:592
	ds_read_b32 v9, v29 offset:724
	s_waitcnt lgkmcnt(0)
	v_cvt_pk_bf16_f32 v8, v8, v9
	ds_read_b32 v9, v29 offset:856
	ds_read_b32 v12, v29 offset:988
	s_waitcnt lgkmcnt(0)
	v_cvt_pk_bf16_f32 v9, v9, v12
	v_add_u32_e32 v12, s4, v66
	v_add_u32_e32 v12, 0x42a00, v12
	v_mad_i64_i32 v[12:13], s[12:13], v12, s5, v[10:11]
	v_lshl_add_u64 v[12:13], v[12:13], 0, s[6:7]
	v_lshl_add_u64 v[12:13], v[12:13], 0, v[0:1]
	flat_store_dwordx4 v[12:13], v[6:9]
	ds_read_b32 v6, v29 offset:96
	ds_read_b32 v7, v29 offset:228
	ds_read_b32 v8, v29 offset:360
	ds_read_b32 v9, v29 offset:492
	ds_read_b32 v12, v29 offset:624
	ds_read_b32 v13, v29 offset:756
	ds_read_b32 v14, v29 offset:888
	ds_read_b32 v15, v29 offset:1020
	v_mad_i64_i32 v[10:11], s[4:5], v16, s5, v[10:11]
	v_lshl_add_u64 v[10:11], v[10:11], 0, s[6:7]
	s_waitcnt lgkmcnt(0)
	v_cvt_pk_bf16_f32 v6, v6, v7
	v_cvt_pk_bf16_f32 v7, v8, v9
	v_cvt_pk_bf16_f32 v8, v12, v13
	v_cvt_pk_bf16_f32 v9, v14, v15
	v_lshl_add_u64 v[10:11], v[10:11], 0, v[0:1]
	flat_store_dwordx4 v[10:11], v[6:9]
	s_waitcnt lgkmcnt(0)

; __device__ __forceinline__ unsigned pk2(float lo, float hi) { f32x2_t v = {lo, hi}; bf16x2_t b = __builtin_convertvector(v, bf16x2_t); return __builtin_bit_cast(unsigned, b); }
; __device__ __forceinline__ void conv_item(const float* W, int K, int N, int kind, int item, const float* gain, unsigned char* Wb, float* scr, int lane) {
;     ...
;     for (int j = 0; j < 4; ++j) { const int n = (lane >> 3) + 8 * j; const float* s = scr + (8 * c) * 33 + n;
;         u32x4 o; o.x = pk2(s[0] * gg[0], s[33] * gg[1]); o.y = pk2(s[2 * 33] * gg[2], s[3 * 33] * gg[3]); o.z = pk2(s[4 * 33] * gg[4], s[5 * 33] * gg[5]); o.w = pk2(s[6 * 33] * gg[6], s[7 * 33] * gg[7]);
;         *(u32x4*)(wdst(kind, n0 + n, Wb) + k0 + 8 * c) = o; }
;     __builtin_amdgcn_s_waitcnt(0); asm volatile("" ::: "memory");
.LBB0_1373:
	s_or_b64 exec, exec, s[4:5]
	v_mov_b64_e32 v[26:27], s[16:17]
	s_and_saveexec_b64 s[4:5], s[20:21]
	v_ashrrev_i32_e32 v25, 31, v24
	v_mov_b64_e32 v[26:27], s[62:63]
	v_mov_b64_e32 v[22:23], v[24:25]
	s_or_b64 exec, exec, s[4:5]
	v_lshlrev_b64 v[22:23], 11, v[22:23]
	s_waitcnt lgkmcnt(0)
	v_pk_mul_f32 v[6:7], v[6:7], v[20:21]
	v_pk_mul_f32 v[8:9], v[8:9], v[18:19]
	v_lshl_add_u64 v[22:23], v[26:27], 0, v[22:23]
	v_cvt_pk_bf16_f32 v6, v6, v7
	v_cvt_pk_bf16_f32 v7, v8, v9
	v_pk_mul_f32 v[8:9], v[10:11], v[16:17]
	v_pk_mul_f32 v[10:11], v[12:13], v[14:15]
	v_cvt_pk_bf16_f32 v8, v8, v9
	v_cvt_pk_bf16_f32 v9, v10, v11
	v_lshl_add_u64 v[10:11], v[22:23], 0, s[92:93]
	v_lshl_add_u64 v[10:11], v[10:11], 0, v[0:1]
	flat_store_dwordx4 v[10:11], v[6:9]
	s_waitcnt lgkmcnt(0)
